# v75 + nt on remaining once-read streams: RAW loads in the post row phases, O/z/r loads in the two finalize loops, f32 weight loads of the P0 transposes and adaLN gemv
# baseline (speedup 1.0000x reference)
; __device__ __forceinline__ void ada_gemv(const Ctx& F, const LAS float* sc, int layer, int gw, int NGW) {
;     ...
;     for (int task = gw; task < 192 * 8; task += NGW) {
;         const int kp = task & 7, cb = task >> 3;
;         const float* W = P.in[layer ? 27 : 2] + (size_t)(kp * 256) * 12288 + cb * 64 + F.lane;
;         float acc = 0.f;
; #pragma unroll 16
;         for (int k = 0; k < 256; ++k) acc += sc[kp * 256 + k] * W[(size_t)k * 12288];
;         MODP[(size_t)(kp * 2 + layer) * 12288 + cb * 64 + F.lane] = acc;
;     }
.LBB0_102:
	v_lshl_add_u64 v[8:9], v[4:5], 0, s[0:1]
	v_add_co_u32_e32 v10, vcc, 0xc000, v8
	global_load_dword v7, v[8:9], off nt
	s_nop 0
	v_addc_co_u32_e32 v11, vcc, 0, v9, vcc
	v_add_co_u32_e32 v12, vcc, s7, v8
	global_load_dword v24, v[10:11], off nt
	s_nop 0
	v_addc_co_u32_e32 v13, vcc, 0, v9, vcc
	v_add_co_u32_e32 v10, vcc, 0x24000, v8
	v_mov_b32_e32 v20, s13
	s_nop 0
	v_addc_co_u32_e32 v11, vcc, 0, v9, vcc
	v_add_co_u32_e32 v14, vcc, 0x30000, v8
	global_load_dword v25, v[12:13], off nt
	global_load_dword v26, v[10:11], off nt
	v_addc_co_u32_e32 v15, vcc, 0, v9, vcc
	v_add_co_u32_e32 v10, vcc, 0x3c000, v8
	s_add_u32 s0, s0, 0xc0000
	s_nop 0
	v_addc_co_u32_e32 v11, vcc, 0, v9, vcc
	v_add_co_u32_e32 v12, vcc, 0x48000, v8
	global_load_dword v27, v[14:15], off nt
	global_load_dword v28, v[10:11], off nt
	v_addc_co_u32_e32 v13, vcc, 0, v9, vcc
	v_add_co_u32_e32 v10, vcc, 0x54000, v8
	s_addc_u32 s1, s1, 0
	s_nop 0
	v_addc_co_u32_e32 v11, vcc, 0, v9, vcc
	v_add_co_u32_e32 v14, vcc, 0x60000, v8
	global_load_dword v29, v[12:13], off nt
	global_load_dword v30, v[10:11], off nt
	v_addc_co_u32_e32 v15, vcc, 0, v9, vcc
	v_add_co_u32_e32 v10, vcc, 0x6c000, v8
	s_add_i32 s13, s13, 64
	s_nop 0
	v_addc_co_u32_e32 v11, vcc, 0, v9, vcc
	v_add_co_u32_e32 v12, vcc, 0x78000, v8
	global_load_dword v31, v[14:15], off nt
	global_load_dword v32, v[10:11], off nt
	v_addc_co_u32_e32 v13, vcc, 0, v9, vcc
	v_add_co_u32_e32 v10, vcc, 0x84000, v8
	s_cmp_eq_u32 s0, 0xc00000
	s_nop 0
	v_addc_co_u32_e32 v11, vcc, 0, v9, vcc
	v_add_co_u32_e32 v14, vcc, 0x90000, v8
	global_load_dword v33, v[12:13], off nt
	global_load_dword v34, v[10:11], off nt
	v_addc_co_u32_e32 v15, vcc, 0, v9, vcc
	v_add_co_u32_e32 v10, vcc, 0x9c000, v8
	s_nop 1
	v_addc_co_u32_e32 v11, vcc, 0, v9, vcc
	v_add_co_u32_e32 v12, vcc, 0xa8000, v8
	global_load_dword v35, v[14:15], off nt
	global_load_dword v36, v[10:11], off nt
	v_addc_co_u32_e32 v13, vcc, 0, v9, vcc
	v_add_co_u32_e32 v8, vcc, 0xb4000, v8
	s_nop 1
	v_addc_co_u32_e32 v9, vcc, 0, v9, vcc
	global_load_dword v37, v[12:13], off nt
	global_load_dword v38, v[8:9], off nt
	ds_read_b128 v[8:11], v20
	ds_read_b128 v[12:15], v20 offset:16
	ds_read_b128 v[16:19], v20 offset:32
	ds_read_b128 v[20:23], v20 offset:48
	s_waitcnt vmcnt(15) lgkmcnt(3)
	v_fmac_f32_e32 v6, v8, v7
	s_waitcnt vmcnt(14)
	v_fmac_f32_e32 v6, v9, v24
	s_waitcnt vmcnt(13)
	v_fmac_f32_e32 v6, v10, v25
	s_waitcnt vmcnt(12)
	v_fmac_f32_e32 v6, v11, v26
	s_waitcnt vmcnt(11) lgkmcnt(2)
	v_fmac_f32_e32 v6, v12, v27
	s_waitcnt vmcnt(10)
	v_fmac_f32_e32 v6, v13, v28
	s_waitcnt vmcnt(9)
	v_fmac_f32_e32 v6, v14, v29
	s_waitcnt vmcnt(8)
	v_fmac_f32_e32 v6, v15, v30
	s_waitcnt vmcnt(7) lgkmcnt(1)
	v_fmac_f32_e32 v6, v16, v31
	s_waitcnt vmcnt(6)
	v_fmac_f32_e32 v6, v17, v32
	s_waitcnt vmcnt(5)
	v_fmac_f32_e32 v6, v18, v33
	s_waitcnt vmcnt(4)
	v_fmac_f32_e32 v6, v19, v34
	s_waitcnt vmcnt(3) lgkmcnt(0)
	v_fmac_f32_e32 v6, v20, v35
	s_waitcnt vmcnt(2)
	v_fmac_f32_e32 v6, v21, v36
	s_waitcnt vmcnt(1)
	v_fmac_f32_e32 v6, v22, v37
	s_waitcnt vmcnt(0)
	v_fmac_f32_e32 v6, v23, v38
	s_cbranch_scc0 .LBB0_102
	s_lshl_b32 s0, s4, 3
	s_andn2_b32 s0, s0, 63
	s_ashr_i32 s1, s0, 31
	s_add_i32 s4, s5, s4
	s_add_i32 s11, s11, s12
	v_lshl_add_u64 v[4:5], s[0:1], 2, v[0:1]
	s_cmpk_gt_i32 s4, 0x5ff
	global_store_dword v[4:5], v6, off
	s_cbranch_scc0 .LBB0_101

; #define LAS __attribute__((address_space(3)))
; __device__ __forceinline__ void transpose_item(const float* W, int K, int Nsrc, int c0, bf16_t* WT, int mode, LAS float* scr, int kb, int nb, int lane) {
;     const int k0 = 64 * kb, n0 = 32 * nb;
;     float tv[32];
; #pragma unroll
;     for (int i = 0; i < 32; ++i) { const int kk = 2 * i + (lane >> 5); tv[i] = W[(size_t)(k0 + kk) * Nsrc + c0 + n0 + (lane & 31)]; }
; #pragma unroll
;     for (int i = 0; i < 32; ++i) { const int kk = 2 * i + (lane >> 5); scr[kk * 33 + (lane & 31)] = tv[i]; }
;     if (gw < 0) { gw = F.bid * 8 + F.wave; NGW = F.G * 8; }
;     const int nnb = ncols / 32, items = (K / 64) * nnb;
;     const int first = (gw - base % NGW + NGW) % NGW;
;     for (int it = first; it < items; it += NGW) transpose_item(W, K, Nsrc, c0, WT, mode, scr, it / nnb, it % nnb, F.lane);
.LBB0_106:
	s_ashr_i32 s14, s0, 31
	s_lshr_b32 s14, s14, 25
	s_add_i32 s14, s0, s14
	s_ashr_i32 s15, s14, 7
	s_lshl_b32 s14, s15, 6
	s_lshl_b32 s15, s15, 12
	s_sub_i32 s16, s1, s15
	v_or_b32_e32 v15, s14, v4
	s_ashr_i32 s17, s16, 31
	s_ashr_i32 s15, s14, 31
	v_or_b32_e32 v23, 2, v15
	v_or_b32_e32 v40, 12, v15
	v_or_b32_e32 v42, 14, v15
	v_or_b32_e32 v44, 16, v15
	v_or_b32_e32 v46, 18, v15
	v_or_b32_e32 v48, 20, v15
	v_or_b32_e32 v50, 22, v15
	v_or_b32_e32 v52, 24, v15
	v_or_b32_e32 v54, 26, v15
	v_or_b32_e32 v56, 28, v15
	v_or_b32_e32 v58, 30, v15
	v_or_b32_e32 v60, 32, v15
	v_or_b32_e32 v62, 34, v15
	v_or_b32_e32 v64, 36, v15
	v_lshl_add_u64 v[20:21], s[16:17], 2, v[0:1]
	v_or_b32_e32 v25, 4, v15
	v_or_b32_e32 v27, 6, v15
	v_or_b32_e32 v36, 8, v15
	v_or_b32_e32 v38, 10, v15
	v_or_b32_e32 v66, 38, v15
	v_or_b32_e32 v68, 40, v15
	v_or_b32_e32 v70, 42, v15
	v_or_b32_e32 v72, 44, v15
	v_or_b32_e32 v74, 46, v15
	v_or_b32_e32 v76, 48, v15
	v_or_b32_e32 v78, 50, v15
	v_or_b32_e32 v80, 52, v15
	v_or_b32_e32 v82, 54, v15
	v_or_b32_e32 v84, 56, v15
	v_or_b32_e32 v86, 58, v15
	v_or_b32_e32 v88, 60, v15
	v_or_b32_e32 v90, 62, v15
	v_lshl_add_u64 v[16:17], s[14:15], 1, v[2:3]
	v_mad_i64_i32 v[28:29], s[14:15], v15, s11, v[20:21]
	v_mad_i64_i32 v[30:31], s[14:15], v23, s11, v[20:21]
	v_mad_i64_i32 v[40:41], s[14:15], v40, s11, v[20:21]
	v_mad_i64_i32 v[42:43], s[14:15], v42, s11, v[20:21]
	v_mad_i64_i32 v[44:45], s[14:15], v44, s11, v[20:21]
	v_mad_i64_i32 v[46:47], s[14:15], v46, s11, v[20:21]
	v_mad_i64_i32 v[48:49], s[14:15], v48, s11, v[20:21]
	v_mad_i64_i32 v[50:51], s[14:15], v50, s11, v[20:21]
	v_mad_i64_i32 v[52:53], s[14:15], v52, s11, v[20:21]
	v_mad_i64_i32 v[54:55], s[14:15], v54, s11, v[20:21]
	v_mad_i64_i32 v[56:57], s[14:15], v56, s11, v[20:21]
	v_mad_i64_i32 v[58:59], s[14:15], v58, s11, v[20:21]
	v_mad_i64_i32 v[60:61], s[14:15], v60, s11, v[20:21]
	v_mad_i64_i32 v[62:63], s[14:15], v62, s11, v[20:21]
	v_mad_i64_i32 v[64:65], s[14:15], v64, s11, v[20:21]
	v_mad_i64_i32 v[32:33], s[14:15], v25, s11, v[20:21]
	v_mad_i64_i32 v[34:35], s[14:15], v27, s11, v[20:21]
	v_mad_i64_i32 v[36:37], s[14:15], v36, s11, v[20:21]
	v_mad_i64_i32 v[38:39], s[14:15], v38, s11, v[20:21]
	v_mad_i64_i32 v[66:67], s[14:15], v66, s11, v[20:21]
	v_mad_i64_i32 v[68:69], s[14:15], v68, s11, v[20:21]
	v_mad_i64_i32 v[70:71], s[14:15], v70, s11, v[20:21]
	v_mad_i64_i32 v[72:73], s[14:15], v72, s11, v[20:21]
	v_mad_i64_i32 v[74:75], s[14:15], v74, s11, v[20:21]
	v_mad_i64_i32 v[76:77], s[14:15], v76, s11, v[20:21]
	v_mad_i64_i32 v[78:79], s[14:15], v78, s11, v[20:21]
	v_mad_i64_i32 v[80:81], s[14:15], v80, s11, v[20:21]
	v_mad_i64_i32 v[82:83], s[14:15], v82, s11, v[20:21]
	v_mad_i64_i32 v[84:85], s[14:15], v84, s11, v[20:21]
	v_mad_i64_i32 v[86:87], s[14:15], v86, s11, v[20:21]
	v_mad_i64_i32 v[88:89], s[14:15], v88, s11, v[20:21]
	v_mad_i64_i32 v[20:21], s[14:15], v90, s11, v[20:21]
	global_load_dword v15, v[28:29], off nt
	s_nop 0
	global_load_dword v28, v[30:31], off nt
	global_load_dword v29, v[32:33], off nt
	s_nop 0
	global_load_dword v30, v[34:35], off nt
	global_load_dword v31, v[36:37], off nt
	global_load_dword v90, v[38:39], off nt
	s_nop 0
	global_load_dword v40, v[40:41], off nt
	s_nop 0
	global_load_dword v41, v[42:43], off nt
	s_nop 0
	global_load_dword v42, v[44:45], off nt
	global_load_dword v43, v[46:47], off nt
	s_nop 0
	global_load_dword v44, v[48:49], off nt
	global_load_dword v45, v[50:51], off nt
	global_load_dword v46, v[52:53], off nt
	global_load_dword v47, v[54:55], off nt
	s_nop 0
	global_load_dword v48, v[56:57], off nt
	global_load_dword v49, v[58:59], off nt
	global_load_dword v50, v[60:61], off nt
	global_load_dword v51, v[62:63], off nt
	global_load_dword v52, v[64:65], off nt
	global_load_dword v53, v[66:67], off nt
	global_load_dword v54, v[68:69], off nt
	global_load_dword v55, v[70:71], off nt
	global_load_dword v56, v[72:73], off nt
	global_load_dword v57, v[74:75], off nt
	global_load_dword v58, v[76:77], off nt
	global_load_dword v59, v[78:79], off nt
	global_load_dword v60, v[80:81], off nt
	global_load_dword v61, v[82:83], off nt
	global_load_dword v62, v[84:85], off nt
	global_load_dword v63, v[86:87], off nt
	global_load_dword v64, v[88:89], off nt
	global_load_dword v65, v[20:21], off nt
	v_add_u32_e32 v18, s16, v5
	v_ashrrev_i32_e32 v19, 31, v18
	v_add_u32_e32 v22, 8, v18
	v_add_u32_e32 v24, 16, v18
	v_add_u32_e32 v26, 24, v18
	v_lshlrev_b64 v[18:19], 12, v[18:19]
	v_ashrrev_i32_e32 v23, 31, v22
	v_ashrrev_i32_e32 v25, 31, v24
	v_ashrrev_i32_e32 v27, 31, v26
	s_waitcnt vmcnt(30)
	ds_write2_b32 v7, v15, v28 offset1:66
	s_waitcnt vmcnt(28)
	ds_write2_b32 v7, v29, v30 offset0:132 offset1:198
	s_waitcnt vmcnt(26)
	ds_write2_b32 v8, v31, v90 offset0:8 offset1:74
	s_waitcnt vmcnt(24)
	ds_write2_b32 v8, v40, v41 offset0:140 offset1:206
	s_waitcnt vmcnt(22)
	ds_write2_b32 v9, v42, v43 offset0:16 offset1:82
	s_waitcnt vmcnt(20)
	ds_write2_b32 v9, v44, v45 offset0:148 offset1:214
	s_waitcnt vmcnt(18)
	ds_write2_b32 v10, v46, v47 offset0:24 offset1:90
	s_waitcnt vmcnt(16)
	ds_write2_b32 v10, v48, v49 offset0:156 offset1:222
	s_waitcnt vmcnt(14)
; #define LAS __attribute__((address_space(3)))
; __device__ __forceinline__ unsigned pk2(float lo, float hi) { return f2bf(lo) | (f2bf(hi) << 16); }
; __device__ __forceinline__ void transpose_item(const float* W, int K, int Nsrc, int c0, bf16_t* WT, int mode, LAS float* scr, int kb, int nb, int lane) {
;     ...
;     for (int i = 0; i < 32; ++i) { const int kk = 2 * i + (lane >> 5); tv[i] = W[(size_t)(k0 + kk) * Nsrc + c0 + n0 + (lane & 31)]; }
; #pragma unroll
;     for (int i = 0; i < 32; ++i) { const int kk = 2 * i + (lane >> 5); scr[kk * 33 + (lane & 31)] = tv[i]; }
;     asm volatile("s_waitcnt lgkmcnt(0)" ::: "memory");
;     const int c = lane & 7;
; #pragma unroll
;     for (int j = 0; j < 4; ++j) { const int n = (lane >> 3) + 8 * j; const LAS float* s = scr + (8 * c) * 33 + n;
;         u32x4 o; o.x = pk2(s[0 * 33], s[1 * 33]); o.y = pk2(s[2 * 33], s[3 * 33]); o.z = pk2(s[4 * 33], s[5 * 33]); o.w = pk2(s[6 * 33], s[7 * 33]);
;         const int nn = n0 + n; const int row = (mode == 0) ? nn : ((nn >> 7) * 256 + (nn & 127) + (mode == 2 ? 128 : 0));
;         *(u32x4*)(WT + (size_t)row * K + k0 + 8 * c) = o; }
;     asm volatile("s_waitcnt lgkmcnt(0)" ::: "memory");
	ds_write2_b32 v11, v50, v51 offset0:32 offset1:98
	s_waitcnt vmcnt(12)
	ds_write2_b32 v11, v52, v53 offset0:164 offset1:230
	s_waitcnt vmcnt(10)
	ds_write2_b32 v12, v54, v55 offset0:40 offset1:106
	s_waitcnt vmcnt(8)
	ds_write2_b32 v12, v56, v57 offset0:172 offset1:238
	s_waitcnt vmcnt(6)
	ds_write2_b32 v13, v58, v59 offset0:48 offset1:114
	s_waitcnt vmcnt(4)
	ds_write2_b32 v13, v60, v61 offset0:180 offset1:246
	s_waitcnt vmcnt(2)
	ds_write2_b32 v14, v62, v63 offset0:56 offset1:122
	s_waitcnt vmcnt(0)
	ds_write2_b32 v14, v64, v65 offset0:188 offset1:254
	v_lshl_add_u64 v[32:33], v[16:17], 0, v[18:19]
	v_lshlrev_b64 v[18:19], 12, v[22:23]
	v_lshlrev_b64 v[20:21], 12, v[24:25]
	v_lshlrev_b64 v[22:23], 12, v[26:27]
	s_waitcnt lgkmcnt(0)
	v_lshl_add_u64 v[34:35], v[16:17], 0, v[18:19]
	v_lshl_add_u64 v[36:37], v[16:17], 0, v[20:21]
	v_lshl_add_u64 v[38:39], v[16:17], 0, v[22:23]
	ds_read2_b32 v[16:17], v6 offset0:33 offset1:41
	ds_read2_b32 v[18:19], v6 offset1:8
	ds_read2_b32 v[20:21], v6 offset0:66 offset1:74
	ds_read2_b32 v[22:23], v6 offset0:99 offset1:107
	ds_read2_b32 v[24:25], v6 offset0:132 offset1:140
	ds_read2_b32 v[26:27], v6 offset0:165 offset1:173
	ds_read2_b32 v[28:29], v6 offset0:198 offset1:206
	ds_read2_b32 v[30:31], v6 offset0:231 offset1:239
	ds_read2_b32 v[40:41], v6 offset0:49 offset1:57
	ds_read2_b32 v[42:43], v6 offset0:16 offset1:24
	ds_read2_b32 v[44:45], v6 offset0:82 offset1:90
	ds_read2_b32 v[46:47], v6 offset0:115 offset1:123
	ds_read2_b32 v[48:49], v6 offset0:148 offset1:156
	ds_read2_b32 v[50:51], v6 offset0:181 offset1:189
	ds_read2_b32 v[52:53], v6 offset0:214 offset1:222
	ds_read2_b32 v[54:55], v6 offset0:247 offset1:255
	s_waitcnt lgkmcnt(14)
	v_bfe_u32 v15, v18, 16, 1
	v_bfe_u32 v56, v16, 16, 1
	s_waitcnt lgkmcnt(13)
	v_bfe_u32 v57, v20, 16, 1
	s_waitcnt lgkmcnt(12)
	v_bfe_u32 v58, v22, 16, 1
	s_waitcnt lgkmcnt(11)
	v_bfe_u32 v59, v24, 16, 1
	s_waitcnt lgkmcnt(10)
	v_bfe_u32 v60, v26, 16, 1
	s_waitcnt lgkmcnt(9)
	v_bfe_u32 v61, v28, 16, 1
	v_bfe_u32 v64, v17, 16, 1
	s_waitcnt lgkmcnt(8)
	v_bfe_u32 v62, v30, 16, 1
	v_bfe_u32 v63, v19, 16, 1
	v_bfe_u32 v65, v21, 16, 1
	v_bfe_u32 v66, v23, 16, 1
	v_bfe_u32 v67, v25, 16, 1
	v_bfe_u32 v68, v27, 16, 1
	v_bfe_u32 v69, v29, 16, 1
	v_bfe_u32 v70, v31, 16, 1
	s_waitcnt lgkmcnt(6)
	v_bfe_u32 v71, v42, 16, 1
	s_waitcnt lgkmcnt(5)
	v_bfe_u32 v73, v44, 16, 1
	s_waitcnt lgkmcnt(3)
	v_bfe_u32 v75, v48, 16, 1
	s_waitcnt lgkmcnt(1)
	v_bfe_u32 v77, v52, 16, 1
	v_bfe_u32 v79, v43, 16, 1
	v_bfe_u32 v81, v45, 16, 1
	v_bfe_u32 v83, v49, 16, 1
	v_bfe_u32 v85, v53, 16, 1
	v_add3_u32 v15, v18, v15, s12
	v_add3_u32 v16, v16, v56, s12
	v_add3_u32 v56, v17, v64, s12
	v_add3_u32 v17, v20, v57, s12
	v_add3_u32 v20, v22, v58, s12
	v_add3_u32 v22, v24, v59, s12
	v_add3_u32 v24, v26, v60, s12
	v_add3_u32 v26, v28, v61, s12
	v_bfe_u32 v72, v40, 16, 1
	v_bfe_u32 v74, v46, 16, 1
	v_bfe_u32 v76, v50, 16, 1
	s_waitcnt lgkmcnt(0)
	v_bfe_u32 v78, v54, 16, 1
	v_bfe_u32 v80, v41, 16, 1
	v_bfe_u32 v82, v47, 16, 1
	v_bfe_u32 v84, v51, 16, 1
	v_bfe_u32 v86, v55, 16, 1
	v_add3_u32 v18, v19, v63, s12
	v_add3_u32 v19, v21, v65, s12
	v_add3_u32 v21, v23, v66, s12
	v_add3_u32 v23, v25, v67, s12
	v_add3_u32 v25, v27, v68, s12
	v_add3_u32 v27, v29, v69, s12
	v_add3_u32 v28, v30, v62, s12
	v_add3_u32 v29, v31, v70, s12
	v_add3_u32 v30, v42, v71, s12
	v_add3_u32 v31, v43, v79, s12
	v_add3_u32 v42, v44, v73, s12
	v_add3_u32 v44, v48, v75, s12
	v_add3_u32 v48, v52, v77, s12
	v_add3_u32 v45, v45, v81, s12
	v_add3_u32 v49, v49, v83, s12
	v_add3_u32 v52, v53, v85, s12
	v_lshrrev_b32_e32 v15, 16, v15
	v_lshrrev_b32_e32 v17, 16, v17
	v_lshrrev_b32_e32 v22, 16, v22
	v_lshrrev_b32_e32 v26, 16, v26
	v_add3_u32 v40, v40, v72, s12
	v_add3_u32 v41, v41, v80, s12
	v_add3_u32 v43, v46, v74, s12
	v_add3_u32 v46, v50, v76, s12
	v_add3_u32 v50, v54, v78, s12
	v_add3_u32 v47, v47, v82, s12
	v_add3_u32 v51, v51, v84, s12
	v_add3_u32 v53, v55, v86, s12
	v_lshrrev_b32_e32 v54, 16, v18
	v_lshrrev_b32_e32 v55, 16, v19
	v_lshrrev_b32_e32 v23, 16, v23
	v_lshrrev_b32_e32 v27, 16, v27
	v_lshrrev_b32_e32 v30, 16, v30
	v_lshrrev_b32_e32 v42, 16, v42
	v_lshrrev_b32_e32 v44, 16, v44
	v_lshrrev_b32_e32 v48, 16, v48
	v_lshrrev_b32_e32 v31, 16, v31
	v_lshrrev_b32_e32 v45, 16, v45
	v_lshrrev_b32_e32 v49, 16, v49
	v_lshrrev_b32_e32 v52, 16, v52
	v_and_or_b32 v16, v16, s13, v15
	v_and_or_b32 v17, v20, s13, v17
	v_and_or_b32 v18, v24, s13, v22
	v_and_or_b32 v19, v28, s13, v26
	v_and_or_b32 v20, v56, s13, v54
	v_and_or_b32 v21, v21, s13, v55
	v_and_or_b32 v22, v25, s13, v23
	v_and_or_b32 v23, v29, s13, v27
	v_and_or_b32 v24, v40, s13, v30
	v_and_or_b32 v25, v43, s13, v42
	v_and_or_b32 v26, v46, s13, v44
	v_and_or_b32 v27, v50, s13, v48
	v_and_or_b32 v28, v41, s13, v31
	v_and_or_b32 v29, v47, s13, v45
	v_and_or_b32 v30, v51, s13, v49
	v_and_or_b32 v31, v53, s13, v52
	global_store_dwordx4 v[32:33], v[16:19], off
	global_store_dwordx4 v[34:35], v[20:23], off
	global_store_dwordx4 v[36:37], v[24:27], off
	global_store_dwordx4 v[38:39], v[28:31], off
	s_waitcnt lgkmcnt(0)
	s_add_i32 s0, s0, s3
	s_add_i32 s1, s1, s10
	s_cmpk_lt_i32 s0, 0x1000
	s_cbranch_scc1 .LBB0_106

; #define LAS __attribute__((address_space(3)))
; __device__ __forceinline__ void transpose_item(const float* W, int K, int Nsrc, int c0, bf16_t* WT, int mode, LAS float* scr, int kb, int nb, int lane) {
;     const int k0 = 64 * kb, n0 = 32 * nb;
;     float tv[32];
; #pragma unroll
;     for (int i = 0; i < 32; ++i) { const int kk = 2 * i + (lane >> 5); tv[i] = W[(size_t)(k0 + kk) * Nsrc + c0 + n0 + (lane & 31)]; }
; #pragma unroll
;     for (int i = 0; i < 32; ++i) { const int kk = 2 * i + (lane >> 5); scr[kk * 33 + (lane & 31)] = tv[i]; }
;     if (gw < 0) { gw = F.bid * 8 + F.wave; NGW = F.G * 8; }
;     const int nnb = ncols / 32, items = (K / 64) * nnb;
;     const int first = (gw - base % NGW + NGW) % NGW;
;     for (int it = first; it < items; it += NGW) transpose_item(W, K, Nsrc, c0, WT, mode, scr, it / nnb, it % nnb, F.lane);
.LBB0_109:
	s_ashr_i32 s13, s0, 31
	s_lshr_b32 s13, s13, 27
	s_add_i32 s13, s0, s13
	s_ashr_i32 s13, s13, 5
	s_lshl_b32 s14, s13, 6
	s_lshl_b32 s13, s13, 10
	v_or_b32_e32 v16, s14, v4
	s_sub_i32 s16, s1, s13
	v_or_b32_e32 v18, 2, v16
	v_or_b32_e32 v20, 4, v16
	v_or_b32_e32 v22, 6, v16
	v_or_b32_e32 v24, 8, v16
	v_or_b32_e32 v26, 10, v16
	v_or_b32_e32 v28, 12, v16
	v_or_b32_e32 v30, 14, v16
	v_or_b32_e32 v38, 22, v16
	v_or_b32_e32 v40, 24, v16
	v_or_b32_e32 v42, 26, v16
	v_or_b32_e32 v44, 28, v16
	v_or_b32_e32 v46, 30, v16
	v_or_b32_e32 v48, 32, v16
	v_or_b32_e32 v50, 34, v16
	v_or_b32_e32 v52, 36, v16
	s_ashr_i32 s17, s16, 31
	v_ashrrev_i32_e32 v17, 31, v16
	v_or_b32_e32 v32, 16, v16
	v_or_b32_e32 v34, 18, v16
	v_or_b32_e32 v36, 20, v16
	v_or_b32_e32 v54, 38, v16
	v_or_b32_e32 v56, 40, v16
	v_or_b32_e32 v58, 42, v16
	v_or_b32_e32 v60, 44, v16
	v_or_b32_e32 v62, 46, v16
	v_or_b32_e32 v64, 48, v16
	v_or_b32_e32 v66, 50, v16
	v_or_b32_e32 v68, 52, v16
	v_or_b32_e32 v70, 54, v16
	v_or_b32_e32 v72, 56, v16
	v_or_b32_e32 v74, 58, v16
	v_or_b32_e32 v76, 60, v16
	v_or_b32_e32 v78, 62, v16
	v_ashrrev_i32_e32 v19, 31, v18
	v_ashrrev_i32_e32 v21, 31, v20
	v_ashrrev_i32_e32 v23, 31, v22
	v_ashrrev_i32_e32 v25, 31, v24
	v_ashrrev_i32_e32 v27, 31, v26
	v_ashrrev_i32_e32 v29, 31, v28
	v_ashrrev_i32_e32 v31, 31, v30
	v_ashrrev_i32_e32 v39, 31, v38
	v_ashrrev_i32_e32 v41, 31, v40
	v_ashrrev_i32_e32 v43, 31, v42
	v_ashrrev_i32_e32 v45, 31, v44
	v_ashrrev_i32_e32 v47, 31, v46
	v_ashrrev_i32_e32 v49, 31, v48
	v_ashrrev_i32_e32 v51, 31, v50
	v_ashrrev_i32_e32 v53, 31, v52
	v_lshl_add_u64 v[84:85], s[16:17], 2, v[0:1]
	v_lshlrev_b64 v[16:17], 12, v[16:17]
	v_ashrrev_i32_e32 v33, 31, v32
	v_ashrrev_i32_e32 v35, 31, v34
	v_ashrrev_i32_e32 v37, 31, v36
	v_ashrrev_i32_e32 v55, 31, v54
	v_ashrrev_i32_e32 v57, 31, v56
	v_ashrrev_i32_e32 v59, 31, v58
	v_ashrrev_i32_e32 v61, 31, v60
	v_ashrrev_i32_e32 v63, 31, v62
	v_ashrrev_i32_e32 v65, 31, v64
	v_ashrrev_i32_e32 v67, 31, v66
	v_ashrrev_i32_e32 v69, 31, v68
	v_ashrrev_i32_e32 v71, 31, v70
	v_ashrrev_i32_e32 v73, 31, v72
	v_ashrrev_i32_e32 v75, 31, v74
	v_ashrrev_i32_e32 v77, 31, v76
	v_ashrrev_i32_e32 v79, 31, v78
	v_lshlrev_b64 v[18:19], 12, v[18:19]
	v_lshlrev_b64 v[20:21], 12, v[20:21]
	v_lshlrev_b64 v[22:23], 12, v[22:23]
	v_lshlrev_b64 v[24:25], 12, v[24:25]
	v_lshlrev_b64 v[26:27], 12, v[26:27]
	v_lshlrev_b64 v[28:29], 12, v[28:29]
	v_lshlrev_b64 v[30:31], 12, v[30:31]
	v_lshlrev_b64 v[38:39], 12, v[38:39]
	v_lshlrev_b64 v[40:41], 12, v[40:41]
	v_lshlrev_b64 v[42:43], 12, v[42:43]
	v_lshlrev_b64 v[44:45], 12, v[44:45]
	v_lshlrev_b64 v[46:47], 12, v[46:47]
	v_lshlrev_b64 v[48:49], 12, v[48:49]
	v_lshlrev_b64 v[50:51], 12, v[50:51]
	v_lshlrev_b64 v[52:53], 12, v[52:53]
	v_lshl_add_u64 v[16:17], v[84:85], 0, v[16:17]
	v_lshlrev_b64 v[32:33], 12, v[32:33]
	v_lshlrev_b64 v[34:35], 12, v[34:35]
	v_lshlrev_b64 v[36:37], 12, v[36:37]
	v_lshlrev_b64 v[54:55], 12, v[54:55]
	v_lshlrev_b64 v[56:57], 12, v[56:57]
	v_lshlrev_b64 v[58:59], 12, v[58:59]
	v_lshlrev_b64 v[60:61], 12, v[60:61]
	v_lshlrev_b64 v[62:63], 12, v[62:63]
	v_lshlrev_b64 v[64:65], 12, v[64:65]
	v_lshlrev_b64 v[66:67], 12, v[66:67]
	v_lshlrev_b64 v[68:69], 12, v[68:69]
	v_lshlrev_b64 v[70:71], 12, v[70:71]
	v_lshlrev_b64 v[72:73], 12, v[72:73]
	v_lshlrev_b64 v[74:75], 12, v[74:75]
	v_lshlrev_b64 v[76:77], 12, v[76:77]
	v_lshlrev_b64 v[78:79], 12, v[78:79]
	v_lshl_add_u64 v[18:19], v[84:85], 0, v[18:19]
	v_lshl_add_u64 v[20:21], v[84:85], 0, v[20:21]
	v_lshl_add_u64 v[22:23], v[84:85], 0, v[22:23]
	v_lshl_add_u64 v[24:25], v[84:85], 0, v[24:25]
	v_lshl_add_u64 v[26:27], v[84:85], 0, v[26:27]
	v_lshl_add_u64 v[28:29], v[84:85], 0, v[28:29]
	v_lshl_add_u64 v[30:31], v[84:85], 0, v[30:31]
	v_lshl_add_u64 v[38:39], v[84:85], 0, v[38:39]
	v_lshl_add_u64 v[40:41], v[84:85], 0, v[40:41]
	v_lshl_add_u64 v[42:43], v[84:85], 0, v[42:43]
	v_lshl_add_u64 v[44:45], v[84:85], 0, v[44:45]
	v_lshl_add_u64 v[46:47], v[84:85], 0, v[46:47]
	v_lshl_add_u64 v[48:49], v[84:85], 0, v[48:49]
	v_lshl_add_u64 v[50:51], v[84:85], 0, v[50:51]
	v_lshl_add_u64 v[52:53], v[84:85], 0, v[52:53]
	v_lshl_add_u64 v[32:33], v[84:85], 0, v[32:33]
	v_lshl_add_u64 v[34:35], v[84:85], 0, v[34:35]
	v_lshl_add_u64 v[36:37], v[84:85], 0, v[36:37]
	v_lshl_add_u64 v[54:55], v[84:85], 0, v[54:55]
	v_lshl_add_u64 v[56:57], v[84:85], 0, v[56:57]
	v_lshl_add_u64 v[58:59], v[84:85], 0, v[58:59]
	v_lshl_add_u64 v[60:61], v[84:85], 0, v[60:61]
	v_lshl_add_u64 v[62:63], v[84:85], 0, v[62:63]
	v_lshl_add_u64 v[64:65], v[84:85], 0, v[64:65]
	v_lshl_add_u64 v[66:67], v[84:85], 0, v[66:67]
	v_lshl_add_u64 v[68:69], v[84:85], 0, v[68:69]
	v_lshl_add_u64 v[70:71], v[84:85], 0, v[70:71]
	v_lshl_add_u64 v[72:73], v[84:85], 0, v[72:73]
	v_lshl_add_u64 v[74:75], v[84:85], 0, v[74:75]
	v_lshl_add_u64 v[76:77], v[84:85], 0, v[76:77]
	v_lshl_add_u64 v[78:79], v[84:85], 0, v[78:79]
	global_load_dword v15, v[16:17], off nt
	s_nop 0
	global_load_dword v16, v[18:19], off nt
	global_load_dword v17, v[20:21], off nt
	s_nop 0
	global_load_dword v18, v[22:23], off nt
	global_load_dword v19, v[24:25], off nt
	global_load_dword v20, v[26:27], off nt
	global_load_dword v21, v[28:29], off nt
	s_nop 0
	global_load_dword v22, v[30:31], off nt
	global_load_dword v23, v[32:33], off nt
	global_load_dword v24, v[34:35], off nt
	global_load_dword v25, v[36:37], off nt
	global_load_dword v26, v[38:39], off nt
	global_load_dword v27, v[40:41], off nt
	global_load_dword v28, v[42:43], off nt
	global_load_dword v29, v[44:45], off nt
	global_load_dword v30, v[46:47], off nt
	global_load_dword v31, v[48:49], off nt
	global_load_dword v38, v[50:51], off nt
	global_load_dword v39, v[52:53], off nt
	global_load_dword v40, v[54:55], off nt
	global_load_dword v41, v[56:57], off nt
	global_load_dword v42, v[58:59], off nt
	global_load_dword v43, v[60:61], off nt
	global_load_dword v44, v[62:63], off nt
	global_load_dword v45, v[64:65], off nt
	global_load_dword v46, v[66:67], off nt
	global_load_dword v47, v[68:69], off nt
	global_load_dword v48, v[70:71], off nt
	global_load_dword v49, v[72:73], off nt
	global_load_dword v50, v[74:75], off nt
	global_load_dword v51, v[76:77], off nt
	global_load_dword v52, v[78:79], off nt
	s_waitcnt vmcnt(30)
; #define LAS __attribute__((address_space(3)))
; __device__ __forceinline__ unsigned pk2(float lo, float hi) { return f2bf(lo) | (f2bf(hi) << 16); }
; __device__ __forceinline__ void transpose_item(const float* W, int K, int Nsrc, int c0, bf16_t* WT, int mode, LAS float* scr, int kb, int nb, int lane) {
;     ...
;     for (int i = 0; i < 32; ++i) { const int kk = 2 * i + (lane >> 5); scr[kk * 33 + (lane & 31)] = tv[i]; }
;     asm volatile("s_waitcnt lgkmcnt(0)" ::: "memory");
;     const int c = lane & 7;
; #pragma unroll
;     for (int j = 0; j < 4; ++j) { const int n = (lane >> 3) + 8 * j; const LAS float* s = scr + (8 * c) * 33 + n;
;         u32x4 o; o.x = pk2(s[0 * 33], s[1 * 33]); o.y = pk2(s[2 * 33], s[3 * 33]); o.z = pk2(s[4 * 33], s[5 * 33]); o.w = pk2(s[6 * 33], s[7 * 33]);
;         const int nn = n0 + n; const int row = (mode == 0) ? nn : ((nn >> 7) * 256 + (nn & 127) + (mode == 2 ? 128 : 0));
;         *(u32x4*)(WT + (size_t)row * K + k0 + 8 * c) = o; }
;     asm volatile("s_waitcnt lgkmcnt(0)" ::: "memory");
	ds_write2_b32 v7, v15, v16 offset1:66
	s_waitcnt vmcnt(28)
	ds_write2_b32 v7, v17, v18 offset0:132 offset1:198
	s_waitcnt vmcnt(26)
	ds_write2_b32 v8, v19, v20 offset0:8 offset1:74
	s_waitcnt vmcnt(24)
	ds_write2_b32 v8, v21, v22 offset0:140 offset1:206
	s_waitcnt vmcnt(22)
	ds_write2_b32 v9, v23, v24 offset0:16 offset1:82
	s_waitcnt vmcnt(20)
	ds_write2_b32 v9, v25, v26 offset0:148 offset1:214
	s_waitcnt vmcnt(18)
	ds_write2_b32 v10, v27, v28 offset0:24 offset1:90
	s_waitcnt vmcnt(16)
	ds_write2_b32 v10, v29, v30 offset0:156 offset1:222
	s_waitcnt vmcnt(14)
	ds_write2_b32 v11, v31, v38 offset0:32 offset1:98
	s_waitcnt vmcnt(12)
	ds_write2_b32 v11, v39, v40 offset0:164 offset1:230
	s_waitcnt vmcnt(10)
	ds_write2_b32 v12, v41, v42 offset0:40 offset1:106
	s_waitcnt vmcnt(8)
	ds_write2_b32 v12, v43, v44 offset0:172 offset1:238
	s_waitcnt vmcnt(6)
	ds_write2_b32 v13, v45, v46 offset0:48 offset1:114
	s_waitcnt vmcnt(4)
	ds_write2_b32 v13, v47, v48 offset0:180 offset1:246
	s_waitcnt vmcnt(2)
	ds_write2_b32 v14, v49, v50 offset0:56 offset1:122
	s_waitcnt vmcnt(0)
	ds_write2_b32 v14, v51, v52 offset0:188 offset1:254
	s_waitcnt lgkmcnt(0)
	v_add_u32_e32 v82, s16, v5
	ds_read2_b32 v[16:17], v6 offset0:33 offset1:41
	ds_read2_b32 v[18:19], v6 offset1:8
	ds_read2_b32 v[20:21], v6 offset0:66 offset1:74
	ds_read2_b32 v[22:23], v6 offset0:99 offset1:107
	ds_read2_b32 v[24:25], v6 offset0:132 offset1:140
	ds_read2_b32 v[26:27], v6 offset0:165 offset1:173
	ds_read2_b32 v[28:29], v6 offset0:198 offset1:206
	ds_read2_b32 v[30:31], v6 offset0:231 offset1:239
	ds_read2_b32 v[38:39], v6 offset0:49 offset1:57
	ds_read2_b32 v[40:41], v6 offset0:16 offset1:24
	ds_read2_b32 v[42:43], v6 offset0:82 offset1:90
	ds_read2_b32 v[44:45], v6 offset0:115 offset1:123
	ds_read2_b32 v[46:47], v6 offset0:148 offset1:156
	ds_read2_b32 v[48:49], v6 offset0:181 offset1:189
	ds_read2_b32 v[50:51], v6 offset0:214 offset1:222
	ds_read2_b32 v[52:53], v6 offset0:247 offset1:255
	v_add_u32_e32 v86, 8, v82
	v_add_u32_e32 v88, 16, v82
	v_add_u32_e32 v90, 24, v82
	s_ashr_i32 s15, s14, 31
	v_ashrrev_i32_e32 v83, 31, v82
	v_ashrrev_i32_e32 v87, 31, v86
	v_ashrrev_i32_e32 v89, 31, v88
	v_ashrrev_i32_e32 v91, 31, v90
	v_lshl_add_u64 v[80:81], s[14:15], 1, v[2:3]
	v_lshlrev_b64 v[82:83], 11, v[82:83]
	v_lshlrev_b64 v[84:85], 11, v[86:87]
	v_lshlrev_b64 v[86:87], 11, v[88:89]
	v_lshlrev_b64 v[88:89], 11, v[90:91]
	s_waitcnt lgkmcnt(14)
	v_bfe_u32 v15, v18, 16, 1
	s_waitcnt lgkmcnt(13)
	v_bfe_u32 v55, v20, 16, 1
	s_waitcnt lgkmcnt(12)
	v_bfe_u32 v56, v22, 16, 1
	s_waitcnt lgkmcnt(11)
	v_bfe_u32 v57, v24, 16, 1
	s_waitcnt lgkmcnt(10)
	v_bfe_u32 v58, v26, 16, 1
	s_waitcnt lgkmcnt(9)
	v_bfe_u32 v59, v28, 16, 1
	v_lshl_add_u64 v[82:83], v[80:81], 0, v[82:83]
	v_lshl_add_u64 v[32:33], v[80:81], 0, v[84:85]
	v_lshl_add_u64 v[34:35], v[80:81], 0, v[86:87]
	v_lshl_add_u64 v[36:37], v[80:81], 0, v[88:89]
	v_bfe_u32 v54, v16, 16, 1
	s_waitcnt lgkmcnt(8)
	v_bfe_u32 v60, v30, 16, 1
	v_bfe_u32 v61, v19, 16, 1
	v_bfe_u32 v62, v17, 16, 1
	v_bfe_u32 v63, v21, 16, 1
	v_bfe_u32 v64, v23, 16, 1
	v_bfe_u32 v65, v25, 16, 1
	v_bfe_u32 v66, v27, 16, 1
	v_bfe_u32 v67, v29, 16, 1
	v_bfe_u32 v68, v31, 16, 1
	s_waitcnt lgkmcnt(6)
	v_bfe_u32 v69, v40, 16, 1
	s_waitcnt lgkmcnt(5)
	v_bfe_u32 v71, v42, 16, 1
	s_waitcnt lgkmcnt(4)
	v_bfe_u32 v72, v44, 16, 1
	s_waitcnt lgkmcnt(3)
	v_bfe_u32 v73, v46, 16, 1
	s_waitcnt lgkmcnt(2)
	v_bfe_u32 v74, v48, 16, 1
	s_waitcnt lgkmcnt(1)
	v_bfe_u32 v75, v50, 16, 1
	v_bfe_u32 v77, v41, 16, 1
	v_bfe_u32 v79, v43, 16, 1
	v_bfe_u32 v81, v47, 16, 1
	v_bfe_u32 v85, v51, 16, 1
	v_add3_u32 v15, v18, v15, s11
	v_add3_u32 v18, v20, v55, s11
	v_add3_u32 v20, v22, v56, s11
	v_add3_u32 v22, v24, v57, s11
	v_add3_u32 v24, v26, v58, s11
	v_add3_u32 v26, v28, v59, s11
	v_bfe_u32 v70, v38, 16, 1
	s_waitcnt lgkmcnt(0)
	v_bfe_u32 v76, v52, 16, 1
	v_bfe_u32 v78, v39, 16, 1
	v_bfe_u32 v80, v45, 16, 1
	v_bfe_u32 v84, v49, 16, 1
	v_bfe_u32 v86, v53, 16, 1
	v_add3_u32 v16, v16, v54, s11
	v_add3_u32 v28, v30, v60, s11
	v_add3_u32 v19, v19, v61, s11
	v_add3_u32 v30, v17, v62, s11
	v_add3_u32 v17, v21, v63, s11
	v_add3_u32 v21, v23, v64, s11
	v_add3_u32 v23, v25, v65, s11
	v_add3_u32 v25, v27, v66, s11
	v_add3_u32 v27, v29, v67, s11
	v_add3_u32 v29, v31, v68, s11
	v_add3_u32 v31, v40, v69, s11
	v_add3_u32 v40, v42, v71, s11
	v_add3_u32 v42, v44, v72, s11
	v_add3_u32 v44, v46, v73, s11
	v_add3_u32 v46, v48, v74, s11
	v_add3_u32 v48, v50, v75, s11
	v_add3_u32 v41, v41, v77, s11
	v_add3_u32 v43, v43, v79, s11
	v_add3_u32 v47, v47, v81, s11
	v_add3_u32 v51, v51, v85, s11
	v_lshrrev_b32_e32 v15, 16, v15
	v_lshrrev_b32_e32 v18, 16, v18
	v_lshrrev_b32_e32 v22, 16, v22
	v_lshrrev_b32_e32 v26, 16, v26
	v_add3_u32 v38, v38, v70, s11
	v_add3_u32 v50, v52, v76, s11
	v_add3_u32 v39, v39, v78, s11
	v_add3_u32 v45, v45, v80, s11
	v_add3_u32 v49, v49, v84, s11
	v_add3_u32 v52, v53, v86, s11
	v_lshrrev_b32_e32 v53, 16, v19
	v_lshrrev_b32_e32 v54, 16, v17
	v_lshrrev_b32_e32 v23, 16, v23
	v_lshrrev_b32_e32 v27, 16, v27
	v_lshrrev_b32_e32 v31, 16, v31
	v_lshrrev_b32_e32 v40, 16, v40
	v_lshrrev_b32_e32 v44, 16, v44
	v_lshrrev_b32_e32 v48, 16, v48
	v_lshrrev_b32_e32 v41, 16, v41
	v_lshrrev_b32_e32 v43, 16, v43
	v_lshrrev_b32_e32 v47, 16, v47
	v_lshrrev_b32_e32 v51, 16, v51
	v_and_or_b32 v16, v16, s12, v15
	v_and_or_b32 v17, v20, s12, v18
	v_and_or_b32 v18, v24, s12, v22
	v_and_or_b32 v19, v28, s12, v26
	v_and_or_b32 v20, v30, s12, v53
	v_and_or_b32 v21, v21, s12, v54
	v_and_or_b32 v22, v25, s12, v23
	v_and_or_b32 v23, v29, s12, v27
	v_and_or_b32 v24, v38, s12, v31
	v_and_or_b32 v25, v42, s12, v40
	v_and_or_b32 v26, v46, s12, v44
	v_and_or_b32 v27, v50, s12, v48
	v_and_or_b32 v28, v39, s12, v41
	v_and_or_b32 v29, v45, s12, v43
	v_and_or_b32 v30, v49, s12, v47
	v_and_or_b32 v31, v52, s12, v51
	global_store_dwordx4 v[82:83], v[16:19], off
	global_store_dwordx4 v[32:33], v[20:23], off
	global_store_dwordx4 v[34:35], v[24:27], off
	global_store_dwordx4 v[36:37], v[28:31], off
	s_waitcnt lgkmcnt(0)
	s_add_i32 s0, s0, s3
	s_add_i32 s1, s1, s10
	s_cmpk_lt_i32 s0, 0x200
	s_cbranch_scc1 .LBB0_109

; #define LAS __attribute__((address_space(3)))
; __device__ __forceinline__ void transpose_item(const float* W, int K, int Nsrc, int c0, bf16_t* WT, int mode, LAS float* scr, int kb, int nb, int lane) {
;     const int k0 = 64 * kb, n0 = 32 * nb;
;     float tv[32];
; #pragma unroll
;     for (int i = 0; i < 32; ++i) { const int kk = 2 * i + (lane >> 5); tv[i] = W[(size_t)(k0 + kk) * Nsrc + c0 + n0 + (lane & 31)]; }
; #pragma unroll
;     for (int i = 0; i < 32; ++i) { const int kk = 2 * i + (lane >> 5); scr[kk * 33 + (lane & 31)] = tv[i]; }
;     ...
;         const int nn = n0 + n; const int row = (mode == 0) ? nn : ((nn >> 7) * 256 + (nn & 127) + (mode == 2 ? 128 : 0));
;         *(u32x4*)(WT + (size_t)row * K + k0 + 8 * c) = o; }
;     asm volatile("s_waitcnt lgkmcnt(0)" ::: "memory");
; }
;     if (gw < 0) { gw = F.bid * 8 + F.wave; NGW = F.G * 8; }
;     const int nnb = ncols / 32, items = (K / 64) * nnb;
;     const int first = (gw - base % NGW + NGW) % NGW;
;     for (int it = first; it < items; it += NGW) transpose_item(W, K, Nsrc, c0, WT, mode, scr, it / nnb, it % nnb, F.lane);
.LBB0_112:
	s_mul_hi_i32 s18, s10, 0x2e8ba2e9
	s_lshr_b32 s19, s18, 31
	s_ashr_i32 s18, s18, 5
	s_add_i32 s19, s18, s19
	s_mul_i32 s20, s19, 0xffffea00
	s_lshl_b32 s18, s19, 6
	s_mul_i32 s21, s19, 0xffffd400
	s_add_i32 s20, s11, s20
	v_or_b32_e32 v22, s18, v4
	s_ashr_i32 s19, s18, 31
	s_add_i32 s22, s13, s21
	s_ashr_i32 s21, s20, 31
	v_or_b32_e32 v28, 6, v22
	v_or_b32_e32 v30, 8, v22
	v_or_b32_e32 v32, 10, v22
	v_or_b32_e32 v42, 20, v22
	v_or_b32_e32 v44, 22, v22
	v_or_b32_e32 v46, 24, v22
	v_or_b32_e32 v48, 26, v22
	v_or_b32_e32 v50, 28, v22
	v_or_b32_e32 v52, 30, v22
	v_or_b32_e32 v54, 32, v22
	v_or_b32_e32 v56, 34, v22
	v_or_b32_e32 v58, 36, v22
	v_or_b32_e32 v60, 38, v22
	v_or_b32_e32 v62, 40, v22
	v_lshl_add_u64 v[18:19], s[18:19], 1, v[2:3]
	s_and_b32 s18, s22, 0xffffff00
	s_and_b32 s19, s20, 0x60
	v_lshl_add_u64 v[20:21], s[20:21], 2, v[0:1]
	v_or_b32_e32 v24, 2, v22
	v_or_b32_e32 v26, 4, v22
	v_or_b32_e32 v34, 12, v22
	v_or_b32_e32 v36, 14, v22
	v_or_b32_e32 v38, 16, v22
	v_or_b32_e32 v40, 18, v22
	v_or_b32_e32 v64, 42, v22
	v_or_b32_e32 v66, 44, v22
	v_or_b32_e32 v68, 46, v22
	v_or_b32_e32 v70, 48, v22
	v_or_b32_e32 v72, 50, v22
	v_or_b32_e32 v74, 52, v22
	v_or_b32_e32 v76, 54, v22
	v_or_b32_e32 v78, 56, v22
	v_or_b32_e32 v80, 58, v22
	v_or_b32_e32 v82, 60, v22
	v_or_b32_e32 v84, 62, v22
	s_or_b32 s20, s18, s19
	v_mad_i64_i32 v[22:23], s[18:19], v22, s15, v[20:21]
	v_mad_i64_i32 v[28:29], s[18:19], v28, s15, v[20:21]
	v_mad_i64_i32 v[30:31], s[18:19], v30, s15, v[20:21]
	v_mad_i64_i32 v[32:33], s[18:19], v32, s15, v[20:21]
	v_mad_i64_i32 v[42:43], s[18:19], v42, s15, v[20:21]
	v_mad_i64_i32 v[44:45], s[18:19], v44, s15, v[20:21]
	v_mad_i64_i32 v[46:47], s[18:19], v46, s15, v[20:21]
	v_mad_i64_i32 v[48:49], s[18:19], v48, s15, v[20:21]
	v_mad_i64_i32 v[50:51], s[18:19], v50, s15, v[20:21]
	v_mad_i64_i32 v[52:53], s[18:19], v52, s15, v[20:21]
	v_mad_i64_i32 v[54:55], s[18:19], v54, s15, v[20:21]
	v_mad_i64_i32 v[56:57], s[18:19], v56, s15, v[20:21]
	v_mad_i64_i32 v[58:59], s[18:19], v58, s15, v[20:21]
	v_mad_i64_i32 v[60:61], s[18:19], v60, s15, v[20:21]
	v_mad_i64_i32 v[62:63], s[18:19], v62, s15, v[20:21]
	v_mad_i64_i32 v[24:25], s[18:19], v24, s15, v[20:21]
	v_mad_i64_i32 v[26:27], s[18:19], v26, s15, v[20:21]
	v_mad_i64_i32 v[34:35], s[18:19], v34, s15, v[20:21]
	v_mad_i64_i32 v[36:37], s[18:19], v36, s15, v[20:21]
	v_mad_i64_i32 v[38:39], s[18:19], v38, s15, v[20:21]
	v_mad_i64_i32 v[40:41], s[18:19], v40, s15, v[20:21]
	v_mad_i64_i32 v[64:65], s[18:19], v64, s15, v[20:21]
	v_mad_i64_i32 v[66:67], s[18:19], v66, s15, v[20:21]
	v_mad_i64_i32 v[68:69], s[18:19], v68, s15, v[20:21]
	v_mad_i64_i32 v[70:71], s[18:19], v70, s15, v[20:21]
	v_mad_i64_i32 v[72:73], s[18:19], v72, s15, v[20:21]
	v_mad_i64_i32 v[74:75], s[18:19], v74, s15, v[20:21]
	v_mad_i64_i32 v[76:77], s[18:19], v76, s15, v[20:21]
	v_mad_i64_i32 v[78:79], s[18:19], v78, s15, v[20:21]
	v_mad_i64_i32 v[80:81], s[18:19], v80, s15, v[20:21]
	v_mad_i64_i32 v[82:83], s[18:19], v82, s15, v[20:21]
	v_mad_i64_i32 v[20:21], s[18:19], v84, s15, v[20:21]
	global_load_dword v92, v[22:23], off nt
	global_load_dword v93, v[24:25], off nt
	global_load_dword v94, v[26:27], off nt
	s_nop 0
	global_load_dword v28, v[28:29], off nt
	s_nop 0
	global_load_dword v29, v[30:31], off nt
	s_nop 0
	global_load_dword v30, v[32:33], off nt
	global_load_dword v31, v[34:35], off nt
	s_nop 0
	global_load_dword v32, v[36:37], off nt
	global_load_dword v33, v[38:39], off nt
	global_load_dword v95, v[40:41], off nt
	s_nop 0
	global_load_dword v42, v[42:43], off nt
	s_nop 0
	global_load_dword v43, v[44:45], off nt
	s_nop 0
	global_load_dword v44, v[46:47], off nt
	global_load_dword v45, v[48:49], off nt
	s_nop 0
	global_load_dword v46, v[50:51], off nt
	global_load_dword v47, v[52:53], off nt
	global_load_dword v48, v[54:55], off nt
	global_load_dword v49, v[56:57], off nt
	s_nop 0
	global_load_dword v50, v[58:59], off nt
	global_load_dword v51, v[60:61], off nt
	global_load_dword v52, v[62:63], off nt
	global_load_dword v53, v[64:65], off nt
	global_load_dword v54, v[66:67], off nt
	global_load_dword v55, v[68:69], off nt
	global_load_dword v56, v[70:71], off nt
	global_load_dword v57, v[72:73], off nt
	global_load_dword v58, v[74:75], off nt
	global_load_dword v59, v[76:77], off nt
	global_load_dword v60, v[78:79], off nt
	global_load_dword v61, v[80:81], off nt
	global_load_dword v62, v[82:83], off nt
	global_load_dword v63, v[20:21], off nt
	v_or_b32_e32 v84, s20, v5
	v_or_b32_e32 v86, s20, v7
	v_or_b32_e32 v88, s20, v8
	v_or_b32_e32 v90, s20, v9
	v_ashrrev_i32_e32 v85, 31, v84
	v_ashrrev_i32_e32 v87, 31, v86
	v_ashrrev_i32_e32 v89, 31, v88
	v_ashrrev_i32_e32 v91, 31, v90
	s_waitcnt vmcnt(30)
	ds_write2_b32 v10, v92, v93 offset1:66
	s_waitcnt vmcnt(28)
	ds_write2_b32 v10, v94, v28 offset0:132 offset1:198
	s_waitcnt vmcnt(26)
	ds_write2_b32 v11, v29, v30 offset0:8 offset1:74
	s_waitcnt vmcnt(24)
	ds_write2_b32 v11, v31, v32 offset0:140 offset1:206
	s_waitcnt vmcnt(22)
	ds_write2_b32 v12, v33, v95 offset0:16 offset1:82
	s_waitcnt vmcnt(20)
	ds_write2_b32 v12, v42, v43 offset0:148 offset1:214
	s_waitcnt vmcnt(18)
	ds_write2_b32 v13, v44, v45 offset0:24 offset1:90
	s_waitcnt vmcnt(16)
; #define LAS __attribute__((address_space(3)))
; __device__ __forceinline__ unsigned pk2(float lo, float hi) { return f2bf(lo) | (f2bf(hi) << 16); }
; __device__ __forceinline__ void transpose_item(const float* W, int K, int Nsrc, int c0, bf16_t* WT, int mode, LAS float* scr, int kb, int nb, int lane) {
;     ...
;     for (int i = 0; i < 32; ++i) { const int kk = 2 * i + (lane >> 5); scr[kk * 33 + (lane & 31)] = tv[i]; }
;     asm volatile("s_waitcnt lgkmcnt(0)" ::: "memory");
;     const int c = lane & 7;
; #pragma unroll
;     for (int j = 0; j < 4; ++j) { const int n = (lane >> 3) + 8 * j; const LAS float* s = scr + (8 * c) * 33 + n;
;         u32x4 o; o.x = pk2(s[0 * 33], s[1 * 33]); o.y = pk2(s[2 * 33], s[3 * 33]); o.z = pk2(s[4 * 33], s[5 * 33]); o.w = pk2(s[6 * 33], s[7 * 33]);
;         const int nn = n0 + n; const int row = (mode == 0) ? nn : ((nn >> 7) * 256 + (nn & 127) + (mode == 2 ? 128 : 0));
;         *(u32x4*)(WT + (size_t)row * K + k0 + 8 * c) = o; }
;     asm volatile("s_waitcnt lgkmcnt(0)" ::: "memory");
	ds_write2_b32 v13, v46, v47 offset0:156 offset1:222
	s_waitcnt vmcnt(14)
	ds_write2_b32 v14, v48, v49 offset0:32 offset1:98
	s_waitcnt vmcnt(12)
	ds_write2_b32 v14, v50, v51 offset0:164 offset1:230
	s_waitcnt vmcnt(10)
	ds_write2_b32 v15, v52, v53 offset0:40 offset1:106
	s_waitcnt vmcnt(8)
	ds_write2_b32 v15, v54, v55 offset0:172 offset1:238
	s_waitcnt vmcnt(6)
	ds_write2_b32 v16, v56, v57 offset0:48 offset1:114
	s_waitcnt vmcnt(4)
	ds_write2_b32 v16, v58, v59 offset0:180 offset1:246
	s_waitcnt vmcnt(2)
	ds_write2_b32 v17, v60, v61 offset0:56 offset1:122
	s_waitcnt vmcnt(0)
	ds_write2_b32 v17, v62, v63 offset0:188 offset1:254
	v_lshlrev_b64 v[20:21], 12, v[84:85]
	v_lshlrev_b64 v[22:23], 12, v[86:87]
	v_lshlrev_b64 v[24:25], 12, v[88:89]
	v_lshlrev_b64 v[26:27], 12, v[90:91]
	s_waitcnt lgkmcnt(0)
	v_lshl_add_u64 v[34:35], v[18:19], 0, v[20:21]
	v_lshl_add_u64 v[36:37], v[18:19], 0, v[22:23]
	v_lshl_add_u64 v[38:39], v[18:19], 0, v[24:25]
	v_lshl_add_u64 v[40:41], v[18:19], 0, v[26:27]
	ds_read2_b32 v[18:19], v6 offset0:33 offset1:41
	ds_read2_b32 v[20:21], v6 offset1:8
	ds_read2_b32 v[22:23], v6 offset0:66 offset1:74
	ds_read2_b32 v[24:25], v6 offset0:99 offset1:107
	ds_read2_b32 v[26:27], v6 offset0:132 offset1:140
	ds_read2_b32 v[28:29], v6 offset0:165 offset1:173
	ds_read2_b32 v[30:31], v6 offset0:198 offset1:206
	ds_read2_b32 v[32:33], v6 offset0:231 offset1:239
	ds_read2_b32 v[42:43], v6 offset0:49 offset1:57
	ds_read2_b32 v[44:45], v6 offset0:16 offset1:24
	ds_read2_b32 v[46:47], v6 offset0:82 offset1:90
	ds_read2_b32 v[48:49], v6 offset0:115 offset1:123
	ds_read2_b32 v[50:51], v6 offset0:148 offset1:156
	ds_read2_b32 v[52:53], v6 offset0:181 offset1:189
	ds_read2_b32 v[54:55], v6 offset0:214 offset1:222
	ds_read2_b32 v[56:57], v6 offset0:247 offset1:255
	s_waitcnt lgkmcnt(14)
	v_bfe_u32 v58, v20, 16, 1
	s_waitcnt lgkmcnt(13)
	v_bfe_u32 v60, v22, 16, 1
	s_waitcnt lgkmcnt(11)
	v_bfe_u32 v62, v26, 16, 1
	s_waitcnt lgkmcnt(9)
	v_bfe_u32 v64, v30, 16, 1
	v_bfe_u32 v59, v18, 16, 1
	v_bfe_u32 v61, v24, 16, 1
	v_bfe_u32 v63, v28, 16, 1
	s_waitcnt lgkmcnt(8)
	v_bfe_u32 v65, v32, 16, 1
	v_bfe_u32 v66, v21, 16, 1
	v_bfe_u32 v67, v19, 16, 1
	v_bfe_u32 v68, v23, 16, 1
	v_bfe_u32 v69, v25, 16, 1
	v_bfe_u32 v70, v27, 16, 1
	v_bfe_u32 v71, v29, 16, 1
	v_bfe_u32 v72, v31, 16, 1
	v_bfe_u32 v73, v33, 16, 1
	s_waitcnt lgkmcnt(6)
	v_bfe_u32 v74, v44, 16, 1
	s_waitcnt lgkmcnt(5)
	v_bfe_u32 v76, v46, 16, 1
	s_waitcnt lgkmcnt(4)
	v_bfe_u32 v77, v48, 16, 1
	s_waitcnt lgkmcnt(3)
	v_bfe_u32 v78, v50, 16, 1
	s_waitcnt lgkmcnt(2)
	v_bfe_u32 v79, v52, 16, 1
	s_waitcnt lgkmcnt(1)
	v_bfe_u32 v80, v54, 16, 1
	v_bfe_u32 v82, v45, 16, 1
	v_bfe_u32 v84, v47, 16, 1
	v_bfe_u32 v86, v51, 16, 1
	v_bfe_u32 v88, v55, 16, 1
	v_add3_u32 v20, v20, v58, s16
	v_add3_u32 v22, v22, v60, s16
	v_add3_u32 v26, v26, v62, s16
	v_add3_u32 v30, v30, v64, s16
	v_bfe_u32 v75, v42, 16, 1
	s_waitcnt lgkmcnt(0)
	v_bfe_u32 v81, v56, 16, 1
	v_bfe_u32 v83, v43, 16, 1
	v_bfe_u32 v85, v49, 16, 1
	v_bfe_u32 v87, v53, 16, 1
	v_bfe_u32 v89, v57, 16, 1
	v_add3_u32 v18, v18, v59, s16
	v_add3_u32 v24, v24, v61, s16
	v_add3_u32 v28, v28, v63, s16
	v_add3_u32 v32, v32, v65, s16
	v_add3_u32 v21, v21, v66, s16
	v_add3_u32 v58, v19, v67, s16
	v_add3_u32 v19, v23, v68, s16
	v_add3_u32 v23, v25, v69, s16
	v_add3_u32 v25, v27, v70, s16
	v_add3_u32 v27, v29, v71, s16
	v_add3_u32 v29, v31, v72, s16
	v_add3_u32 v31, v33, v73, s16
	v_add3_u32 v33, v44, v74, s16
	v_add3_u32 v44, v46, v76, s16
	v_add3_u32 v46, v48, v77, s16
	v_add3_u32 v48, v50, v78, s16
	v_add3_u32 v50, v52, v79, s16
	v_add3_u32 v52, v54, v80, s16
	v_add3_u32 v45, v45, v82, s16
	v_add3_u32 v47, v47, v84, s16
	v_add3_u32 v51, v51, v86, s16
	v_add3_u32 v55, v55, v88, s16
	v_lshrrev_b32_e32 v20, 16, v20
	v_lshrrev_b32_e32 v22, 16, v22
	v_lshrrev_b32_e32 v26, 16, v26
	v_lshrrev_b32_e32 v30, 16, v30
	v_add3_u32 v42, v42, v75, s16
	v_add3_u32 v54, v56, v81, s16
	v_add3_u32 v43, v43, v83, s16
	v_add3_u32 v49, v49, v85, s16
	v_add3_u32 v53, v53, v87, s16
	v_add3_u32 v56, v57, v89, s16
	v_lshrrev_b32_e32 v57, 16, v21
	v_lshrrev_b32_e32 v59, 16, v19
	v_lshrrev_b32_e32 v25, 16, v25
	v_lshrrev_b32_e32 v29, 16, v29
	v_lshrrev_b32_e32 v33, 16, v33
	v_lshrrev_b32_e32 v44, 16, v44
	v_lshrrev_b32_e32 v48, 16, v48
	v_lshrrev_b32_e32 v52, 16, v52
	v_lshrrev_b32_e32 v45, 16, v45
	v_lshrrev_b32_e32 v47, 16, v47
	v_lshrrev_b32_e32 v51, 16, v51
	v_lshrrev_b32_e32 v55, 16, v55
	v_and_or_b32 v18, v18, s17, v20
	v_and_or_b32 v19, v24, s17, v22
	v_and_or_b32 v20, v28, s17, v26
	v_and_or_b32 v21, v32, s17, v30
	v_and_or_b32 v22, v58, s17, v57
	v_and_or_b32 v23, v23, s17, v59
	v_and_or_b32 v24, v27, s17, v25
	v_and_or_b32 v25, v31, s17, v29
	v_and_or_b32 v26, v42, s17, v33
	v_and_or_b32 v27, v46, s17, v44
	v_and_or_b32 v28, v50, s17, v48
	v_and_or_b32 v29, v54, s17, v52
	v_and_or_b32 v30, v43, s17, v45
	v_and_or_b32 v31, v49, s17, v47
	v_and_or_b32 v32, v53, s17, v51
	v_and_or_b32 v33, v56, s17, v55
	global_store_dwordx4 v[34:35], v[18:21], off
	global_store_dwordx4 v[36:37], v[22:25], off
	global_store_dwordx4 v[38:39], v[26:29], off
	global_store_dwordx4 v[40:41], v[30:33], off
	s_waitcnt lgkmcnt(0)
	s_add_i32 s10, s10, s3
	s_add_i32 s11, s11, s12
	s_add_i32 s13, s13, s14
	s_cmpk_lt_i32 s10, 0x1600
	s_cbranch_scc1 .LBB0_112

; #define LAS __attribute__((address_space(3)))
; __device__ __forceinline__ void transpose_item(const float* W, int K, int Nsrc, int c0, bf16_t* WT, int mode, LAS float* scr, int kb, int nb, int lane) {
;     const int k0 = 64 * kb, n0 = 32 * nb;
;     float tv[32];
; #pragma unroll
;     for (int i = 0; i < 32; ++i) { const int kk = 2 * i + (lane >> 5); tv[i] = W[(size_t)(k0 + kk) * Nsrc + c0 + n0 + (lane & 31)]; }
; #pragma unroll
;     for (int i = 0; i < 32; ++i) { const int kk = 2 * i + (lane >> 5); scr[kk * 33 + (lane & 31)] = tv[i]; }
;     ...
;         const int nn = n0 + n; const int row = (mode == 0) ? nn : ((nn >> 7) * 256 + (nn & 127) + (mode == 2 ? 128 : 0));
;         *(u32x4*)(WT + (size_t)row * K + k0 + 8 * c) = o; }
;     asm volatile("s_waitcnt lgkmcnt(0)" ::: "memory");
; }
;     if (gw < 0) { gw = F.bid * 8 + F.wave; NGW = F.G * 8; }
;     const int nnb = ncols / 32, items = (K / 64) * nnb;
;     const int first = (gw - base % NGW + NGW) % NGW;
;     for (int it = first; it < items; it += NGW) transpose_item(W, K, Nsrc, c0, WT, mode, scr, it / nnb, it % nnb, F.lane);
.LBB0_115:
	s_mul_hi_i32 s12, s5, 0x2e8ba2e9
	s_lshr_b32 s13, s12, 31
	s_ashr_i32 s12, s12, 5
	s_add_i32 s13, s12, s13
	s_mul_i32 s14, s13, 0xffffea00
	s_lshl_b32 s12, s13, 6
	s_mul_i32 s15, s13, 0xffffd400
	s_add_i32 s14, s0, s14
	v_or_b32_e32 v15, s12, v4
	s_ashr_i32 s13, s12, 31
	s_add_i32 s16, s4, s15
	s_ashr_i32 s15, s14, 31
	v_or_b32_e32 v26, 6, v15
	v_or_b32_e32 v28, 8, v15
	v_or_b32_e32 v30, 10, v15
	v_or_b32_e32 v40, 20, v15
	v_or_b32_e32 v42, 22, v15
	v_or_b32_e32 v44, 24, v15
	v_or_b32_e32 v46, 26, v15
	v_or_b32_e32 v48, 28, v15
	v_or_b32_e32 v50, 30, v15
	v_or_b32_e32 v52, 32, v15
	v_or_b32_e32 v54, 34, v15
	v_or_b32_e32 v56, 36, v15
	v_or_b32_e32 v58, 38, v15
	v_or_b32_e32 v60, 40, v15
	v_lshl_add_u64 v[16:17], s[12:13], 1, v[2:3]
	s_and_b32 s12, s16, 0xffffff00
	s_and_b32 s13, s14, 0x60
	v_lshl_add_u64 v[18:19], s[14:15], 2, v[0:1]
	v_or_b32_e32 v22, 2, v15
	v_or_b32_e32 v24, 4, v15
	v_or_b32_e32 v32, 12, v15
	v_or_b32_e32 v34, 14, v15
	v_or_b32_e32 v36, 16, v15
	v_or_b32_e32 v38, 18, v15
	v_or_b32_e32 v62, 42, v15
	v_or_b32_e32 v64, 44, v15
	v_or_b32_e32 v66, 46, v15
	v_or_b32_e32 v68, 48, v15
	v_or_b32_e32 v70, 50, v15
	v_or_b32_e32 v72, 52, v15
	v_or_b32_e32 v74, 54, v15
	v_or_b32_e32 v76, 56, v15
	v_or_b32_e32 v78, 58, v15
	v_or_b32_e32 v80, 60, v15
	v_or_b32_e32 v82, 62, v15
	s_or_b32 s14, s12, s13
	v_mad_i64_i32 v[20:21], s[12:13], v15, s7, v[18:19]
	v_mad_i64_i32 v[26:27], s[12:13], v26, s7, v[18:19]
	v_mad_i64_i32 v[28:29], s[12:13], v28, s7, v[18:19]
	v_mad_i64_i32 v[30:31], s[12:13], v30, s7, v[18:19]
	v_mad_i64_i32 v[40:41], s[12:13], v40, s7, v[18:19]
	v_mad_i64_i32 v[42:43], s[12:13], v42, s7, v[18:19]
	v_mad_i64_i32 v[44:45], s[12:13], v44, s7, v[18:19]
	v_mad_i64_i32 v[46:47], s[12:13], v46, s7, v[18:19]
	v_mad_i64_i32 v[48:49], s[12:13], v48, s7, v[18:19]
	v_mad_i64_i32 v[50:51], s[12:13], v50, s7, v[18:19]
	v_mad_i64_i32 v[52:53], s[12:13], v52, s7, v[18:19]
	v_mad_i64_i32 v[54:55], s[12:13], v54, s7, v[18:19]
	v_mad_i64_i32 v[56:57], s[12:13], v56, s7, v[18:19]
	v_mad_i64_i32 v[58:59], s[12:13], v58, s7, v[18:19]
	v_mad_i64_i32 v[60:61], s[12:13], v60, s7, v[18:19]
	v_mad_i64_i32 v[22:23], s[12:13], v22, s7, v[18:19]
	v_mad_i64_i32 v[24:25], s[12:13], v24, s7, v[18:19]
	v_mad_i64_i32 v[32:33], s[12:13], v32, s7, v[18:19]
	v_mad_i64_i32 v[34:35], s[12:13], v34, s7, v[18:19]
	v_mad_i64_i32 v[36:37], s[12:13], v36, s7, v[18:19]
	v_mad_i64_i32 v[38:39], s[12:13], v38, s7, v[18:19]
	v_mad_i64_i32 v[62:63], s[12:13], v62, s7, v[18:19]
	v_mad_i64_i32 v[64:65], s[12:13], v64, s7, v[18:19]
	v_mad_i64_i32 v[66:67], s[12:13], v66, s7, v[18:19]
	v_mad_i64_i32 v[68:69], s[12:13], v68, s7, v[18:19]
	v_mad_i64_i32 v[70:71], s[12:13], v70, s7, v[18:19]
	v_mad_i64_i32 v[72:73], s[12:13], v72, s7, v[18:19]
	v_mad_i64_i32 v[74:75], s[12:13], v74, s7, v[18:19]
	v_mad_i64_i32 v[76:77], s[12:13], v76, s7, v[18:19]
	v_mad_i64_i32 v[78:79], s[12:13], v78, s7, v[18:19]
	v_mad_i64_i32 v[80:81], s[12:13], v80, s7, v[18:19]
	v_mad_i64_i32 v[18:19], s[12:13], v82, s7, v[18:19]
	global_load_dword v82, v[20:21], off nt
	global_load_dword v83, v[22:23], off nt
	global_load_dword v84, v[24:25], off nt
	s_nop 0
	global_load_dword v26, v[26:27], off nt
	s_nop 0
	global_load_dword v27, v[28:29], off nt
	s_nop 0
	global_load_dword v28, v[30:31], off nt
	global_load_dword v29, v[32:33], off nt
	s_nop 0
	global_load_dword v30, v[34:35], off nt
	global_load_dword v31, v[36:37], off nt
	global_load_dword v85, v[38:39], off nt
	s_nop 0
	global_load_dword v40, v[40:41], off nt
	s_nop 0
	global_load_dword v41, v[42:43], off nt
	s_nop 0
	global_load_dword v42, v[44:45], off nt
	global_load_dword v43, v[46:47], off nt
	s_nop 0
	global_load_dword v44, v[48:49], off nt
	global_load_dword v45, v[50:51], off nt
	global_load_dword v46, v[52:53], off nt
	global_load_dword v47, v[54:55], off nt
	s_nop 0
	global_load_dword v48, v[56:57], off nt
	global_load_dword v49, v[58:59], off nt
	global_load_dword v50, v[60:61], off nt
	global_load_dword v51, v[62:63], off nt
	global_load_dword v52, v[64:65], off nt
	global_load_dword v53, v[66:67], off nt
	global_load_dword v54, v[68:69], off nt
	global_load_dword v55, v[70:71], off nt
	global_load_dword v56, v[72:73], off nt
	global_load_dword v57, v[74:75], off nt
	global_load_dword v58, v[76:77], off nt
	global_load_dword v59, v[78:79], off nt
	global_load_dword v60, v[80:81], off nt
	global_load_dword v61, v[18:19], off nt
	v_or_b32_e32 v15, s14, v5
	v_or_b32_e32 v18, 0x80, v15
	v_or_b32_e32 v20, 0x88, v15
	v_or_b32_e32 v22, 0x90, v15
	v_or_b32_e32 v24, 0x98, v15
	v_ashrrev_i32_e32 v19, 31, v18
	v_ashrrev_i32_e32 v21, 31, v20
	v_ashrrev_i32_e32 v23, 31, v22
	v_ashrrev_i32_e32 v25, 31, v24
	s_waitcnt vmcnt(30)
	ds_write2_b32 v7, v82, v83 offset1:66
	s_waitcnt vmcnt(28)
	ds_write2_b32 v7, v84, v26 offset0:132 offset1:198
	s_waitcnt vmcnt(26)
	ds_write2_b32 v8, v27, v28 offset0:8 offset1:74
	s_waitcnt vmcnt(24)
	ds_write2_b32 v8, v29, v30 offset0:140 offset1:206
	s_waitcnt vmcnt(22)
	ds_write2_b32 v9, v31, v85 offset0:16 offset1:82
	s_waitcnt vmcnt(20)
	ds_write2_b32 v9, v40, v41 offset0:148 offset1:214
	s_waitcnt vmcnt(18)
	ds_write2_b32 v10, v42, v43 offset0:24 offset1:90
	s_waitcnt vmcnt(16)
	ds_write2_b32 v10, v44, v45 offset0:156 offset1:222
	s_waitcnt vmcnt(14)
; #define LAS __attribute__((address_space(3)))
; __device__ __forceinline__ unsigned pk2(float lo, float hi) { return f2bf(lo) | (f2bf(hi) << 16); }
; __device__ __forceinline__ void transpose_item(const float* W, int K, int Nsrc, int c0, bf16_t* WT, int mode, LAS float* scr, int kb, int nb, int lane) {
;     ...
;     for (int i = 0; i < 32; ++i) { const int kk = 2 * i + (lane >> 5); scr[kk * 33 + (lane & 31)] = tv[i]; }
;     asm volatile("s_waitcnt lgkmcnt(0)" ::: "memory");
;     const int c = lane & 7;
; #pragma unroll
;     for (int j = 0; j < 4; ++j) { const int n = (lane >> 3) + 8 * j; const LAS float* s = scr + (8 * c) * 33 + n;
;         u32x4 o; o.x = pk2(s[0 * 33], s[1 * 33]); o.y = pk2(s[2 * 33], s[3 * 33]); o.z = pk2(s[4 * 33], s[5 * 33]); o.w = pk2(s[6 * 33], s[7 * 33]);
;         const int nn = n0 + n; const int row = (mode == 0) ? nn : ((nn >> 7) * 256 + (nn & 127) + (mode == 2 ? 128 : 0));
;         *(u32x4*)(WT + (size_t)row * K + k0 + 8 * c) = o; }
;     asm volatile("s_waitcnt lgkmcnt(0)" ::: "memory");
	ds_write2_b32 v11, v46, v47 offset0:32 offset1:98
	s_waitcnt vmcnt(12)
	ds_write2_b32 v11, v48, v49 offset0:164 offset1:230
	s_waitcnt vmcnt(10)
	ds_write2_b32 v12, v50, v51 offset0:40 offset1:106
	s_waitcnt vmcnt(8)
	ds_write2_b32 v12, v52, v53 offset0:172 offset1:238
	s_waitcnt vmcnt(6)
	ds_write2_b32 v13, v54, v55 offset0:48 offset1:114
	s_waitcnt vmcnt(4)
	ds_write2_b32 v13, v56, v57 offset0:180 offset1:246
	s_waitcnt vmcnt(2)
	ds_write2_b32 v14, v58, v59 offset0:56 offset1:122
	s_waitcnt vmcnt(0)
	ds_write2_b32 v14, v60, v61 offset0:188 offset1:254
	v_lshlrev_b64 v[18:19], 12, v[18:19]
	v_lshlrev_b64 v[20:21], 12, v[20:21]
	v_lshlrev_b64 v[22:23], 12, v[22:23]
	v_lshlrev_b64 v[24:25], 12, v[24:25]
	s_waitcnt lgkmcnt(0)
	v_lshl_add_u64 v[32:33], v[16:17], 0, v[18:19]
	v_lshl_add_u64 v[34:35], v[16:17], 0, v[20:21]
	v_lshl_add_u64 v[36:37], v[16:17], 0, v[22:23]
	v_lshl_add_u64 v[38:39], v[16:17], 0, v[24:25]
	ds_read2_b32 v[16:17], v6 offset0:33 offset1:41
	ds_read2_b32 v[18:19], v6 offset1:8
	ds_read2_b32 v[20:21], v6 offset0:66 offset1:74
	ds_read2_b32 v[22:23], v6 offset0:99 offset1:107
	ds_read2_b32 v[24:25], v6 offset0:132 offset1:140
	ds_read2_b32 v[26:27], v6 offset0:165 offset1:173
	ds_read2_b32 v[28:29], v6 offset0:198 offset1:206
	ds_read2_b32 v[30:31], v6 offset0:231 offset1:239
	ds_read2_b32 v[40:41], v6 offset0:49 offset1:57
	ds_read2_b32 v[42:43], v6 offset0:16 offset1:24
	ds_read2_b32 v[44:45], v6 offset0:82 offset1:90
	ds_read2_b32 v[46:47], v6 offset0:115 offset1:123
	ds_read2_b32 v[48:49], v6 offset0:148 offset1:156
	ds_read2_b32 v[50:51], v6 offset0:181 offset1:189
	ds_read2_b32 v[52:53], v6 offset0:214 offset1:222
	ds_read2_b32 v[54:55], v6 offset0:247 offset1:255
	s_waitcnt lgkmcnt(14)
	v_bfe_u32 v15, v18, 16, 1
	s_waitcnt lgkmcnt(13)
	v_bfe_u32 v57, v20, 16, 1
	s_waitcnt lgkmcnt(12)
	v_bfe_u32 v58, v22, 16, 1
	s_waitcnt lgkmcnt(11)
	v_bfe_u32 v59, v24, 16, 1
	s_waitcnt lgkmcnt(10)
	v_bfe_u32 v60, v26, 16, 1
	s_waitcnt lgkmcnt(9)
	v_bfe_u32 v61, v28, 16, 1
	v_bfe_u32 v56, v16, 16, 1
	s_waitcnt lgkmcnt(8)
	v_bfe_u32 v62, v30, 16, 1
	v_bfe_u32 v63, v19, 16, 1
	v_bfe_u32 v64, v17, 16, 1
	v_bfe_u32 v65, v21, 16, 1
	v_bfe_u32 v66, v23, 16, 1
	v_bfe_u32 v67, v25, 16, 1
	v_bfe_u32 v68, v27, 16, 1
	v_bfe_u32 v69, v29, 16, 1
	v_bfe_u32 v70, v31, 16, 1
	s_waitcnt lgkmcnt(6)
	v_bfe_u32 v71, v42, 16, 1
	s_waitcnt lgkmcnt(5)
	v_bfe_u32 v73, v44, 16, 1
	s_waitcnt lgkmcnt(4)
	v_bfe_u32 v74, v46, 16, 1
	s_waitcnt lgkmcnt(3)
	v_bfe_u32 v75, v48, 16, 1
	s_waitcnt lgkmcnt(2)
	v_bfe_u32 v76, v50, 16, 1
	s_waitcnt lgkmcnt(1)
	v_bfe_u32 v77, v52, 16, 1
	v_bfe_u32 v79, v43, 16, 1
	v_bfe_u32 v81, v45, 16, 1
	v_bfe_u32 v83, v49, 16, 1
	v_bfe_u32 v85, v53, 16, 1
	v_add3_u32 v15, v18, v15, s10
	v_add3_u32 v18, v20, v57, s10
	v_add3_u32 v20, v22, v58, s10
	v_add3_u32 v22, v24, v59, s10
	v_add3_u32 v24, v26, v60, s10
	v_add3_u32 v26, v28, v61, s10
	v_bfe_u32 v72, v40, 16, 1
	s_waitcnt lgkmcnt(0)
	v_bfe_u32 v78, v54, 16, 1
	v_bfe_u32 v80, v41, 16, 1
	v_bfe_u32 v82, v47, 16, 1
	v_bfe_u32 v84, v51, 16, 1
	v_bfe_u32 v86, v55, 16, 1
	v_add3_u32 v16, v16, v56, s10
	v_add3_u32 v28, v30, v62, s10
	v_add3_u32 v19, v19, v63, s10
	v_add3_u32 v30, v17, v64, s10
	v_add3_u32 v17, v21, v65, s10
	v_add3_u32 v21, v23, v66, s10
	v_add3_u32 v23, v25, v67, s10
	v_add3_u32 v25, v27, v68, s10
	v_add3_u32 v27, v29, v69, s10
	v_add3_u32 v29, v31, v70, s10
	v_add3_u32 v31, v42, v71, s10
	v_add3_u32 v42, v44, v73, s10
	v_add3_u32 v44, v46, v74, s10
	v_add3_u32 v46, v48, v75, s10
	v_add3_u32 v48, v50, v76, s10
	v_add3_u32 v50, v52, v77, s10
	v_add3_u32 v43, v43, v79, s10
	v_add3_u32 v45, v45, v81, s10
	v_add3_u32 v49, v49, v83, s10
	v_add3_u32 v53, v53, v85, s10
	v_lshrrev_b32_e32 v15, 16, v15
	v_lshrrev_b32_e32 v18, 16, v18
	v_lshrrev_b32_e32 v22, 16, v22
	v_lshrrev_b32_e32 v26, 16, v26
	v_add3_u32 v40, v40, v72, s10
	v_add3_u32 v52, v54, v78, s10
	v_add3_u32 v41, v41, v80, s10
	v_add3_u32 v47, v47, v82, s10
	v_add3_u32 v51, v51, v84, s10
	v_add3_u32 v54, v55, v86, s10
	v_lshrrev_b32_e32 v55, 16, v19
	v_lshrrev_b32_e32 v56, 16, v17
	v_lshrrev_b32_e32 v23, 16, v23
	v_lshrrev_b32_e32 v27, 16, v27
	v_lshrrev_b32_e32 v31, 16, v31
	v_lshrrev_b32_e32 v42, 16, v42
	v_lshrrev_b32_e32 v46, 16, v46
	v_lshrrev_b32_e32 v50, 16, v50
	v_lshrrev_b32_e32 v43, 16, v43
	v_lshrrev_b32_e32 v45, 16, v45
	v_lshrrev_b32_e32 v49, 16, v49
	v_lshrrev_b32_e32 v53, 16, v53
	v_and_or_b32 v16, v16, s11, v15
	v_and_or_b32 v17, v20, s11, v18
	v_and_or_b32 v18, v24, s11, v22
	v_and_or_b32 v19, v28, s11, v26
	v_and_or_b32 v20, v30, s11, v55
	v_and_or_b32 v21, v21, s11, v56
	v_and_or_b32 v22, v25, s11, v23
	v_and_or_b32 v23, v29, s11, v27
	v_and_or_b32 v24, v40, s11, v31
	v_and_or_b32 v25, v44, s11, v42
	v_and_or_b32 v26, v48, s11, v46
	v_and_or_b32 v27, v52, s11, v50
	v_and_or_b32 v28, v41, s11, v43
	v_and_or_b32 v29, v47, s11, v45
	v_and_or_b32 v30, v51, s11, v49
	v_and_or_b32 v31, v54, s11, v53
	global_store_dwordx4 v[32:33], v[16:19], off
	global_store_dwordx4 v[34:35], v[20:23], off
	global_store_dwordx4 v[36:37], v[24:27], off
	global_store_dwordx4 v[38:39], v[28:31], off
	s_waitcnt lgkmcnt(0)
	s_add_i32 s5, s5, s3
	s_add_i32 s0, s0, s1
	s_add_i32 s4, s4, s6
	s_cmpk_lt_i32 s5, 0x1600
	s_cbranch_scc1 .LBB0_115

; __device__ __forceinline__ unsigned cvt_pk_bf16(float lo, float hi) { unsigned r; asm volatile("v_cvt_pk_bf16_f32 %0, %1, %2" : "=v"(r) : "v"(lo), "v"(hi)); return r; }
; __device__ __forceinline__ float sigmoidf_(float x) { return __builtin_amdgcn_rcpf(1.0f + __expf(-x)); }
;     __device__ __forceinline__ void operator()(const f32x4 (&acc)[2][2][4][2], const Unit& u, int wr, int wc, int fr, int fq) const {
;         const int row0 = u.pm * BM + wr * 64 + fr, col0 = u.pn * BM + wc * 32 + 8 * fq;
;         f32x4 bv[2][2];
; #pragma unroll
;         for (int bj = 0; bj < 2; ++bj)
; #pragma unroll
;             for (int n = 0; n < 2; ++n) bv[bj][n] = *(const f32x4*)(bias + col0 + bj * HALF + 4 * n);
; #pragma unroll
;         for (int ai = 0; ai < 2; ++ai)
; #pragma unroll
;             for (int m = 0; m < 4; ++m) { const size_t r = (size_t)(row0 + ai * HALF + m * 16);
; #pragma unroll
;                 for (int bj = 0; bj < 2; ++bj) {
;                     const u32x4 yv = *(const u32x4*)(Y + r * ldy + col0 + bj * HALF);
;                     const f32x4 v0 = acc[ai][bj][m][0] + bv[bj][0], v1 = acc[ai][bj][m][1] + bv[bj][1];
;                     float o[8];
;                     const unsigned yy[4] = {yv.x, yv.y, yv.z, yv.w};
; #pragma unroll
;                     for (int j = 0; j < 4; ++j) { const float ylo = __uint_as_float(yy[j] << 16), yhi = __uint_as_float(yy[j] & 0xffff0000u);
;                         const float a0 = (j < 2) ? v0[2 * j] : v1[2 * j - 4], a1 = (j < 2) ? v0[2 * j + 1] : v1[2 * j - 3];
;                         o[2 * j] = ylo * sigmoidf_(a0); o[2 * j + 1] = yhi * sigmoidf_(a1); }
;                     u32x4 w; w.x = cvt_pk_bf16(o[0], o[1]); w.y = cvt_pk_bf16(o[2], o[3]); w.z = cvt_pk_bf16(o[4], o[5]); w.w = cvt_pk_bf16(o[6], o[7]);
;                     *(u32x4*)(O + r * ldc + col0 + bj * HALF) = w; } }
.LBB0_1118:
	v_lshl_or_b32 v56, s56, 8, v166
	v_readlane_b32 s56, v247, 12
	v_ashrrev_i32_e32 v57, 31, v56
	v_readlane_b32 s60, v247, 16
	v_readlane_b32 s61, v247, 17
	v_lshl_add_u32 v162, s24, 8, v164
	v_ashrrev_i32_e32 v163, 31, v162
	v_lshl_add_u64 v[58:59], v[56:57], 2, s[60:61]
	global_load_dwordx4 v[80:83], v[58:59], off nt
	global_load_dwordx4 v[76:79], v[58:59], off offset:16 nt
	v_lshlrev_b64 v[60:61], 11, v[162:163]
	v_lshlrev_b64 v[160:161], 1, v[56:57]
	v_lshl_add_u64 v[56:57], s[6:7], 0, v[60:61]
	v_lshl_add_u64 v[174:175], v[56:57], 0, v[160:161]
	global_load_dwordx4 v[170:173], v[174:175], off nt
	global_load_dwordx4 v[60:63], v[58:59], off offset:528 nt
	s_nop 0
	global_load_dwordx4 v[56:59], v[58:59], off offset:512 nt
	s_andn2_b64 vcc, exec, s[0:1]
	s_mov_b64 s[0:1], -1
	v_readlane_b32 s57, v247, 13
	v_readlane_b32 s58, v247, 14
	v_readlane_b32 s59, v247, 15
	v_readlane_b32 s62, v247, 18
	v_readlane_b32 s63, v247, 19
	v_readlane_b32 s64, v247, 20
	v_readlane_b32 s65, v247, 21
	v_readlane_b32 s66, v247, 22
	v_readlane_b32 s67, v247, 23
	v_readlane_b32 s68, v247, 24
	v_readlane_b32 s69, v247, 25
	v_readlane_b32 s70, v247, 26
	v_readlane_b32 s71, v247, 27
	s_waitcnt vmcnt(0)
	v_pk_add_f32 v[142:143], v[142:143], v[82:83]
	v_pk_add_f32 v[140:141], v[140:141], v[80:81]
	v_pk_add_f32 v[138:139], v[138:139], v[78:79]
	v_pk_add_f32 v[136:137], v[136:137], v[76:77]
	v_mul_f32_e32 v140, 0xbfb8aa3b, v140
	v_mul_f32_e32 v141, 0xbfb8aa3b, v141
	v_mul_f32_e32 v142, 0xbfb8aa3b, v142
	v_mul_f32_e32 v143, 0xbfb8aa3b, v143
	v_mul_f32_e32 v139, 0xbfb8aa3b, v139
	v_mul_f32_e32 v136, 0xbfb8aa3b, v136
	v_mul_f32_e32 v137, 0xbfb8aa3b, v137
	v_mul_f32_e32 v138, 0xbfb8aa3b, v138
	v_exp_f32_e32 v140, v140
	v_exp_f32_e32 v141, v141
	v_exp_f32_e32 v142, v142
	v_exp_f32_e32 v143, v143
	v_exp_f32_e32 v139, v139
	v_exp_f32_e32 v136, v136
	v_exp_f32_e32 v137, v137
	v_exp_f32_e32 v138, v138
	v_add_f32_e32 v140, 1.0, v140
	v_add_f32_e32 v141, 1.0, v141
	v_add_f32_e32 v142, 1.0, v142
	v_add_f32_e32 v143, 1.0, v143
	v_add_f32_e32 v139, 1.0, v139
	v_add_f32_e32 v136, 1.0, v136
	v_add_f32_e32 v137, 1.0, v137
	v_add_f32_e32 v138, 1.0, v138
	v_rcp_f32_e32 v140, v140
	v_rcp_f32_e32 v141, v141
	v_rcp_f32_e32 v142, v142
	v_rcp_f32_e32 v143, v143
	v_rcp_f32_e32 v139, v139
	v_rcp_f32_e32 v136, v136
	v_rcp_f32_e32 v137, v137
	v_rcp_f32_e32 v138, v138
	v_lshlrev_b32_e32 v176, 16, v170
	v_and_b32_e32 v170, 0xffff0000, v170
	v_lshlrev_b32_e32 v177, 16, v171
	v_and_b32_e32 v171, 0xffff0000, v171
	v_lshlrev_b32_e32 v179, 16, v173
	v_and_b32_e32 v173, 0xffff0000, v173
	v_lshlrev_b32_e32 v178, 16, v172
	v_and_b32_e32 v172, 0xffff0000, v172
	v_mul_f32_e32 v140, v140, v176
	v_mul_f32_e32 v141, v141, v170
	v_mul_f32_e32 v142, v142, v177
	v_mul_f32_e32 v143, v143, v171
	v_mul_f32_e32 v139, v139, v173
	v_mul_f32_e32 v170, v136, v178
	v_mul_f32_e32 v171, v137, v172
	v_mul_f32_e32 v172, v138, v179
	v_cvt_pk_bf16_f32 v136, v140, v141
	v_cvt_pk_bf16_f32 v137, v142, v143
	v_cvt_pk_bf16_f32 v138, v170, v171
	v_cvt_pk_bf16_f32 v139, v172, v139
	global_load_dwordx4 v[140:143], v[174:175], off offset:256 nt
	v_pk_add_f32 v[134:135], v[134:135], v[58:59]
	v_pk_add_f32 v[132:133], v[132:133], v[56:57]
	v_pk_add_f32 v[130:131], v[130:131], v[62:63]
	v_pk_add_f32 v[128:129], v[128:129], v[60:61]
	v_mul_f32_e32 v132, 0xbfb8aa3b, v132
	v_mul_f32_e32 v133, 0xbfb8aa3b, v133
	v_mul_f32_e32 v134, 0xbfb8aa3b, v134
	v_mul_f32_e32 v135, 0xbfb8aa3b, v135
	v_mul_f32_e32 v131, 0xbfb8aa3b, v131
	v_mul_f32_e32 v128, 0xbfb8aa3b, v128
	v_mul_f32_e32 v129, 0xbfb8aa3b, v129
	v_mul_f32_e32 v130, 0xbfb8aa3b, v130
	v_exp_f32_e32 v132, v132
	v_exp_f32_e32 v133, v133
	v_exp_f32_e32 v134, v134
	v_exp_f32_e32 v135, v135
	v_exp_f32_e32 v131, v131
	v_exp_f32_e32 v128, v128
	v_exp_f32_e32 v129, v129
	v_exp_f32_e32 v130, v130
	v_add_f32_e32 v132, 1.0, v132
	v_add_f32_e32 v133, 1.0, v133
	v_add_f32_e32 v134, 1.0, v134
	v_add_f32_e32 v135, 1.0, v135
	v_add_f32_e32 v131, 1.0, v131
	v_or_b32_e32 v170, 16, v162
	v_lshlrev_b64 v[172:173], 12, v[162:163]
	v_add_f32_e32 v128, 1.0, v128
	v_add_f32_e32 v129, 1.0, v129
	v_add_f32_e32 v130, 1.0, v130
	v_rcp_f32_e32 v132, v132
	v_rcp_f32_e32 v133, v133
	v_rcp_f32_e32 v134, v134
	v_rcp_f32_e32 v135, v135
	v_rcp_f32_e32 v131, v131
	v_ashrrev_i32_e32 v171, 31, v170
	v_lshl_add_u64 v[172:173], s[10:11], 0, v[172:173]
	v_rcp_f32_e32 v128, v128
	v_rcp_f32_e32 v129, v129
	v_rcp_f32_e32 v130, v130
	v_lshlrev_b64 v[174:175], 11, v[170:171]
	v_lshl_add_u64 v[172:173], v[172:173], 0, v[160:161]
	v_lshl_add_u64 v[174:175], s[6:7], 0, v[174:175]
	global_store_dwordx4 v[172:173], v[136:139], off
	v_lshl_add_u64 v[174:175], v[174:175], 0, v[160:161]
	v_pk_add_f32 v[126:127], v[126:127], v[82:83]
	v_pk_add_f32 v[124:125], v[124:125], v[80:81]
	v_pk_add_f32 v[122:123], v[122:123], v[78:79]
	v_pk_add_f32 v[120:121], v[120:121], v[76:77]
	v_mul_f32_e32 v124, 0xbfb8aa3b, v124
	v_mul_f32_e32 v125, 0xbfb8aa3b, v125
	v_mul_f32_e32 v126, 0xbfb8aa3b, v126
	v_mul_f32_e32 v127, 0xbfb8aa3b, v127
	v_mul_f32_e32 v123, 0xbfb8aa3b, v123
	v_mul_f32_e32 v120, 0xbfb8aa3b, v120
	v_mul_f32_e32 v121, 0xbfb8aa3b, v121
	v_mul_f32_e32 v122, 0xbfb8aa3b, v122
	v_exp_f32_e32 v124, v124
	v_exp_f32_e32 v125, v125
	v_exp_f32_e32 v126, v126
	v_exp_f32_e32 v127, v127
	v_exp_f32_e32 v123, v123
	v_exp_f32_e32 v120, v120
	v_exp_f32_e32 v121, v121
	v_exp_f32_e32 v122, v122
	v_add_f32_e32 v124, 1.0, v124
	v_add_f32_e32 v125, 1.0, v125
	v_add_f32_e32 v126, 1.0, v126
	v_add_f32_e32 v127, 1.0, v127
	v_add_f32_e32 v123, 1.0, v123
	v_add_f32_e32 v120, 1.0, v120
	v_add_f32_e32 v121, 1.0, v121
	v_add_f32_e32 v122, 1.0, v122
	v_rcp_f32_e32 v124, v124
	v_rcp_f32_e32 v125, v125
	v_rcp_f32_e32 v126, v126
	v_rcp_f32_e32 v127, v127
	v_rcp_f32_e32 v123, v123
	v_rcp_f32_e32 v120, v120
	s_waitcnt vmcnt(1)
; __device__ __forceinline__ unsigned cvt_pk_bf16(float lo, float hi) { unsigned r; asm volatile("v_cvt_pk_bf16_f32 %0, %1, %2" : "=v"(r) : "v"(lo), "v"(hi)); return r; }
; __device__ __forceinline__ float sigmoidf_(float x) { return __builtin_amdgcn_rcpf(1.0f + __expf(-x)); }
;     __device__ __forceinline__ void operator()(const f32x4 (&acc)[2][2][4][2], const Unit& u, int wr, int wc, int fr, int fq) const {
;     ...
;             for (int m = 0; m < 4; ++m) { const size_t r = (size_t)(row0 + ai * HALF + m * 16);
; #pragma unroll
;                 for (int bj = 0; bj < 2; ++bj) {
;                     const u32x4 yv = *(const u32x4*)(Y + r * ldy + col0 + bj * HALF);
;                     const f32x4 v0 = acc[ai][bj][m][0] + bv[bj][0], v1 = acc[ai][bj][m][1] + bv[bj][1];
;                     float o[8];
;                     const unsigned yy[4] = {yv.x, yv.y, yv.z, yv.w};
; #pragma unroll
;                     for (int j = 0; j < 4; ++j) { const float ylo = __uint_as_float(yy[j] << 16), yhi = __uint_as_float(yy[j] & 0xffff0000u);
;                         const float a0 = (j < 2) ? v0[2 * j] : v1[2 * j - 4], a1 = (j < 2) ? v0[2 * j + 1] : v1[2 * j - 3];
;                         o[2 * j] = ylo * sigmoidf_(a0); o[2 * j + 1] = yhi * sigmoidf_(a1); }
;                     u32x4 w; w.x = cvt_pk_bf16(o[0], o[1]); w.y = cvt_pk_bf16(o[2], o[3]); w.z = cvt_pk_bf16(o[4], o[5]); w.w = cvt_pk_bf16(o[6], o[7]);
;                     *(u32x4*)(O + r * ldc + col0 + bj * HALF) = w; } }
	v_lshlrev_b32_e32 v136, 16, v140
	v_and_b32_e32 v137, 0xffff0000, v140
	v_lshlrev_b32_e32 v138, 16, v141
	v_and_b32_e32 v139, 0xffff0000, v141
	v_lshlrev_b32_e32 v140, 16, v142
	v_and_b32_e32 v141, 0xffff0000, v142
	v_lshlrev_b32_e32 v142, 16, v143
	v_and_b32_e32 v143, 0xffff0000, v143
	v_mul_f32_e32 v132, v132, v136
	v_mul_f32_e32 v133, v133, v137
	v_mul_f32_e32 v134, v134, v138
	v_mul_f32_e32 v135, v135, v139
	v_mul_f32_e32 v131, v131, v143
	v_mul_f32_e32 v136, v128, v140
	v_mul_f32_e32 v137, v129, v141
	v_mul_f32_e32 v138, v130, v142
	v_cvt_pk_bf16_f32 v128, v132, v133
	v_cvt_pk_bf16_f32 v129, v134, v135
	v_cvt_pk_bf16_f32 v130, v136, v137
	v_cvt_pk_bf16_f32 v131, v138, v131
	global_load_dwordx4 v[132:135], v[174:175], off nt
	v_rcp_f32_e32 v121, v121
	v_rcp_f32_e32 v122, v122
	global_store_dwordx4 v[172:173], v[128:131], off offset:256
	v_pk_add_f32 v[118:119], v[118:119], v[58:59]
	v_pk_add_f32 v[116:117], v[116:117], v[56:57]
	v_pk_add_f32 v[114:115], v[114:115], v[62:63]
	v_pk_add_f32 v[112:113], v[112:113], v[60:61]
	v_mul_f32_e32 v116, 0xbfb8aa3b, v116
	v_mul_f32_e32 v117, 0xbfb8aa3b, v117
	v_mul_f32_e32 v118, 0xbfb8aa3b, v118
	v_mul_f32_e32 v119, 0xbfb8aa3b, v119
	v_mul_f32_e32 v115, 0xbfb8aa3b, v115
	v_mul_f32_e32 v112, 0xbfb8aa3b, v112
	v_mul_f32_e32 v113, 0xbfb8aa3b, v113
	v_mul_f32_e32 v114, 0xbfb8aa3b, v114
	v_exp_f32_e32 v116, v116
	v_exp_f32_e32 v117, v117
	v_exp_f32_e32 v118, v118
	v_exp_f32_e32 v119, v119
	v_exp_f32_e32 v115, v115
	v_exp_f32_e32 v112, v112
	v_exp_f32_e32 v113, v113
	v_exp_f32_e32 v114, v114
	v_add_f32_e32 v116, 1.0, v116
	v_add_f32_e32 v117, 1.0, v117
	v_add_f32_e32 v118, 1.0, v118
	v_add_f32_e32 v119, 1.0, v119
	v_add_f32_e32 v115, 1.0, v115
	v_add_f32_e32 v112, 1.0, v112
	v_add_f32_e32 v113, 1.0, v113
	v_add_f32_e32 v114, 1.0, v114
	v_rcp_f32_e32 v116, v116
	v_rcp_f32_e32 v117, v117
	v_rcp_f32_e32 v118, v118
	v_rcp_f32_e32 v119, v119
	v_rcp_f32_e32 v115, v115
	v_rcp_f32_e32 v112, v112
	v_rcp_f32_e32 v113, v113
	v_rcp_f32_e32 v114, v114
	v_pk_add_f32 v[110:111], v[110:111], v[82:83]
	v_pk_add_f32 v[108:109], v[108:109], v[80:81]
	v_pk_add_f32 v[106:107], v[106:107], v[78:79]
	v_pk_add_f32 v[104:105], v[104:105], v[76:77]
	v_mul_f32_e32 v108, 0xbfb8aa3b, v108
	v_mul_f32_e32 v109, 0xbfb8aa3b, v109
	v_mul_f32_e32 v110, 0xbfb8aa3b, v110
	v_mul_f32_e32 v111, 0xbfb8aa3b, v111
	v_mul_f32_e32 v107, 0xbfb8aa3b, v107
	v_mul_f32_e32 v104, 0xbfb8aa3b, v104
	v_mul_f32_e32 v105, 0xbfb8aa3b, v105
	v_mul_f32_e32 v106, 0xbfb8aa3b, v106
	v_exp_f32_e32 v108, v108
	v_exp_f32_e32 v109, v109
	v_exp_f32_e32 v110, v110
	v_exp_f32_e32 v111, v111
	v_exp_f32_e32 v107, v107
	v_exp_f32_e32 v104, v104
	v_exp_f32_e32 v105, v105
	v_exp_f32_e32 v106, v106
	v_add_f32_e32 v108, 1.0, v108
	v_add_f32_e32 v109, 1.0, v109
	v_add_f32_e32 v110, 1.0, v110
	v_add_f32_e32 v111, 1.0, v111
	v_add_f32_e32 v107, 1.0, v107
	v_add_f32_e32 v104, 1.0, v104
	v_add_f32_e32 v105, 1.0, v105
	v_add_f32_e32 v106, 1.0, v106
	v_rcp_f32_e32 v108, v108
	v_rcp_f32_e32 v109, v109
	v_rcp_f32_e32 v110, v110
	v_rcp_f32_e32 v111, v111
	v_rcp_f32_e32 v107, v107
	v_rcp_f32_e32 v104, v104
	v_rcp_f32_e32 v105, v105
	v_rcp_f32_e32 v106, v106
	v_pk_add_f32 v[102:103], v[102:103], v[58:59]
	v_pk_add_f32 v[100:101], v[100:101], v[56:57]
	v_pk_add_f32 v[98:99], v[98:99], v[62:63]
	v_pk_add_f32 v[96:97], v[96:97], v[60:61]
	s_waitcnt vmcnt(1)
	v_lshlrev_b32_e32 v128, 16, v132
	v_and_b32_e32 v129, 0xffff0000, v132
	v_lshlrev_b32_e32 v130, 16, v133
	v_and_b32_e32 v131, 0xffff0000, v133
	v_lshlrev_b32_e32 v132, 16, v134
	v_and_b32_e32 v133, 0xffff0000, v134
	v_lshlrev_b32_e32 v134, 16, v135
	v_and_b32_e32 v135, 0xffff0000, v135
	v_mul_f32_e32 v124, v124, v128
	v_mul_f32_e32 v125, v125, v129
	v_mul_f32_e32 v126, v126, v130
	v_mul_f32_e32 v127, v127, v131
	v_mul_f32_e32 v123, v123, v135
	v_mul_f32_e32 v128, v120, v132
	v_mul_f32_e32 v129, v121, v133
	v_mul_f32_e32 v130, v122, v134
	v_cvt_pk_bf16_f32 v120, v124, v125
	v_cvt_pk_bf16_f32 v121, v126, v127
	v_cvt_pk_bf16_f32 v122, v128, v129
	v_cvt_pk_bf16_f32 v123, v130, v123
	global_load_dwordx4 v[124:127], v[174:175], off offset:256 nt
	v_or_b32_e32 v128, 32, v162
	v_lshlrev_b64 v[130:131], 12, v[170:171]
	v_ashrrev_i32_e32 v129, 31, v128
	v_lshl_add_u64 v[130:131], s[10:11], 0, v[130:131]
	v_lshlrev_b64 v[132:133], 11, v[128:129]
	v_lshl_add_u64 v[130:131], v[130:131], 0, v[160:161]
	v_lshl_add_u64 v[132:133], s[6:7], 0, v[132:133]
	global_store_dwordx4 v[130:131], v[120:123], off
	v_lshl_add_u64 v[132:133], v[132:133], 0, v[160:161]
	v_mul_f32_e32 v100, 0xbfb8aa3b, v100
	v_mul_f32_e32 v101, 0xbfb8aa3b, v101
	v_mul_f32_e32 v102, 0xbfb8aa3b, v102
	v_mul_f32_e32 v103, 0xbfb8aa3b, v103
	v_mul_f32_e32 v99, 0xbfb8aa3b, v99
	v_mul_f32_e32 v96, 0xbfb8aa3b, v96
	v_mul_f32_e32 v97, 0xbfb8aa3b, v97
	v_mul_f32_e32 v98, 0xbfb8aa3b, v98
	v_exp_f32_e32 v100, v100
	v_exp_f32_e32 v101, v101
	v_exp_f32_e32 v102, v102
	v_exp_f32_e32 v103, v103
	v_exp_f32_e32 v99, v99
	v_exp_f32_e32 v96, v96
	v_exp_f32_e32 v97, v97
	v_exp_f32_e32 v98, v98
	v_add_f32_e32 v100, 1.0, v100
	v_add_f32_e32 v101, 1.0, v101
	v_add_f32_e32 v102, 1.0, v102
	v_add_f32_e32 v103, 1.0, v103
	v_add_f32_e32 v99, 1.0, v99
	v_add_f32_e32 v96, 1.0, v96
	v_add_f32_e32 v97, 1.0, v97
	v_add_f32_e32 v98, 1.0, v98
	v_rcp_f32_e32 v100, v100
	v_rcp_f32_e32 v101, v101
	v_rcp_f32_e32 v102, v102
	v_rcp_f32_e32 v103, v103
	v_rcp_f32_e32 v99, v99
	v_rcp_f32_e32 v96, v96
	v_rcp_f32_e32 v97, v97
	v_rcp_f32_e32 v98, v98
	v_pk_add_f32 v[94:95], v[94:95], v[82:83]
	v_pk_add_f32 v[92:93], v[92:93], v[80:81]
	v_pk_add_f32 v[90:91], v[90:91], v[78:79]
	v_pk_add_f32 v[88:89], v[88:89], v[76:77]
	v_mul_f32_e32 v92, 0xbfb8aa3b, v92
	v_mul_f32_e32 v93, 0xbfb8aa3b, v93
	v_mul_f32_e32 v94, 0xbfb8aa3b, v94
	v_mul_f32_e32 v95, 0xbfb8aa3b, v95
	v_mul_f32_e32 v91, 0xbfb8aa3b, v91
	v_mul_f32_e32 v88, 0xbfb8aa3b, v88
	v_mul_f32_e32 v89, 0xbfb8aa3b, v89
	v_mul_f32_e32 v90, 0xbfb8aa3b, v90
	v_exp_f32_e32 v92, v92
	v_exp_f32_e32 v93, v93
	v_exp_f32_e32 v94, v94
	v_exp_f32_e32 v95, v95
	v_exp_f32_e32 v91, v91
	v_exp_f32_e32 v88, v88
	v_exp_f32_e32 v89, v89
	v_exp_f32_e32 v90, v90
	v_add_f32_e32 v92, 1.0, v92
	v_add_f32_e32 v93, 1.0, v93
	v_add_f32_e32 v94, 1.0, v94
	v_add_f32_e32 v95, 1.0, v95
	v_add_f32_e32 v91, 1.0, v91
	v_add_f32_e32 v88, 1.0, v88
	v_add_f32_e32 v89, 1.0, v89
	v_add_f32_e32 v90, 1.0, v90
	v_rcp_f32_e32 v92, v92
	v_rcp_f32_e32 v93, v93
	v_rcp_f32_e32 v94, v94
	v_rcp_f32_e32 v95, v95
	v_rcp_f32_e32 v91, v91
	v_rcp_f32_e32 v88, v88
	v_rcp_f32_e32 v89, v89
	v_rcp_f32_e32 v90, v90
	v_pk_add_f32 v[86:87], v[86:87], v[58:59]
	v_pk_add_f32 v[84:85], v[84:85], v[56:57]
	s_waitcnt vmcnt(1)
; __device__ __forceinline__ unsigned cvt_pk_bf16(float lo, float hi) { unsigned r; asm volatile("v_cvt_pk_bf16_f32 %0, %1, %2" : "=v"(r) : "v"(lo), "v"(hi)); return r; }
; __device__ __forceinline__ float sigmoidf_(float x) { return __builtin_amdgcn_rcpf(1.0f + __expf(-x)); }
;     __device__ __forceinline__ void operator()(const f32x4 (&acc)[2][2][4][2], const Unit& u, int wr, int wc, int fr, int fq) const {
;     ...
;             for (int m = 0; m < 4; ++m) { const size_t r = (size_t)(row0 + ai * HALF + m * 16);
; #pragma unroll
;                 for (int bj = 0; bj < 2; ++bj) {
;                     const u32x4 yv = *(const u32x4*)(Y + r * ldy + col0 + bj * HALF);
;                     const f32x4 v0 = acc[ai][bj][m][0] + bv[bj][0], v1 = acc[ai][bj][m][1] + bv[bj][1];
;                     float o[8];
;                     const unsigned yy[4] = {yv.x, yv.y, yv.z, yv.w};
; #pragma unroll
;                     for (int j = 0; j < 4; ++j) { const float ylo = __uint_as_float(yy[j] << 16), yhi = __uint_as_float(yy[j] & 0xffff0000u);
;                         const float a0 = (j < 2) ? v0[2 * j] : v1[2 * j - 4], a1 = (j < 2) ? v0[2 * j + 1] : v1[2 * j - 3];
;                         o[2 * j] = ylo * sigmoidf_(a0); o[2 * j + 1] = yhi * sigmoidf_(a1); }
;                     u32x4 w; w.x = cvt_pk_bf16(o[0], o[1]); w.y = cvt_pk_bf16(o[2], o[3]); w.z = cvt_pk_bf16(o[4], o[5]); w.w = cvt_pk_bf16(o[6], o[7]);
;                     *(u32x4*)(O + r * ldc + col0 + bj * HALF) = w; } }
	v_lshlrev_b32_e32 v120, 16, v124
	v_and_b32_e32 v121, 0xffff0000, v124
	v_lshlrev_b32_e32 v122, 16, v125
	v_and_b32_e32 v123, 0xffff0000, v125
	v_lshlrev_b32_e32 v124, 16, v126
	v_and_b32_e32 v125, 0xffff0000, v126
	v_lshlrev_b32_e32 v126, 16, v127
	v_and_b32_e32 v127, 0xffff0000, v127
	v_mul_f32_e32 v116, v116, v120
	v_mul_f32_e32 v117, v117, v121
	v_mul_f32_e32 v118, v118, v122
	v_mul_f32_e32 v119, v119, v123
	v_mul_f32_e32 v115, v115, v127
	v_mul_f32_e32 v120, v112, v124
	v_mul_f32_e32 v121, v113, v125
	v_mul_f32_e32 v122, v114, v126
	v_cvt_pk_bf16_f32 v112, v116, v117
	v_cvt_pk_bf16_f32 v113, v118, v119
	v_cvt_pk_bf16_f32 v114, v120, v121
	v_cvt_pk_bf16_f32 v115, v122, v115
	global_load_dwordx4 v[116:119], v[132:133], off nt
	v_pk_add_f32 v[74:75], v[74:75], v[62:63]
	global_store_dwordx4 v[130:131], v[112:115], off offset:256
	v_pk_add_f32 v[72:73], v[72:73], v[60:61]
	v_mul_f32_e32 v84, 0xbfb8aa3b, v84
	v_mul_f32_e32 v85, 0xbfb8aa3b, v85
	v_mul_f32_e32 v86, 0xbfb8aa3b, v86
	v_mul_f32_e32 v87, 0xbfb8aa3b, v87
	v_mul_f32_e32 v75, 0xbfb8aa3b, v75
	v_mul_f32_e32 v72, 0xbfb8aa3b, v72
	v_mul_f32_e32 v73, 0xbfb8aa3b, v73
	v_mul_f32_e32 v74, 0xbfb8aa3b, v74
	v_exp_f32_e32 v84, v84
	v_exp_f32_e32 v85, v85
	v_exp_f32_e32 v86, v86
	v_exp_f32_e32 v87, v87
	v_exp_f32_e32 v75, v75
	v_exp_f32_e32 v72, v72
	v_exp_f32_e32 v73, v73
	v_exp_f32_e32 v74, v74
	v_add_f32_e32 v84, 1.0, v84
	v_add_f32_e32 v85, 1.0, v85
	v_add_f32_e32 v86, 1.0, v86
	v_add_f32_e32 v87, 1.0, v87
	v_add_f32_e32 v75, 1.0, v75
	v_add_f32_e32 v72, 1.0, v72
	v_add_f32_e32 v73, 1.0, v73
	v_add_f32_e32 v74, 1.0, v74
	v_rcp_f32_e32 v84, v84
	v_rcp_f32_e32 v85, v85
	v_rcp_f32_e32 v86, v86
	v_rcp_f32_e32 v87, v87
	v_rcp_f32_e32 v75, v75
	v_rcp_f32_e32 v72, v72
	v_rcp_f32_e32 v73, v73
	v_rcp_f32_e32 v74, v74
	v_pk_add_f32 v[70:71], v[70:71], v[82:83]
	v_pk_add_f32 v[68:69], v[68:69], v[80:81]
	v_pk_add_f32 v[66:67], v[66:67], v[78:79]
	v_pk_add_f32 v[64:65], v[64:65], v[76:77]
	v_mul_f32_e32 v68, 0xbfb8aa3b, v68
	v_mul_f32_e32 v69, 0xbfb8aa3b, v69
	v_mul_f32_e32 v70, 0xbfb8aa3b, v70
	v_mul_f32_e32 v71, 0xbfb8aa3b, v71
	v_mul_f32_e32 v67, 0xbfb8aa3b, v67
	v_mul_f32_e32 v64, 0xbfb8aa3b, v64
	v_mul_f32_e32 v65, 0xbfb8aa3b, v65
	v_mul_f32_e32 v66, 0xbfb8aa3b, v66
	v_exp_f32_e32 v68, v68
	v_exp_f32_e32 v69, v69
	v_exp_f32_e32 v70, v70
	v_exp_f32_e32 v71, v71
	v_exp_f32_e32 v67, v67
	v_exp_f32_e32 v64, v64
	v_exp_f32_e32 v65, v65
	v_exp_f32_e32 v66, v66
	v_add_f32_e32 v68, 1.0, v68
	v_add_f32_e32 v69, 1.0, v69
	v_add_f32_e32 v70, 1.0, v70
	v_add_f32_e32 v71, 1.0, v71
	v_add_f32_e32 v67, 1.0, v67
	v_add_f32_e32 v64, 1.0, v64
	v_add_f32_e32 v65, 1.0, v65
	v_add_f32_e32 v66, 1.0, v66
	v_rcp_f32_e32 v68, v68
	v_rcp_f32_e32 v69, v69
	v_rcp_f32_e32 v70, v70
	v_rcp_f32_e32 v71, v71
	v_rcp_f32_e32 v67, v67
	v_rcp_f32_e32 v64, v64
	v_rcp_f32_e32 v65, v65
	v_rcp_f32_e32 v66, v66
	v_pk_add_f32 v[54:55], v[54:55], v[58:59]
	v_pk_add_f32 v[52:53], v[52:53], v[56:57]
	v_pk_add_f32 v[50:51], v[50:51], v[62:63]
	v_pk_add_f32 v[48:49], v[48:49], v[60:61]
	v_mul_f32_e32 v52, 0xbfb8aa3b, v52
	v_mul_f32_e32 v53, 0xbfb8aa3b, v53
	v_mul_f32_e32 v54, 0xbfb8aa3b, v54
	v_mul_f32_e32 v55, 0xbfb8aa3b, v55
	s_waitcnt vmcnt(1)
	v_lshlrev_b32_e32 v112, 16, v116
	v_and_b32_e32 v113, 0xffff0000, v116
	v_lshlrev_b32_e32 v114, 16, v117
	v_and_b32_e32 v115, 0xffff0000, v117
	v_lshlrev_b32_e32 v116, 16, v118
	v_and_b32_e32 v117, 0xffff0000, v118
	v_lshlrev_b32_e32 v118, 16, v119
	v_and_b32_e32 v119, 0xffff0000, v119
	v_mul_f32_e32 v108, v108, v112
	v_mul_f32_e32 v109, v109, v113
	v_mul_f32_e32 v110, v110, v114
	v_mul_f32_e32 v111, v111, v115
	v_mul_f32_e32 v107, v107, v119
	v_mul_f32_e32 v112, v104, v116
	v_mul_f32_e32 v113, v105, v117
	v_mul_f32_e32 v114, v106, v118
	v_cvt_pk_bf16_f32 v104, v108, v109
	v_cvt_pk_bf16_f32 v105, v110, v111
	v_cvt_pk_bf16_f32 v106, v112, v113
	v_cvt_pk_bf16_f32 v107, v114, v107
	global_load_dwordx4 v[108:111], v[132:133], off offset:256 nt
	v_or_b32_e32 v112, 48, v162
	v_lshlrev_b64 v[114:115], 12, v[128:129]
	v_ashrrev_i32_e32 v113, 31, v112
	v_lshl_add_u64 v[114:115], s[10:11], 0, v[114:115]
	v_lshlrev_b64 v[116:117], 11, v[112:113]
	v_lshl_add_u64 v[114:115], v[114:115], 0, v[160:161]
	v_lshl_add_u64 v[116:117], s[6:7], 0, v[116:117]
	global_store_dwordx4 v[114:115], v[104:107], off
	v_lshl_add_u64 v[116:117], v[116:117], 0, v[160:161]
	v_mul_f32_e32 v51, 0xbfb8aa3b, v51
	v_mul_f32_e32 v48, 0xbfb8aa3b, v48
	v_mul_f32_e32 v49, 0xbfb8aa3b, v49
	v_mul_f32_e32 v50, 0xbfb8aa3b, v50
	v_exp_f32_e32 v52, v52
	v_exp_f32_e32 v53, v53
	v_exp_f32_e32 v54, v54
	v_exp_f32_e32 v55, v55
	v_exp_f32_e32 v51, v51
	v_exp_f32_e32 v48, v48
	v_exp_f32_e32 v49, v49
	v_exp_f32_e32 v50, v50
	v_add_f32_e32 v52, 1.0, v52
	v_add_f32_e32 v53, 1.0, v53
	v_add_f32_e32 v54, 1.0, v54
	v_add_f32_e32 v55, 1.0, v55
	v_add_f32_e32 v51, 1.0, v51
	v_add_f32_e32 v48, 1.0, v48
	v_add_f32_e32 v49, 1.0, v49
	v_add_f32_e32 v50, 1.0, v50
	v_rcp_f32_e32 v52, v52
	v_rcp_f32_e32 v53, v53
	v_rcp_f32_e32 v54, v54
	v_rcp_f32_e32 v55, v55
	v_rcp_f32_e32 v51, v51
	v_rcp_f32_e32 v48, v48
	v_rcp_f32_e32 v49, v49
	v_rcp_f32_e32 v50, v50
	v_pk_add_f32 v[46:47], v[46:47], v[82:83]
	v_pk_add_f32 v[44:45], v[44:45], v[80:81]
	v_pk_add_f32 v[42:43], v[42:43], v[78:79]
	v_pk_add_f32 v[40:41], v[40:41], v[76:77]
	v_mul_f32_e32 v44, 0xbfb8aa3b, v44
	v_mul_f32_e32 v45, 0xbfb8aa3b, v45
	v_mul_f32_e32 v46, 0xbfb8aa3b, v46
	v_mul_f32_e32 v47, 0xbfb8aa3b, v47
	v_mul_f32_e32 v43, 0xbfb8aa3b, v43
	v_mul_f32_e32 v40, 0xbfb8aa3b, v40
	v_mul_f32_e32 v41, 0xbfb8aa3b, v41
	v_mul_f32_e32 v42, 0xbfb8aa3b, v42
	v_exp_f32_e32 v44, v44
	v_exp_f32_e32 v45, v45
	v_exp_f32_e32 v46, v46
	v_exp_f32_e32 v47, v47
	v_exp_f32_e32 v43, v43
	v_exp_f32_e32 v40, v40
	v_exp_f32_e32 v41, v41
	v_exp_f32_e32 v42, v42
	v_add_f32_e32 v44, 1.0, v44
	v_add_f32_e32 v45, 1.0, v45
	v_add_f32_e32 v46, 1.0, v46
	v_add_f32_e32 v47, 1.0, v47
	v_add_f32_e32 v43, 1.0, v43
	v_add_f32_e32 v40, 1.0, v40
	v_add_f32_e32 v41, 1.0, v41
	v_add_f32_e32 v42, 1.0, v42
	v_rcp_f32_e32 v44, v44
	v_rcp_f32_e32 v45, v45
	v_rcp_f32_e32 v46, v46
	v_rcp_f32_e32 v47, v47
	v_rcp_f32_e32 v43, v43
	v_rcp_f32_e32 v40, v40
	v_rcp_f32_e32 v41, v41
	v_rcp_f32_e32 v42, v42
	v_pk_add_f32 v[38:39], v[38:39], v[58:59]
	v_pk_add_f32 v[36:37], v[36:37], v[56:57]
	v_pk_add_f32 v[34:35], v[34:35], v[62:63]
	v_pk_add_f32 v[32:33], v[32:33], v[60:61]
	v_mul_f32_e32 v36, 0xbfb8aa3b, v36
	v_mul_f32_e32 v37, 0xbfb8aa3b, v37
	s_waitcnt vmcnt(1)
; __device__ __forceinline__ unsigned cvt_pk_bf16(float lo, float hi) { unsigned r; asm volatile("v_cvt_pk_bf16_f32 %0, %1, %2" : "=v"(r) : "v"(lo), "v"(hi)); return r; }
; __device__ __forceinline__ float sigmoidf_(float x) { return __builtin_amdgcn_rcpf(1.0f + __expf(-x)); }
;     __device__ __forceinline__ void operator()(const f32x4 (&acc)[2][2][4][2], const Unit& u, int wr, int wc, int fr, int fq) const {
;     ...
;             for (int m = 0; m < 4; ++m) { const size_t r = (size_t)(row0 + ai * HALF + m * 16);
; #pragma unroll
;                 for (int bj = 0; bj < 2; ++bj) {
;                     const u32x4 yv = *(const u32x4*)(Y + r * ldy + col0 + bj * HALF);
;                     const f32x4 v0 = acc[ai][bj][m][0] + bv[bj][0], v1 = acc[ai][bj][m][1] + bv[bj][1];
;                     float o[8];
;                     const unsigned yy[4] = {yv.x, yv.y, yv.z, yv.w};
; #pragma unroll
;                     for (int j = 0; j < 4; ++j) { const float ylo = __uint_as_float(yy[j] << 16), yhi = __uint_as_float(yy[j] & 0xffff0000u);
;                         const float a0 = (j < 2) ? v0[2 * j] : v1[2 * j - 4], a1 = (j < 2) ? v0[2 * j + 1] : v1[2 * j - 3];
;                         o[2 * j] = ylo * sigmoidf_(a0); o[2 * j + 1] = yhi * sigmoidf_(a1); }
;                     u32x4 w; w.x = cvt_pk_bf16(o[0], o[1]); w.y = cvt_pk_bf16(o[2], o[3]); w.z = cvt_pk_bf16(o[4], o[5]); w.w = cvt_pk_bf16(o[6], o[7]);
;                     *(u32x4*)(O + r * ldc + col0 + bj * HALF) = w; } }
	v_lshlrev_b32_e32 v104, 16, v108
	v_and_b32_e32 v105, 0xffff0000, v108
	v_lshlrev_b32_e32 v106, 16, v109
	v_and_b32_e32 v107, 0xffff0000, v109
	v_lshlrev_b32_e32 v108, 16, v110
	v_and_b32_e32 v109, 0xffff0000, v110
	v_lshlrev_b32_e32 v110, 16, v111
	v_and_b32_e32 v111, 0xffff0000, v111
	v_mul_f32_e32 v100, v100, v104
	v_mul_f32_e32 v101, v101, v105
	v_mul_f32_e32 v102, v102, v106
	v_mul_f32_e32 v103, v103, v107
	v_mul_f32_e32 v99, v99, v111
	v_mul_f32_e32 v104, v96, v108
	v_mul_f32_e32 v105, v97, v109
	v_mul_f32_e32 v106, v98, v110
	v_cvt_pk_bf16_f32 v96, v100, v101
	v_cvt_pk_bf16_f32 v97, v102, v103
	v_cvt_pk_bf16_f32 v98, v104, v105
	v_cvt_pk_bf16_f32 v99, v106, v99
	global_load_dwordx4 v[100:103], v[116:117], off nt
	v_mul_f32_e32 v38, 0xbfb8aa3b, v38
	global_store_dwordx4 v[114:115], v[96:99], off offset:256
	v_mul_f32_e32 v39, 0xbfb8aa3b, v39
	v_mul_f32_e32 v35, 0xbfb8aa3b, v35
	v_mul_f32_e32 v32, 0xbfb8aa3b, v32
	v_mul_f32_e32 v33, 0xbfb8aa3b, v33
	v_mul_f32_e32 v34, 0xbfb8aa3b, v34
	v_exp_f32_e32 v36, v36
	v_exp_f32_e32 v37, v37
	v_exp_f32_e32 v38, v38
	v_exp_f32_e32 v39, v39
	v_exp_f32_e32 v35, v35
	v_exp_f32_e32 v32, v32
	v_exp_f32_e32 v33, v33
	v_exp_f32_e32 v34, v34
	v_add_f32_e32 v36, 1.0, v36
	v_add_f32_e32 v37, 1.0, v37
	v_add_f32_e32 v38, 1.0, v38
	v_add_f32_e32 v39, 1.0, v39
	v_add_f32_e32 v35, 1.0, v35
	v_add_f32_e32 v32, 1.0, v32
	v_add_f32_e32 v33, 1.0, v33
	v_add_f32_e32 v34, 1.0, v34
	v_rcp_f32_e32 v36, v36
	v_rcp_f32_e32 v37, v37
	v_rcp_f32_e32 v38, v38
	v_rcp_f32_e32 v39, v39
	v_rcp_f32_e32 v35, v35
	v_rcp_f32_e32 v32, v32
	v_rcp_f32_e32 v33, v33
	v_rcp_f32_e32 v34, v34
	v_pk_add_f32 v[30:31], v[30:31], v[82:83]
	v_pk_add_f32 v[28:29], v[28:29], v[80:81]
	v_pk_add_f32 v[26:27], v[26:27], v[78:79]
	v_pk_add_f32 v[24:25], v[24:25], v[76:77]
	v_mul_f32_e32 v28, 0xbfb8aa3b, v28
	v_mul_f32_e32 v29, 0xbfb8aa3b, v29
	v_mul_f32_e32 v30, 0xbfb8aa3b, v30
	v_mul_f32_e32 v31, 0xbfb8aa3b, v31
	v_mul_f32_e32 v27, 0xbfb8aa3b, v27
	v_mul_f32_e32 v24, 0xbfb8aa3b, v24
	v_mul_f32_e32 v25, 0xbfb8aa3b, v25
	v_mul_f32_e32 v26, 0xbfb8aa3b, v26
	v_exp_f32_e32 v28, v28
	v_exp_f32_e32 v29, v29
	v_exp_f32_e32 v30, v30
	v_exp_f32_e32 v31, v31
	v_exp_f32_e32 v27, v27
	v_exp_f32_e32 v24, v24
	v_exp_f32_e32 v25, v25
	v_exp_f32_e32 v26, v26
	v_add_f32_e32 v28, 1.0, v28
	v_add_f32_e32 v29, 1.0, v29
	v_add_f32_e32 v30, 1.0, v30
	v_add_f32_e32 v31, 1.0, v31
	v_add_f32_e32 v27, 1.0, v27
	v_add_f32_e32 v24, 1.0, v24
	v_add_f32_e32 v25, 1.0, v25
	v_add_f32_e32 v26, 1.0, v26
	v_rcp_f32_e32 v28, v28
	v_rcp_f32_e32 v29, v29
	v_rcp_f32_e32 v30, v30
	v_rcp_f32_e32 v31, v31
	v_rcp_f32_e32 v27, v27
	v_rcp_f32_e32 v24, v24
	v_rcp_f32_e32 v25, v25
	v_rcp_f32_e32 v26, v26
	v_pk_add_f32 v[22:23], v[22:23], v[58:59]
	v_pk_add_f32 v[20:21], v[20:21], v[56:57]
	v_pk_add_f32 v[18:19], v[18:19], v[62:63]
	v_pk_add_f32 v[16:17], v[16:17], v[60:61]
	v_mul_f32_e32 v20, 0xbfb8aa3b, v20
	v_mul_f32_e32 v21, 0xbfb8aa3b, v21
	v_mul_f32_e32 v22, 0xbfb8aa3b, v22
	v_mul_f32_e32 v23, 0xbfb8aa3b, v23
	v_mul_f32_e32 v19, 0xbfb8aa3b, v19
	v_mul_f32_e32 v16, 0xbfb8aa3b, v16
	v_mul_f32_e32 v17, 0xbfb8aa3b, v17
	v_mul_f32_e32 v18, 0xbfb8aa3b, v18
	s_waitcnt vmcnt(1)
	v_lshlrev_b32_e32 v96, 16, v100
	v_and_b32_e32 v97, 0xffff0000, v100
	v_lshlrev_b32_e32 v98, 16, v101
	v_and_b32_e32 v99, 0xffff0000, v101
	v_lshlrev_b32_e32 v100, 16, v102
	v_and_b32_e32 v101, 0xffff0000, v102
	v_lshlrev_b32_e32 v102, 16, v103
	v_and_b32_e32 v103, 0xffff0000, v103
	v_mul_f32_e32 v92, v92, v96
	v_mul_f32_e32 v93, v93, v97
	v_mul_f32_e32 v94, v94, v98
	v_mul_f32_e32 v95, v95, v99
	v_mul_f32_e32 v91, v91, v103
	v_mul_f32_e32 v96, v88, v100
	v_mul_f32_e32 v97, v89, v101
	v_mul_f32_e32 v98, v90, v102
	v_cvt_pk_bf16_f32 v88, v92, v93
	v_cvt_pk_bf16_f32 v89, v94, v95
	v_cvt_pk_bf16_f32 v90, v96, v97
	v_cvt_pk_bf16_f32 v91, v98, v91
	global_load_dwordx4 v[92:95], v[116:117], off offset:256 nt
	v_add_u32_e32 v96, 0x80, v162
	v_lshlrev_b64 v[98:99], 12, v[112:113]
	v_ashrrev_i32_e32 v97, 31, v96
	v_lshl_add_u64 v[98:99], s[10:11], 0, v[98:99]
	v_lshlrev_b64 v[100:101], 11, v[96:97]
	v_lshl_add_u64 v[98:99], v[98:99], 0, v[160:161]
	v_lshl_add_u64 v[100:101], s[6:7], 0, v[100:101]
	global_store_dwordx4 v[98:99], v[88:91], off
	v_lshl_add_u64 v[100:101], v[100:101], 0, v[160:161]
	v_exp_f32_e32 v20, v20
	v_exp_f32_e32 v21, v21
	v_exp_f32_e32 v22, v22
	v_exp_f32_e32 v23, v23
	v_exp_f32_e32 v19, v19
	v_exp_f32_e32 v16, v16
	v_exp_f32_e32 v17, v17
	v_exp_f32_e32 v18, v18
	v_add_f32_e32 v20, 1.0, v20
	v_add_f32_e32 v21, 1.0, v21
	v_add_f32_e32 v22, 1.0, v22
	v_add_f32_e32 v23, 1.0, v23
	v_add_f32_e32 v19, 1.0, v19
	v_add_f32_e32 v16, 1.0, v16
	v_add_f32_e32 v17, 1.0, v17
	v_add_f32_e32 v18, 1.0, v18
	v_rcp_f32_e32 v20, v20
	v_rcp_f32_e32 v21, v21
	v_rcp_f32_e32 v22, v22
	v_rcp_f32_e32 v23, v23
	v_rcp_f32_e32 v19, v19
	v_rcp_f32_e32 v16, v16
	v_rcp_f32_e32 v17, v17
	v_rcp_f32_e32 v18, v18
	v_pk_add_f32 v[14:15], v[14:15], v[82:83]
	v_pk_add_f32 v[12:13], v[12:13], v[80:81]
	v_pk_add_f32 v[10:11], v[10:11], v[78:79]
	v_pk_add_f32 v[8:9], v[8:9], v[76:77]
	v_mul_f32_e32 v12, 0xbfb8aa3b, v12
	v_mul_f32_e32 v13, 0xbfb8aa3b, v13
	v_mul_f32_e32 v14, 0xbfb8aa3b, v14
	v_mul_f32_e32 v15, 0xbfb8aa3b, v15
	v_mul_f32_e32 v11, 0xbfb8aa3b, v11
	v_mul_f32_e32 v8, 0xbfb8aa3b, v8
	v_mul_f32_e32 v9, 0xbfb8aa3b, v9
	v_mul_f32_e32 v10, 0xbfb8aa3b, v10
	v_exp_f32_e32 v12, v12
	v_exp_f32_e32 v13, v13
	v_exp_f32_e32 v14, v14
	v_exp_f32_e32 v15, v15
	v_exp_f32_e32 v11, v11
	v_exp_f32_e32 v8, v8
	v_exp_f32_e32 v9, v9
	v_exp_f32_e32 v10, v10
	v_add_f32_e32 v12, 1.0, v12
	v_add_f32_e32 v13, 1.0, v13
	v_add_f32_e32 v14, 1.0, v14
	v_add_f32_e32 v15, 1.0, v15
	v_add_f32_e32 v11, 1.0, v11
	v_add_f32_e32 v8, 1.0, v8
	v_add_f32_e32 v9, 1.0, v9
	v_add_f32_e32 v10, 1.0, v10
	v_rcp_f32_e32 v12, v12
	v_rcp_f32_e32 v13, v13
	v_rcp_f32_e32 v14, v14
	v_rcp_f32_e32 v15, v15
	v_rcp_f32_e32 v11, v11
	v_rcp_f32_e32 v8, v8
	v_rcp_f32_e32 v9, v9
	v_rcp_f32_e32 v10, v10
	v_pk_add_f32 v[2:3], v[2:3], v[62:63]
	v_pk_add_f32 v[0:1], v[0:1], v[60:61]
	v_pk_add_f32 v[6:7], v[6:7], v[58:59]
	v_pk_add_f32 v[4:5], v[4:5], v[56:57]
	v_mul_f32_e32 v1, 0xbfb8aa3b, v1
	v_mul_f32_e32 v0, 0xbfb8aa3b, v0
	v_mul_f32_e32 v7, 0xbfb8aa3b, v7
	v_mul_f32_e32 v5, 0xbfb8aa3b, v5
	v_mul_f32_e32 v3, 0xbfb8aa3b, v3
	v_mul_f32_e32 v6, 0xbfb8aa3b, v6
	s_waitcnt vmcnt(1)
; __device__ __forceinline__ unsigned cvt_pk_bf16(float lo, float hi) { unsigned r; asm volatile("v_cvt_pk_bf16_f32 %0, %1, %2" : "=v"(r) : "v"(lo), "v"(hi)); return r; }
; __device__ __forceinline__ float sigmoidf_(float x) { return __builtin_amdgcn_rcpf(1.0f + __expf(-x)); }
;     __device__ __forceinline__ void operator()(const f32x4 (&acc)[2][2][4][2], const Unit& u, int wr, int wc, int fr, int fq) const {
;     ...
;             for (int m = 0; m < 4; ++m) { const size_t r = (size_t)(row0 + ai * HALF + m * 16);
; #pragma unroll
;                 for (int bj = 0; bj < 2; ++bj) {
;                     const u32x4 yv = *(const u32x4*)(Y + r * ldy + col0 + bj * HALF);
;                     const f32x4 v0 = acc[ai][bj][m][0] + bv[bj][0], v1 = acc[ai][bj][m][1] + bv[bj][1];
;                     float o[8];
;                     const unsigned yy[4] = {yv.x, yv.y, yv.z, yv.w};
; #pragma unroll
;                     for (int j = 0; j < 4; ++j) { const float ylo = __uint_as_float(yy[j] << 16), yhi = __uint_as_float(yy[j] & 0xffff0000u);
;                         const float a0 = (j < 2) ? v0[2 * j] : v1[2 * j - 4], a1 = (j < 2) ? v0[2 * j + 1] : v1[2 * j - 3];
;                         o[2 * j] = ylo * sigmoidf_(a0); o[2 * j + 1] = yhi * sigmoidf_(a1); }
;                     u32x4 w; w.x = cvt_pk_bf16(o[0], o[1]); w.y = cvt_pk_bf16(o[2], o[3]); w.z = cvt_pk_bf16(o[4], o[5]); w.w = cvt_pk_bf16(o[6], o[7]);
;                     *(u32x4*)(O + r * ldc + col0 + bj * HALF) = w; } }
	v_lshlrev_b32_e32 v88, 16, v92
	v_and_b32_e32 v89, 0xffff0000, v92
	v_lshlrev_b32_e32 v90, 16, v93
	v_and_b32_e32 v91, 0xffff0000, v93
	v_lshlrev_b32_e32 v92, 16, v94
	v_and_b32_e32 v93, 0xffff0000, v94
	v_lshlrev_b32_e32 v94, 16, v95
	v_and_b32_e32 v95, 0xffff0000, v95
	v_mul_f32_e32 v84, v84, v88
	v_mul_f32_e32 v85, v85, v89
	v_mul_f32_e32 v86, v86, v90
	v_mul_f32_e32 v87, v87, v91
	v_mul_f32_e32 v75, v75, v95
	v_mul_f32_e32 v88, v72, v92
	v_mul_f32_e32 v89, v73, v93
	v_mul_f32_e32 v90, v74, v94
	v_cvt_pk_bf16_f32 v72, v84, v85
	v_cvt_pk_bf16_f32 v73, v86, v87
	v_cvt_pk_bf16_f32 v74, v88, v89
	v_cvt_pk_bf16_f32 v75, v90, v75
	global_load_dwordx4 v[84:87], v[100:101], off nt
	v_mul_f32_e32 v4, 0xbfb8aa3b, v4
	global_store_dwordx4 v[98:99], v[72:75], off offset:256
	v_mul_f32_e32 v2, 0xbfb8aa3b, v2
	v_exp_f32_e32 v1, v1
	v_exp_f32_e32 v0, v0
	v_exp_f32_e32 v7, v7
	v_exp_f32_e32 v5, v5
	v_exp_f32_e32 v3, v3
	v_exp_f32_e32 v6, v6
	v_exp_f32_e32 v4, v4
	v_exp_f32_e32 v2, v2
	v_add_f32_e32 v1, 1.0, v1
	v_add_f32_e32 v0, 1.0, v0
	v_add_f32_e32 v7, 1.0, v7
	v_add_f32_e32 v5, 1.0, v5
	v_add_f32_e32 v3, 1.0, v3
	v_add_f32_e32 v6, 1.0, v6
	v_add_f32_e32 v4, 1.0, v4
	v_add_f32_e32 v2, 1.0, v2
	v_rcp_f32_e32 v1, v1
	v_rcp_f32_e32 v0, v0
	v_rcp_f32_e32 v7, v7
	v_rcp_f32_e32 v5, v5
	v_rcp_f32_e32 v3, v3
	v_rcp_f32_e32 v6, v6
	v_rcp_f32_e32 v4, v4
	v_rcp_f32_e32 v2, v2
	s_waitcnt vmcnt(1)
	v_lshlrev_b32_e32 v72, 16, v84
	v_and_b32_e32 v73, 0xffff0000, v84
	v_lshlrev_b32_e32 v74, 16, v85
	v_and_b32_e32 v75, 0xffff0000, v85
	v_lshlrev_b32_e32 v84, 16, v86
	v_and_b32_e32 v85, 0xffff0000, v86
	v_lshlrev_b32_e32 v86, 16, v87
	v_and_b32_e32 v87, 0xffff0000, v87
	v_mul_f32_e32 v68, v68, v72
	v_mul_f32_e32 v69, v69, v73
	v_mul_f32_e32 v70, v70, v74
	v_mul_f32_e32 v71, v71, v75
	v_mul_f32_e32 v67, v67, v87
	v_mul_f32_e32 v72, v64, v84
	v_mul_f32_e32 v73, v65, v85
	v_mul_f32_e32 v74, v66, v86
	v_cvt_pk_bf16_f32 v64, v68, v69
	v_cvt_pk_bf16_f32 v65, v70, v71
	v_cvt_pk_bf16_f32 v66, v72, v73
	v_cvt_pk_bf16_f32 v67, v74, v67
	global_load_dwordx4 v[68:71], v[100:101], off offset:256 nt
	v_add_u32_e32 v72, 0x90, v162
	v_lshlrev_b64 v[74:75], 12, v[96:97]
	v_ashrrev_i32_e32 v73, 31, v72
	v_lshl_add_u64 v[74:75], s[10:11], 0, v[74:75]
	v_lshlrev_b64 v[84:85], 11, v[72:73]
	v_lshl_add_u64 v[74:75], v[74:75], 0, v[160:161]
	v_lshl_add_u64 v[84:85], s[6:7], 0, v[84:85]
	global_store_dwordx4 v[74:75], v[64:67], off
	v_lshl_add_u64 v[84:85], v[84:85], 0, v[160:161]
	s_waitcnt vmcnt(1)
	v_lshlrev_b32_e32 v64, 16, v68
	v_and_b32_e32 v65, 0xffff0000, v68
	v_lshlrev_b32_e32 v66, 16, v69
	v_and_b32_e32 v67, 0xffff0000, v69
	v_lshlrev_b32_e32 v68, 16, v70
	v_and_b32_e32 v69, 0xffff0000, v70
	v_lshlrev_b32_e32 v70, 16, v71
	v_and_b32_e32 v71, 0xffff0000, v71
	v_mul_f32_e32 v52, v52, v64
	v_mul_f32_e32 v53, v53, v65
	v_mul_f32_e32 v54, v54, v66
	v_mul_f32_e32 v55, v55, v67
	v_mul_f32_e32 v51, v51, v71
	v_mul_f32_e32 v64, v48, v68
	v_mul_f32_e32 v65, v49, v69
	v_mul_f32_e32 v66, v50, v70
	v_cvt_pk_bf16_f32 v48, v52, v53
	v_cvt_pk_bf16_f32 v49, v54, v55
	v_cvt_pk_bf16_f32 v50, v64, v65
	v_cvt_pk_bf16_f32 v51, v66, v51
	global_load_dwordx4 v[52:55], v[84:85], off nt
	s_nop 0
	global_store_dwordx4 v[74:75], v[48:51], off offset:256
	s_waitcnt vmcnt(1)
	s_nop 0
	v_lshlrev_b32_e32 v48, 16, v52
	v_and_b32_e32 v49, 0xffff0000, v52
	v_lshlrev_b32_e32 v50, 16, v53
	v_and_b32_e32 v51, 0xffff0000, v53
	v_lshlrev_b32_e32 v52, 16, v54
	v_and_b32_e32 v53, 0xffff0000, v54
	v_lshlrev_b32_e32 v54, 16, v55
	v_and_b32_e32 v55, 0xffff0000, v55
	v_mul_f32_e32 v44, v44, v48
	v_mul_f32_e32 v45, v45, v49
	v_mul_f32_e32 v46, v46, v50
	v_mul_f32_e32 v47, v47, v51
	v_mul_f32_e32 v43, v43, v55
	v_mul_f32_e32 v48, v40, v52
	v_mul_f32_e32 v49, v41, v53
	v_mul_f32_e32 v50, v42, v54
	v_cvt_pk_bf16_f32 v40, v44, v45
	v_cvt_pk_bf16_f32 v41, v46, v47
	v_cvt_pk_bf16_f32 v42, v48, v49
	v_cvt_pk_bf16_f32 v43, v50, v43
	global_load_dwordx4 v[44:47], v[84:85], off offset:256 nt
	v_add_u32_e32 v48, 0xa0, v162
	v_lshlrev_b64 v[50:51], 12, v[72:73]
	v_ashrrev_i32_e32 v49, 31, v48
	v_lshl_add_u64 v[50:51], s[10:11], 0, v[50:51]
	v_lshlrev_b64 v[52:53], 11, v[48:49]
	v_lshl_add_u64 v[50:51], v[50:51], 0, v[160:161]
	v_lshl_add_u64 v[52:53], s[6:7], 0, v[52:53]
	global_store_dwordx4 v[50:51], v[40:43], off
	v_lshl_add_u64 v[52:53], v[52:53], 0, v[160:161]
	s_waitcnt vmcnt(1)
; __device__ __forceinline__ unsigned cvt_pk_bf16(float lo, float hi) { unsigned r; asm volatile("v_cvt_pk_bf16_f32 %0, %1, %2" : "=v"(r) : "v"(lo), "v"(hi)); return r; }
; __device__ __forceinline__ float sigmoidf_(float x) { return __builtin_amdgcn_rcpf(1.0f + __expf(-x)); }
; #define PG8_BAR __builtin_amdgcn_s_barrier()
;     __device__ __forceinline__ void operator()(const f32x4 (&acc)[2][2][4][2], const Unit& u, int wr, int wc, int fr, int fq) const {
;     ...
;             for (int m = 0; m < 4; ++m) { const size_t r = (size_t)(row0 + ai * HALF + m * 16);
; #pragma unroll
;                 for (int bj = 0; bj < 2; ++bj) {
;                     const u32x4 yv = *(const u32x4*)(Y + r * ldy + col0 + bj * HALF);
;                     const f32x4 v0 = acc[ai][bj][m][0] + bv[bj][0], v1 = acc[ai][bj][m][1] + bv[bj][1];
;                     float o[8];
;                     const unsigned yy[4] = {yv.x, yv.y, yv.z, yv.w};
; #pragma unroll
;                     for (int j = 0; j < 4; ++j) { const float ylo = __uint_as_float(yy[j] << 16), yhi = __uint_as_float(yy[j] & 0xffff0000u);
;                         const float a0 = (j < 2) ? v0[2 * j] : v1[2 * j - 4], a1 = (j < 2) ? v0[2 * j + 1] : v1[2 * j - 3];
;                         o[2 * j] = ylo * sigmoidf_(a0); o[2 * j + 1] = yhi * sigmoidf_(a1); }
;                     u32x4 w; w.x = cvt_pk_bf16(o[0], o[1]); w.y = cvt_pk_bf16(o[2], o[3]); w.z = cvt_pk_bf16(o[4], o[5]); w.w = cvt_pk_bf16(o[6], o[7]);
;                     *(u32x4*)(O + r * ldc + col0 + bj * HALF) = w; } }
;     }
; template <class Epi>
; __device__ __forceinline__ void gemm_phase(LAS unsigned char* lds, const Gemm g, const StaticOrder& S, const Epi& E) {
;     ...
;         if (wr == 0) PG8_BAR;
;         E(acc, cur, wr, wc, fr, fq);
;         if (!has_next) break;
; #pragma unroll
;         for (int a = 0; a < 2; ++a)
; #pragma unroll
;             for (int b = 0; b < 2; ++b)
; #pragma unroll
;                 for (int m = 0; m < 4; ++m)
; #pragma unroll
;                     for (int n = 0; n < 2; ++n) acc[a][b][m][n] = (f32x4){0.f, 0.f, 0.f, 0.f};
;         cur = nxt; cA = nA; cB = nB; ++ui;
;         if (wr == 1) PG8_BAR;
	v_lshlrev_b32_e32 v40, 16, v44
	v_and_b32_e32 v41, 0xffff0000, v44
	v_lshlrev_b32_e32 v42, 16, v45
	v_and_b32_e32 v43, 0xffff0000, v45
	v_lshlrev_b32_e32 v44, 16, v46
	v_and_b32_e32 v45, 0xffff0000, v46
	v_lshlrev_b32_e32 v46, 16, v47
	v_and_b32_e32 v47, 0xffff0000, v47
	v_mul_f32_e32 v36, v36, v40
	v_mul_f32_e32 v37, v37, v41
	v_mul_f32_e32 v38, v38, v42
	v_mul_f32_e32 v39, v39, v43
	v_mul_f32_e32 v35, v35, v47
	v_mul_f32_e32 v40, v32, v44
	v_mul_f32_e32 v41, v33, v45
	v_mul_f32_e32 v42, v34, v46
	v_cvt_pk_bf16_f32 v32, v36, v37
	v_cvt_pk_bf16_f32 v33, v38, v39
	v_cvt_pk_bf16_f32 v34, v40, v41
	v_cvt_pk_bf16_f32 v35, v42, v35
	global_load_dwordx4 v[36:39], v[52:53], off nt
	s_nop 0
	global_store_dwordx4 v[50:51], v[32:35], off offset:256
	s_waitcnt vmcnt(1)
	s_nop 0
	v_lshlrev_b32_e32 v32, 16, v36
	v_and_b32_e32 v33, 0xffff0000, v36
	v_lshlrev_b32_e32 v34, 16, v37
	v_and_b32_e32 v35, 0xffff0000, v37
	v_lshlrev_b32_e32 v36, 16, v38
	v_and_b32_e32 v37, 0xffff0000, v38
	v_lshlrev_b32_e32 v38, 16, v39
	v_and_b32_e32 v39, 0xffff0000, v39
	v_mul_f32_e32 v28, v28, v32
	v_mul_f32_e32 v29, v29, v33
	v_mul_f32_e32 v30, v30, v34
	v_mul_f32_e32 v31, v31, v35
	v_mul_f32_e32 v27, v27, v39
	v_mul_f32_e32 v32, v24, v36
	v_mul_f32_e32 v33, v25, v37
	v_mul_f32_e32 v34, v26, v38
	v_cvt_pk_bf16_f32 v24, v28, v29
	v_cvt_pk_bf16_f32 v25, v30, v31
	v_cvt_pk_bf16_f32 v26, v32, v33
	v_cvt_pk_bf16_f32 v27, v34, v27
	global_load_dwordx4 v[28:31], v[52:53], off offset:256 nt
	v_add_u32_e32 v32, 0xb0, v162
	v_lshlrev_b64 v[34:35], 12, v[48:49]
	v_ashrrev_i32_e32 v33, 31, v32
	v_lshl_add_u64 v[34:35], s[10:11], 0, v[34:35]
	v_lshlrev_b64 v[36:37], 11, v[32:33]
	v_lshl_add_u64 v[34:35], v[34:35], 0, v[160:161]
	v_lshl_add_u64 v[36:37], s[6:7], 0, v[36:37]
	global_store_dwordx4 v[34:35], v[24:27], off
	v_lshl_add_u64 v[36:37], v[36:37], 0, v[160:161]
	s_waitcnt vmcnt(1)
	v_lshlrev_b32_e32 v24, 16, v28
	v_and_b32_e32 v25, 0xffff0000, v28
	v_lshlrev_b32_e32 v26, 16, v29
	v_and_b32_e32 v27, 0xffff0000, v29
	v_lshlrev_b32_e32 v28, 16, v30
	v_and_b32_e32 v29, 0xffff0000, v30
	v_lshlrev_b32_e32 v30, 16, v31
	v_and_b32_e32 v31, 0xffff0000, v31
	v_mul_f32_e32 v20, v20, v24
	v_mul_f32_e32 v21, v21, v25
	v_mul_f32_e32 v22, v22, v26
	v_mul_f32_e32 v23, v23, v27
	v_mul_f32_e32 v19, v19, v31
	v_mul_f32_e32 v24, v16, v28
	v_mul_f32_e32 v25, v17, v29
	v_mul_f32_e32 v26, v18, v30
	v_cvt_pk_bf16_f32 v16, v20, v21
	v_cvt_pk_bf16_f32 v17, v22, v23
	v_cvt_pk_bf16_f32 v18, v24, v25
	v_cvt_pk_bf16_f32 v19, v26, v19
	global_load_dwordx4 v[20:23], v[36:37], off nt
	s_nop 0
	global_store_dwordx4 v[34:35], v[16:19], off offset:256
	s_waitcnt vmcnt(1)
	s_nop 0
	v_lshlrev_b32_e32 v16, 16, v20
	v_and_b32_e32 v17, 0xffff0000, v20
	v_lshlrev_b32_e32 v18, 16, v21
	v_and_b32_e32 v19, 0xffff0000, v21
	v_lshlrev_b32_e32 v20, 16, v22
	v_and_b32_e32 v21, 0xffff0000, v22
	v_lshlrev_b32_e32 v22, 16, v23
	v_and_b32_e32 v23, 0xffff0000, v23
	v_mul_f32_e32 v12, v12, v16
	v_mul_f32_e32 v13, v13, v17
	v_mul_f32_e32 v14, v14, v18
	v_mul_f32_e32 v15, v15, v19
	v_mul_f32_e32 v11, v11, v23
	v_mul_f32_e32 v16, v8, v20
	v_mul_f32_e32 v17, v9, v21
	v_mul_f32_e32 v18, v10, v22
	v_cvt_pk_bf16_f32 v8, v12, v13
	v_cvt_pk_bf16_f32 v9, v14, v15
	v_cvt_pk_bf16_f32 v10, v16, v17
	v_cvt_pk_bf16_f32 v11, v18, v11
	global_load_dwordx4 v[12:15], v[36:37], off offset:256 nt
	v_lshlrev_b64 v[16:17], 12, v[32:33]
	v_lshl_add_u64 v[16:17], s[10:11], 0, v[16:17]
	v_lshl_add_u64 v[16:17], v[16:17], 0, v[160:161]
	global_store_dwordx4 v[16:17], v[8:11], off
	s_waitcnt vmcnt(1)
	s_nop 0
	v_and_b32_e32 v8, 0xffff0000, v15
	v_lshlrev_b32_e32 v9, 16, v15
	v_and_b32_e32 v10, 0xffff0000, v14
	v_lshlrev_b32_e32 v11, 16, v14
	v_and_b32_e32 v14, 0xffff0000, v13
	v_and_b32_e32 v15, 0xffff0000, v12
	v_lshlrev_b32_e32 v13, 16, v13
	v_lshlrev_b32_e32 v12, 16, v12
	v_mul_f32_e32 v10, v1, v10
	v_mul_f32_e32 v11, v0, v11
	v_mul_f32_e32 v1, v7, v14
	v_mul_f32_e32 v0, v5, v15
	v_mul_f32_e32 v3, v3, v8
	v_mul_f32_e32 v6, v6, v13
	v_mul_f32_e32 v4, v4, v12
	v_mul_f32_e32 v5, v2, v9
	v_cvt_pk_bf16_f32 v0, v4, v0
	v_cvt_pk_bf16_f32 v1, v6, v1
	v_cvt_pk_bf16_f32 v2, v11, v10
	v_cvt_pk_bf16_f32 v3, v5, v3
	global_store_dwordx4 v[16:17], v[0:3], off offset:256
	s_cbranch_vccnz .LBB0_1107
	s_andn2_b64 vcc, exec, s[8:9]
	s_cbranch_vccnz .LBB0_1106
	s_barrier
	s_branch .LBB0_1106

; __device__ __forceinline__ void gdn_finalize(const Ctx& F) {
;     ...
;     const int gw = F.bid * 8 + F.wave, NGW = F.G * 8, lane = F.lane, d0 = (lane & 7) * 16;
;     float nw[16];
; #pragma unroll
;     for (int i = 0; i < 16; ++i) nw[i] = P.in[22][d0 + i];
;     for (int row = gw; row < SEQ; row += NGW) {
;         float o[16]; const u32x4* op = (const u32x4*)(O + ((size_t)lane * SEQ + row) * 16);
;         float ss = 0.f;
;         { const u32x4 a = op[0], b = op[1]; const unsigned ww[8] = {a.x, a.y, a.z, a.w, b.x, b.y, b.z, b.w};
; #pragma unroll
;           for (int i = 0; i < 8; ++i) { o[2 * i] = __uint_as_float(ww[i] << 16); o[2 * i + 1] = __uint_as_float(ww[i] & 0xffff0000u); ss += o[2 * i] * o[2 * i] + o[2 * i + 1] * o[2 * i + 1]; } }
;         ss += __shfl_xor(ss, 1); ss += __shfl_xor(ss, 2); ss += __shfl_xor(ss, 4);
.LBB0_1122:
	s_lshl_b32 s0, s76, 3
	s_add_i32 s0, s0, s94
	s_cmpk_gt_i32 s0, 0x3fff
	s_cbranch_scc1 .LBB0_1125
	s_waitcnt vmcnt(0)
	v_lshlrev_b32_e32 v0, 6, v242
	v_readlane_b32 s8, v247, 12
	v_and_b32_e32 v12, 0x1c0, v0
	v_readlane_b32 s20, v247, 24
	v_readlane_b32 s21, v247, 25
	s_waitcnt lgkmcnt(0)
	s_nop 3
	global_load_dwordx4 v[0:3], v12, s[20:21] offset:32 nt
	global_load_dwordx4 v[4:7], v12, s[20:21] offset:48 nt
	global_load_dwordx4 v[8:11], v12, s[20:21] nt
	s_nop 0
	global_load_dwordx4 v[12:15], v12, s[20:21] offset:16 nt
	v_mbcnt_lo_u32_b32 v16, -1, 0
	v_mbcnt_hi_u32_b32 v22, -1, v16
	v_and_b32_e32 v24, 64, v22
	v_xor_b32_e32 v23, 1, v22
	v_add_u32_e32 v24, 64, v24
	v_xor_b32_e32 v25, 2, v22
	v_cmp_lt_i32_e32 vcc, v23, v24
	v_xor_b32_e32 v27, 4, v22
	v_readlane_b32 s12, v247, 16
	v_cndmask_b32_e32 v23, v22, v23, vcc
	v_cmp_lt_i32_e32 vcc, v25, v24
	v_readlane_b32 s13, v247, 17
	v_readlane_b32 s16, v247, 20
	v_readlane_b32 s17, v247, 21
	s_lshl_b32 s6, s33, 3
	s_ashr_i32 s1, s0, 31
	v_cndmask_b32_e32 v25, v22, v25, vcc
	v_cmp_lt_i32_e32 vcc, v27, v24
	v_readlane_b32 s9, v247, 13
	v_readlane_b32 s10, v247, 14
	v_readlane_b32 s11, v247, 15
	v_readlane_b32 s14, v247, 18
	v_readlane_b32 s15, v247, 19
	v_readlane_b32 s18, v247, 22
	v_readlane_b32 s19, v247, 23
	v_lshlrev_b32_e32 v20, 19, v242
	v_mov_b32_e32 v21, 0
	v_lshlrev_b32_e32 v18, 5, v242
	s_lshl_b64 s[12:13], s[0:1], 12
	s_ashr_i32 s7, s6, 31
	s_lshl_b64 s[16:17], s[0:1], 13
	s_lshl_b64 s[20:21], s[0:1], 5
	v_cndmask_b32_e32 v22, v22, v27, vcc
	s_mov_b64 s[8:9], 0xac00000
	s_mov_b64 s[10:11], 0x16c01800
	s_mov_b32 s3, 0x16c01000
	s_mov_b32 s18, 0xffff0000
	v_mov_b32_e32 v26, 0x358637bd
	s_mov_b32 s19, 0x800000
	v_or_b32_e32 v16, s12, v18
	v_mov_b32_e32 v17, s13
	s_lshl_b64 s[12:13], s[6:7], 12
	s_lshl_b64 s[14:15], s[6:7], 13
	v_or_b32_e32 v18, s16, v18
	v_mov_b32_e32 v19, s17
	v_lshl_add_u64 v[20:21], v[20:21], 0, s[20:21]
	s_lshl_b64 s[16:17], s[6:7], 5
	v_lshlrev_b32_e32 v27, 2, v23
	v_lshlrev_b32_e32 v28, 2, v25
	v_lshlrev_b32_e32 v29, 2, v22
	s_movk_i32 s1, 0x7fff
	v_readlane_b32 s22, v247, 26
	v_readlane_b32 s23, v247, 27
	s_waitcnt vmcnt(3)
	v_mov_b32_e32 v22, v1
	v_mov_b32_e32 v23, v3
	v_mov_b32_e32 v1, v2
	s_waitcnt vmcnt(2)
	v_mov_b32_e32 v2, v5
	v_mov_b32_e32 v3, v7
	v_mov_b32_e32 v5, v6
	s_waitcnt vmcnt(1)
	v_mov_b32_e32 v6, v9
	v_mov_b32_e32 v7, v11
	v_mov_b32_e32 v9, v10
	s_waitcnt vmcnt(0)
	v_mov_b32_e32 v10, v13
	v_mov_b32_e32 v11, v15
	v_mov_b32_e32 v13, v14
.LBB0_1124:
	v_lshl_add_u64 v[14:15], s[92:93], 0, v[20:21]
	v_lshl_add_u64 v[30:31], v[14:15], 0, s[8:9]
	v_add_co_u32_e32 v14, vcc, 0xac00000, v14
	v_lshl_add_u64 v[24:25], s[92:93], 0, v[18:19]
	s_nop 0
	v_addc_co_u32_e32 v15, vcc, 0, v15, vcc
	v_lshl_add_u64 v[38:39], v[24:25], 0, s[10:11]
	v_add_co_u32_e32 v24, vcc, s3, v24
	global_load_dwordx4 v[30:33], v[30:31], off offset:16 nt
	s_nop 0
	global_load_dwordx4 v[34:37], v[14:15], off nt
	v_addc_co_u32_e32 v25, vcc, 0, v25, vcc
	global_load_dwordx4 v[38:41], v[38:39], off offset:16 nt
	s_nop 0
	global_load_dwordx4 v[42:45], v[24:25], off offset:2048 nt
	v_lshl_add_u64 v[46:47], s[92:93], 0, v[16:17]
	v_add_co_u32_e32 v14, vcc, 0x12c00000, v46
	s_add_i32 s0, s0, s6
	s_nop 0
	v_addc_co_u32_e32 v15, vcc, 0, v47, vcc
	v_lshl_add_u64 v[16:17], v[16:17], 0, s[12:13]
	v_lshl_add_u64 v[18:19], v[18:19], 0, s[14:15]
	v_lshl_add_u64 v[20:21], v[20:21], 0, s[16:17]
	s_cmpk_lt_i32 s0, 0x4000
	s_waitcnt vmcnt(3)
	v_lshlrev_b32_e32 v25, 16, v31
	s_waitcnt vmcnt(2)
	v_lshlrev_b32_e32 v49, 16, v35
	v_lshlrev_b32_e32 v48, 16, v34
	v_and_b32_e32 v35, 0xffff0000, v35
	v_and_b32_e32 v34, 0xffff0000, v34
	v_lshlrev_b32_e32 v51, 16, v37
	v_lshlrev_b32_e32 v50, 16, v36
	v_and_b32_e32 v37, 0xffff0000, v37
	v_and_b32_e32 v36, 0xffff0000, v36
	s_waitcnt vmcnt(1)
	v_lshlrev_b32_e32 v55, 16, v39
	v_lshlrev_b32_e32 v54, 16, v38
	v_and_b32_e32 v39, 0xffff0000, v39
	v_pk_mul_f32 v[58:59], v[34:35], v[34:35]
	s_waitcnt vmcnt(0)
; __device__ __forceinline__ unsigned pk2(float lo, float hi) { return f2bf(lo) | (f2bf(hi) << 16); }
; __device__ __forceinline__ float siluf_(float x) { return x * __builtin_amdgcn_rcpf(1.0f + __expf(-x)); }
; __device__ __forceinline__ void gdn_finalize(const Ctx& F) {
;     ...
;           for (int i = 0; i < 8; ++i) { o[2 * i] = __uint_as_float(ww[i] << 16); o[2 * i + 1] = __uint_as_float(ww[i] & 0xffff0000u); ss += o[2 * i] * o[2 * i] + o[2 * i + 1] * o[2 * i + 1]; } }
;         ss += __shfl_xor(ss, 1); ss += __shfl_xor(ss, 2); ss += __shfl_xor(ss, 4);
;         const float rstd = rsqrtf(ss * (1.0f / 128.0f) + EPS);
;         const u32x4* zp = (const u32x4*)(Y0 + (size_t)row * 4096 + 3072 + lane * 16); unsigned zz[8];
;         { const u32x4 a = zp[0], b = zp[1]; zz[0] = a.x; zz[1] = a.y; zz[2] = a.z; zz[3] = a.w; zz[4] = b.x; zz[5] = b.y; zz[6] = b.z; zz[7] = b.w; }
;         unsigned ov[8];
; #pragma unroll
;         for (int i = 0; i < 8; ++i) { const float z0 = __uint_as_float(zz[i] << 16), z1 = __uint_as_float(zz[i] & 0xffff0000u);
;             ov[i] = pk2(o[2 * i] * rstd * nw[2 * i] * siluf_(z0), o[2 * i + 1] * rstd * nw[2 * i + 1] * siluf_(z1)); }
;         u32x4* cp = (u32x4*)(CAT + (size_t)row * 2048 + 1024 + lane * 16);
;         cp[0] = (u32x4){ov[0], ov[1], ov[2], ov[3]}; cp[1] = (u32x4){ov[4], ov[5], ov[6], ov[7]};
	v_lshlrev_b32_e32 v61, 16, v43
	v_lshlrev_b32_e32 v64, 16, v44
	v_and_b32_e32 v44, 0xffff0000, v44
	v_and_b32_e32 v38, 0xffff0000, v38
	v_lshlrev_b32_e32 v60, 16, v42
	v_and_b32_e32 v43, 0xffff0000, v43
	v_pk_mul_f32 v[62:63], v[36:37], v[36:37]
	v_lshlrev_b32_e32 v65, 16, v45
	v_lshlrev_b32_e32 v66, 16, v40
	v_mul_f32_e32 v68, 0xbfb8aa3b, v54
	v_mul_f32_e32 v71, 0xbfb8aa3b, v39
	v_pk_fma_f32 v[58:59], v[48:49], v[48:49], v[58:59]
	v_mul_f32_e32 v74, 0xbfb8aa3b, v61
	v_mul_f32_e32 v77, 0xbfb8aa3b, v44
	v_lshlrev_b32_e32 v24, 16, v30
	v_and_b32_e32 v31, 0xffff0000, v31
	v_and_b32_e32 v30, 0xffff0000, v30
	v_and_b32_e32 v42, 0xffff0000, v42
	v_and_b32_e32 v45, 0xffff0000, v45
	v_and_b32_e32 v40, 0xffff0000, v40
	v_mul_f32_e32 v69, 0xbfb8aa3b, v38
	v_mul_f32_e32 v72, 0xbfb8aa3b, v60
	v_mul_f32_e32 v75, 0xbfb8aa3b, v43
	v_pk_fma_f32 v[62:63], v[50:51], v[50:51], v[62:63]
	v_mul_f32_e32 v78, 0xbfb8aa3b, v65
	v_mul_f32_e32 v80, 0xbfb8aa3b, v66
	v_exp_f32_e32 v68, v68
	v_exp_f32_e32 v71, v71
	v_exp_f32_e32 v74, v74
	v_exp_f32_e32 v77, v77
	v_add_f32_e32 v58, v58, v59
	v_pk_mul_f32 v[52:53], v[30:31], v[30:31]
	v_mul_f32_e32 v70, 0xbfb8aa3b, v55
	v_mul_f32_e32 v73, 0xbfb8aa3b, v42
	v_mul_f32_e32 v76, 0xbfb8aa3b, v64
	v_mul_f32_e32 v79, 0xbfb8aa3b, v45
	v_mul_f32_e32 v81, 0xbfb8aa3b, v40
	v_exp_f32_e32 v69, v69
	v_exp_f32_e32 v72, v72
	v_exp_f32_e32 v75, v75
	v_exp_f32_e32 v78, v78
	v_exp_f32_e32 v59, v80
	v_add_f32_e32 v58, v62, v58
	v_lshlrev_b32_e32 v47, 16, v33
	v_lshlrev_b32_e32 v46, 16, v32
	v_and_b32_e32 v33, 0xffff0000, v33
	v_and_b32_e32 v32, 0xffff0000, v32
	v_pk_fma_f32 v[52:53], v[24:25], v[24:25], v[52:53]
	v_exp_f32_e32 v70, v70
	v_exp_f32_e32 v73, v73
	v_exp_f32_e32 v76, v76
	v_exp_f32_e32 v79, v79
	v_exp_f32_e32 v80, v81
	v_add_f32_e32 v58, v63, v58
	v_pk_mul_f32 v[56:57], v[32:33], v[32:33]
	v_add_f32_e32 v52, v52, v58
	v_pk_fma_f32 v[56:57], v[46:47], v[46:47], v[56:57]
	v_add_f32_e32 v58, 1.0, v68
	v_add_f32_e32 v68, 1.0, v71
	v_add_f32_e32 v71, 1.0, v74
	v_add_f32_e32 v74, 1.0, v77
	v_add_f32_e32 v77, v53, v52
	v_add_f32_e32 v62, 1.0, v69
	v_add_f32_e32 v69, 1.0, v72
	v_add_f32_e32 v72, 1.0, v75
	v_add_f32_e32 v75, 1.0, v78
	v_add_f32_e32 v78, 1.0, v59
	v_add_f32_e32 v56, v56, v77
	v_add_f32_e32 v63, 1.0, v70
	v_add_f32_e32 v70, 1.0, v73
	v_add_f32_e32 v73, 1.0, v76
	v_add_f32_e32 v76, 1.0, v79
	v_add_f32_e32 v79, 1.0, v80
	v_rcp_f32_e32 v52, v58
	v_rcp_f32_e32 v58, v62
	v_rcp_f32_e32 v62, v69
	v_rcp_f32_e32 v69, v72
	v_rcp_f32_e32 v72, v74
	v_rcp_f32_e32 v74, v78
	v_add_f32_e32 v78, v57, v56
	v_rcp_f32_e32 v59, v68
	v_rcp_f32_e32 v68, v70
	v_rcp_f32_e32 v70, v73
	v_rcp_f32_e32 v73, v76
	v_rcp_f32_e32 v76, v79
	ds_bpermute_b32 v79, v27, v78
	v_rcp_f32_e32 v53, v63
	v_rcp_f32_e32 v63, v71
	v_lshlrev_b32_e32 v67, 16, v41
	v_and_b32_e32 v41, 0xffff0000, v41
	v_pk_mul_f32 v[52:53], v[52:53], v[54:55]
	v_pk_mul_f32 v[54:55], v[62:63], v[60:61]
	s_waitcnt lgkmcnt(0)
	v_add_f32_e32 v60, v78, v79
	ds_bpermute_b32 v61, v28, v60
	v_mul_f32_e32 v82, 0xbfb8aa3b, v67
	v_mul_f32_e32 v83, 0xbfb8aa3b, v41
	v_exp_f32_e32 v81, v82
	v_exp_f32_e32 v82, v83
	s_waitcnt lgkmcnt(0)
	v_add_f32_e32 v60, v60, v61
	ds_bpermute_b32 v61, v29, v60
	v_add_f32_e32 v80, 1.0, v81
	v_add_f32_e32 v81, 1.0, v82
	v_rcp_f32_e32 v71, v75
	v_rcp_f32_e32 v75, v80
	s_waitcnt lgkmcnt(0)
	v_add_f32_e32 v60, v60, v61
	v_fmamk_f32 v60, v60, 0x3c000000, v26
	v_mul_f32_e32 v61, 0x4b800000, v60
	v_cmp_gt_f32_e32 vcc, s19, v60
	v_rcp_f32_e32 v77, v81
	v_pk_mul_f32 v[42:43], v[68:69], v[42:43]
	v_cndmask_b32_e32 v60, v60, v61, vcc
	v_rsq_f32_e32 v60, v60
	v_pk_mul_f32 v[56:57], v[70:71], v[64:65]
	v_pk_mul_f32 v[44:45], v[72:73], v[44:45]
	v_pk_mul_f32 v[38:39], v[58:59], v[38:39]
	v_mul_f32_e32 v61, 0x45800000, v60
	v_cndmask_b32_e32 v60, v60, v61, vcc
	v_pk_mul_f32 v[48:49], v[60:61], v[48:49] op_sel_hi:[0,1]
	v_pk_mul_f32 v[34:35], v[60:61], v[34:35] op_sel_hi:[0,1]
	v_pk_mul_f32 v[50:51], v[60:61], v[50:51] op_sel_hi:[0,1]
	v_pk_mul_f32 v[36:37], v[60:61], v[36:37] op_sel_hi:[0,1]
	v_pk_mul_f32 v[24:25], v[60:61], v[24:25] op_sel_hi:[0,1]
	v_pk_mul_f32 v[30:31], v[60:61], v[30:31] op_sel_hi:[0,1]
	v_pk_mul_f32 v[46:47], v[60:61], v[46:47] op_sel_hi:[0,1]
	v_pk_mul_f32 v[32:33], v[60:61], v[32:33] op_sel_hi:[0,1]
	v_pk_mul_f32 v[48:49], v[8:9], v[48:49]
	v_pk_mul_f32 v[34:35], v[6:7], v[34:35]
	v_pk_mul_f32 v[50:51], v[12:13], v[50:51]
	v_pk_mul_f32 v[36:37], v[10:11], v[36:37]
	v_pk_mul_f32 v[58:59], v[74:75], v[66:67]
	v_pk_mul_f32 v[40:41], v[76:77], v[40:41]
	v_pk_mul_f32 v[24:25], v[0:1], v[24:25]
	v_pk_mul_f32 v[30:31], v[22:23], v[30:31]
	v_pk_mul_f32 v[46:47], v[4:5], v[46:47]
	v_pk_mul_f32 v[32:33], v[2:3], v[32:33]
	v_pk_mul_f32 v[48:49], v[54:55], v[48:49]
	v_pk_mul_f32 v[34:35], v[42:43], v[34:35]
	v_pk_mul_f32 v[42:43], v[56:57], v[50:51]
	v_pk_mul_f32 v[36:37], v[44:45], v[36:37]
	v_pk_mul_f32 v[24:25], v[52:53], v[24:25]
	v_pk_mul_f32 v[30:31], v[38:39], v[30:31]
	v_pk_mul_f32 v[38:39], v[58:59], v[46:47]
	v_pk_mul_f32 v[32:33], v[40:41], v[32:33]
	v_bfe_u32 v40, v37, 16, 1
	v_bfe_u32 v41, v36, 16, 1
	v_bfe_u32 v46, v48, 16, 1
	v_bfe_u32 v47, v49, 16, 1
	v_bfe_u32 v50, v42, 16, 1
	v_bfe_u32 v51, v43, 16, 1
	v_bfe_u32 v44, v35, 16, 1
	v_bfe_u32 v45, v34, 16, 1
	v_bfe_u32 v52, v33, 16, 1
	v_bfe_u32 v53, v32, 16, 1
	v_bfe_u32 v54, v31, 16, 1
	v_bfe_u32 v55, v30, 16, 1
	v_bfe_u32 v56, v24, 16, 1
	v_bfe_u32 v57, v25, 16, 1
	v_bfe_u32 v58, v38, 16, 1
	v_bfe_u32 v59, v39, 16, 1
	v_add3_u32 v36, v36, v41, s1
	v_add3_u32 v37, v37, v40, s1
	v_add3_u32 v40, v43, v51, s1
	v_add3_u32 v41, v42, v50, s1
	v_add3_u32 v42, v49, v47, s1
	v_add3_u32 v43, v48, v46, s1
	v_add3_u32 v34, v34, v45, s1
	v_add3_u32 v35, v35, v44, s1
	v_add3_u32 v44, v30, v55, s1
	v_add3_u32 v45, v31, v54, s1
	v_add3_u32 v46, v32, v53, s1
	v_add3_u32 v47, v33, v52, s1
	v_add3_u32 v30, v39, v59, s1
	v_add3_u32 v31, v38, v58, s1
	v_add3_u32 v25, v25, v57, s1
	v_add3_u32 v24, v24, v56, s1
	v_lshrrev_b32_e32 v38, 16, v43
	v_lshrrev_b32_e32 v39, 16, v42
	v_lshrrev_b32_e32 v32, 16, v41
	v_lshrrev_b32_e32 v33, 16, v40
	v_lshrrev_b32_e32 v24, 16, v24
	v_lshrrev_b32_e32 v25, 16, v25
	v_lshrrev_b32_e32 v40, 16, v31
	v_lshrrev_b32_e32 v41, 16, v30
	v_and_or_b32 v33, v37, s18, v33
	v_and_or_b32 v32, v36, s18, v32
	v_and_or_b32 v31, v35, s18, v39
	v_and_or_b32 v30, v34, s18, v38
	v_and_or_b32 v37, v47, s18, v41
	v_and_or_b32 v36, v46, s18, v40
	v_and_or_b32 v35, v45, s18, v25
	v_and_or_b32 v34, v44, s18, v24
	global_store_dwordx4 v[14:15], v[30:33], off offset:2048
	global_store_dwordx4 v[14:15], v[34:37], off offset:2064
	s_cbranch_scc1 .LBB0_1124

; #define LAS __attribute__((address_space(3)))
; template <bool POST, bool PRE>
; __device__ __forceinline__ void row_core(const Params& P, const RowCfg& c, LAS float* vA, LAS float* vB, LAS float* vP, const bf16_t* RAW, const float* SSQ, bf16_t* H, int row, int lane, f32x4 (&v)[8]) {
;     ...
;         const u32x2* rs = (const u32x2*)(RAW + (size_t)row * DM) + lane;
;         float s = (lane < 32) ? SSQ[(size_t)row * 32 + lane] : 0.f; s = wave_sum(s);
;         const float rstd = rsqrtf(s * (1.0f / DM) + EPS);
;         f32x4* os = (f32x4*)(P.out + (size_t)row * DM) + lane;
; #pragma unroll
;         for (int j = 0; j < 8; ++j) { const u32x2 rb = rs[64 * j]; const f32x4 r = (f32x4){__uint_as_float(rb.x << 16), __uint_as_float(rb.x & 0xffff0000u), __uint_as_float(rb.y << 16), __uint_as_float(rb.y & 0xffff0000u)};
;             const f32x4 pv = *(const LAS f32x4*)(vP + j * 256 + lane * 4); v[j] += r * rstd * pv; os[64 * j] = v[j]; }
.LBB0_1273:
	s_or_b64 exec, exec, s[20:21]
	v_lshl_add_u64 v[38:39], s[92:93], 0, v[36:37]
	v_add_co_u32_e32 v44, vcc, s9, v38
	s_waitcnt vmcnt(0)
	ds_bpermute_b32 v41, v43, v40
	v_addc_co_u32_e32 v45, vcc, 0, v39, vcc
	global_load_dwordx2 v[62:63], v[44:45], off nt
	s_add_i32 s6, s6, s8
	s_waitcnt lgkmcnt(0)
	v_add_f32_e32 v40, v40, v41
	ds_bpermute_b32 v41, v46, v40
	s_add_u32 s12, s12, s14
	s_addc_u32 s13, s13, s15
	v_lshl_add_u64 v[34:35], v[34:35], 0, s[10:11]
	v_lshl_add_u64 v[36:37], v[36:37], 0, s[16:17]
	s_waitcnt lgkmcnt(0)
	v_add_f32_e32 v40, v40, v41
	ds_bpermute_b32 v41, v47, v40
	s_waitcnt lgkmcnt(0)
	v_add_f32_e32 v40, v40, v41
	ds_bpermute_b32 v41, v48, v40
	s_waitcnt lgkmcnt(0)
	v_add_f32_e32 v40, v40, v41
	ds_bpermute_b32 v41, v49, v40
	s_waitcnt lgkmcnt(0)
	v_add_f32_e32 v42, v40, v41
	ds_bpermute_b32 v52, v50, v42
	v_lshl_add_u64 v[40:41], s[18:19], 0, v[32:33]
	s_add_u32 s18, s18, s14
	s_addc_u32 s19, s19, s15
	s_cmpk_lt_i32 s6, 0x4000
	s_waitcnt lgkmcnt(0)
	v_add_f32_e32 v42, v42, v52
	v_fmamk_f32 v42, v42, 0x3a000000, v51
	v_mul_f32_e32 v52, 0x4b800000, v42
	v_cmp_gt_f32_e32 vcc, s7, v42
	s_waitcnt vmcnt(0)
	v_lshlrev_b32_e32 v64, 16, v62
	v_cndmask_b32_e32 v42, v42, v52, vcc
	v_rsq_f32_e32 v42, v42
	v_add_u32_e32 v52, 0, v32
	ds_read_b128 v[54:57], v52 offset:16384
	ds_read_b128 v[58:61], v52 offset:17408
	v_and_b32_e32 v65, 0xffff0000, v62
	v_mul_f32_e32 v53, 0x45800000, v42
	v_cndmask_b32_e32 v42, v42, v53, vcc
	v_lshlrev_b32_e32 v62, 16, v63
	v_and_b32_e32 v63, 0xffff0000, v63
	v_pk_mul_f32 v[64:65], v[42:43], v[64:65] op_sel_hi:[0,1]
	v_pk_mul_f32 v[62:63], v[42:43], v[62:63] op_sel_hi:[0,1]
	s_waitcnt lgkmcnt(1)
	v_pk_fma_f32 v[2:3], v[56:57], v[62:63], v[2:3]
	v_pk_fma_f32 v[0:1], v[54:55], v[64:65], v[0:1]
	global_store_dwordx4 v[40:41], v[0:3], off nt
	global_load_dwordx2 v[54:55], v[44:45], off offset:512 nt
	s_waitcnt vmcnt(0)
	v_lshlrev_b32_e32 v56, 16, v54
	v_and_b32_e32 v57, 0xffff0000, v54
	v_lshlrev_b32_e32 v54, 16, v55
	v_and_b32_e32 v55, 0xffff0000, v55
	v_pk_mul_f32 v[56:57], v[42:43], v[56:57] op_sel_hi:[0,1]
	v_pk_mul_f32 v[54:55], v[42:43], v[54:55] op_sel_hi:[0,1]
	s_waitcnt lgkmcnt(0)
	v_pk_fma_f32 v[6:7], v[60:61], v[54:55], v[6:7]
	v_pk_fma_f32 v[4:5], v[58:59], v[56:57], v[4:5]
	global_store_dwordx4 v[40:41], v[4:7], off offset:1024 nt
	global_load_dwordx2 v[62:63], v[44:45], off offset:1024 nt
	ds_read_b128 v[54:57], v52 offset:18432
	ds_read_b128 v[58:61], v52 offset:19456
	s_waitcnt vmcnt(0)
	v_lshlrev_b32_e32 v64, 16, v62
	v_and_b32_e32 v65, 0xffff0000, v62
	v_lshlrev_b32_e32 v62, 16, v63
	v_and_b32_e32 v63, 0xffff0000, v63
	v_pk_mul_f32 v[64:65], v[42:43], v[64:65] op_sel_hi:[0,1]
	v_pk_mul_f32 v[62:63], v[42:43], v[62:63] op_sel_hi:[0,1]
	s_waitcnt lgkmcnt(1)
	v_pk_fma_f32 v[10:11], v[56:57], v[62:63], v[10:11]
	v_pk_fma_f32 v[8:9], v[54:55], v[64:65], v[8:9]
	global_store_dwordx4 v[40:41], v[8:11], off offset:2048 nt
	global_load_dwordx2 v[54:55], v[44:45], off offset:1536 nt
	s_waitcnt vmcnt(0)
	v_lshlrev_b32_e32 v56, 16, v54
	v_and_b32_e32 v57, 0xffff0000, v54
	v_lshlrev_b32_e32 v54, 16, v55
	v_and_b32_e32 v55, 0xffff0000, v55
	v_pk_mul_f32 v[56:57], v[42:43], v[56:57] op_sel_hi:[0,1]
	v_pk_mul_f32 v[54:55], v[42:43], v[54:55] op_sel_hi:[0,1]
	s_waitcnt lgkmcnt(0)
	v_pk_fma_f32 v[14:15], v[60:61], v[54:55], v[14:15]
	v_pk_fma_f32 v[12:13], v[58:59], v[56:57], v[12:13]
	global_store_dwordx4 v[40:41], v[12:15], off offset:3072 nt
	global_load_dwordx2 v[62:63], v[44:45], off offset:2048 nt
	ds_read_b128 v[54:57], v52 offset:20480
	ds_read_b128 v[58:61], v52 offset:21504
	v_add_co_u32_e32 v40, vcc, s3, v40
	s_waitcnt vmcnt(0)
	v_lshlrev_b32_e32 v64, 16, v62
	v_and_b32_e32 v65, 0xffff0000, v62
	v_lshlrev_b32_e32 v62, 16, v63
	v_and_b32_e32 v63, 0xffff0000, v63
	v_pk_mul_f32 v[64:65], v[42:43], v[64:65] op_sel_hi:[0,1]
	v_pk_mul_f32 v[62:63], v[42:43], v[62:63] op_sel_hi:[0,1]
	v_addc_co_u32_e32 v41, vcc, 0, v41, vcc
	s_waitcnt lgkmcnt(1)
	v_pk_fma_f32 v[18:19], v[56:57], v[62:63], v[18:19]
	v_pk_fma_f32 v[16:17], v[54:55], v[64:65], v[16:17]
	global_store_dwordx4 v[40:41], v[16:19], off nt
	global_load_dwordx2 v[54:55], v[44:45], off offset:2560 nt
	s_waitcnt vmcnt(0)
	v_lshlrev_b32_e32 v56, 16, v54
	v_and_b32_e32 v57, 0xffff0000, v54
	v_lshlrev_b32_e32 v54, 16, v55
	v_and_b32_e32 v55, 0xffff0000, v55
	v_pk_mul_f32 v[56:57], v[42:43], v[56:57] op_sel_hi:[0,1]
	v_pk_mul_f32 v[54:55], v[42:43], v[54:55] op_sel_hi:[0,1]
	s_waitcnt lgkmcnt(0)
	v_pk_fma_f32 v[22:23], v[60:61], v[54:55], v[22:23]
	v_pk_fma_f32 v[20:21], v[58:59], v[56:57], v[20:21]
	global_store_dwordx4 v[40:41], v[20:23], off offset:1024 nt
	global_load_dwordx2 v[62:63], v[44:45], off offset:3072 nt
	ds_read_b128 v[54:57], v52 offset:22528
	ds_read_b128 v[58:61], v52 offset:23552
	s_waitcnt vmcnt(0)
	v_lshlrev_b32_e32 v64, 16, v62
	v_and_b32_e32 v65, 0xffff0000, v62
	v_lshlrev_b32_e32 v62, 16, v63
	v_and_b32_e32 v63, 0xffff0000, v63
	v_pk_mul_f32 v[64:65], v[42:43], v[64:65] op_sel_hi:[0,1]
	v_pk_mul_f32 v[62:63], v[42:43], v[62:63] op_sel_hi:[0,1]
	s_waitcnt lgkmcnt(1)
; #define LAS __attribute__((address_space(3)))
; __device__ __forceinline__ unsigned cvt_pk_bf16(float lo, float hi) { unsigned r; asm volatile("v_cvt_pk_bf16_f32 %0, %1, %2" : "=v"(r) : "v"(lo), "v"(hi)); return r; }
; template <bool POST, bool PRE>
; __device__ __forceinline__ void row_core(const Params& P, const RowCfg& c, LAS float* vA, LAS float* vB, LAS float* vP, const bf16_t* RAW, const float* SSQ, bf16_t* H, int row, int lane, f32x4 (&v)[8]) {
;     ...
;             const f32x4 pv = *(const LAS f32x4*)(vP + j * 256 + lane * 4); v[j] += r * rstd * pv; os[64 * j] = v[j]; }
;     }
;     if (PRE) {
;         float s2 = 0.f;
; #pragma unroll
;         for (int j = 0; j < 8; ++j) s2 += (v[j][0] * v[j][0] + v[j][1] * v[j][1]) + (v[j][2] * v[j][2] + v[j][3] * v[j][3]);
;         s2 = wave_sum(s2);
;         const float rstd2 = rsqrtf(s2 * (1.0f / DM) + EPS);
;         u32x2* hs = (u32x2*)(H + (size_t)row * DM) + lane;
; #pragma unroll
;         for (int j = 0; j < 8; ++j) { const f32x4 a = *(const LAS f32x4*)(vA + j * 256 + lane * 4), b = *(const LAS f32x4*)(vB + j * 256 + lane * 4);
;             v[j] = v[j] * rstd2 * a + b; u32x2 w; w.x = cvt_pk_bf16(v[j][0], v[j][1]); w.y = cvt_pk_bf16(v[j][2], v[j][3]); hs[64 * j] = w; }
	v_pk_fma_f32 v[30:31], v[56:57], v[62:63], v[30:31]
	v_pk_fma_f32 v[28:29], v[54:55], v[64:65], v[28:29]
	global_store_dwordx4 v[40:41], v[28:31], off offset:2048 nt
	global_load_dwordx2 v[44:45], v[44:45], off offset:3584 nt
	v_mov_b32_e32 v56, v1
	v_mov_b32_e32 v64, v3
	v_mov_b32_e32 v57, v5
	v_mov_b32_e32 v65, v7
	v_mov_b32_e32 v54, v0
	v_mov_b32_e32 v62, v2
	v_mov_b32_e32 v55, v4
	v_mov_b32_e32 v63, v6
	v_pk_mul_f32 v[56:57], v[56:57], v[56:57]
	v_pk_mul_f32 v[64:65], v[64:65], v[64:65]
	v_pk_fma_f32 v[54:55], v[54:55], v[54:55], v[56:57]
	v_pk_fma_f32 v[56:57], v[62:63], v[62:63], v[64:65]
	v_pk_mul_f32 v[62:63], v[8:9], v[8:9]
	v_pk_add_f32 v[54:55], v[54:55], v[56:57]
	v_pk_mul_f32 v[56:57], v[10:11], v[10:11]
	v_pk_add_f32 v[54:55], v[54:55], v[54:55] op_sel:[0,1] op_sel_hi:[1,0]
	v_pk_mov_b32 v[64:65], v[62:63], v[56:57] op_sel:[1,0]
	v_mov_b32_e32 v63, v57
	v_pk_add_f32 v[56:57], v[64:65], v[62:63]
	v_mul_f32_e32 v62, v13, v13
	v_mul_f32_e32 v64, v15, v15
	v_pk_add_f32 v[56:57], v[56:57], v[56:57] op_sel:[0,1] op_sel_hi:[1,0]
	v_pk_fma_f32 v[62:63], v[12:13], v[12:13], v[62:63] op_sel_hi:[1,1,0]
	v_pk_fma_f32 v[64:65], v[14:15], v[14:15], v[64:65] op_sel_hi:[1,1,0]
	v_mul_f32_e32 v55, v16, v16
	v_mul_f32_e32 v57, v17, v17
	v_mul_f32_e32 v63, v18, v18
	v_mul_f32_e32 v65, v19, v19
	v_pk_add_f32 v[54:55], v[54:55], v[56:57]
	v_pk_add_f32 v[56:57], v[62:63], v[64:65]
	v_pk_mul_f32 v[62:63], v[20:21], v[20:21]
	v_pk_add_f32 v[54:55], v[54:55], v[56:57]
	v_pk_mul_f32 v[56:57], v[22:23], v[22:23]
	v_pk_add_f32 v[54:55], v[54:55], v[54:55] op_sel:[0,1] op_sel_hi:[1,0]
	v_pk_mov_b32 v[64:65], v[62:63], v[56:57] op_sel:[1,0]
	v_mov_b32_e32 v63, v57
	v_pk_add_f32 v[56:57], v[64:65], v[62:63]
	v_mul_f32_e32 v62, v29, v29
	v_mul_f32_e32 v64, v31, v31
	v_pk_add_f32 v[56:57], v[56:57], v[56:57] op_sel:[0,1] op_sel_hi:[1,0]
	v_pk_fma_f32 v[62:63], v[28:29], v[28:29], v[62:63] op_sel_hi:[1,1,0]
	v_pk_fma_f32 v[64:65], v[30:31], v[30:31], v[64:65] op_sel_hi:[1,1,0]
	s_waitcnt vmcnt(0)
	v_lshlrev_b32_e32 v66, 16, v44
	v_and_b32_e32 v67, 0xffff0000, v44
	v_lshlrev_b32_e32 v44, 16, v45
	v_and_b32_e32 v45, 0xffff0000, v45
	v_pk_mul_f32 v[66:67], v[42:43], v[66:67] op_sel_hi:[0,1]
	v_pk_mul_f32 v[44:45], v[42:43], v[44:45] op_sel_hi:[0,1]
	s_waitcnt lgkmcnt(0)
	v_pk_fma_f32 v[26:27], v[60:61], v[44:45], v[26:27]
	v_pk_fma_f32 v[24:25], v[58:59], v[66:67], v[24:25]
	v_mul_f32_e32 v63, v26, v26
	v_mul_f32_e32 v55, v24, v24
	v_mul_f32_e32 v57, v25, v25
	v_mul_f32_e32 v65, v27, v27
	v_pk_add_f32 v[44:45], v[54:55], v[56:57]
	v_pk_add_f32 v[54:55], v[62:63], v[64:65]
	s_nop 0
	v_pk_add_f32 v[44:45], v[44:45], v[54:55]
	ds_read_b128 v[54:57], v52
	ds_read_b128 v[58:61], v52 offset:8192
	v_add_f32_e32 v42, v44, v45
	ds_bpermute_b32 v44, v43, v42
	global_store_dwordx4 v[40:41], v[24:27], off offset:3072 nt
	s_waitcnt lgkmcnt(0)
	v_add_f32_e32 v42, v42, v44
	ds_bpermute_b32 v44, v46, v42
	s_waitcnt lgkmcnt(0)
	v_add_f32_e32 v42, v42, v44
	ds_bpermute_b32 v44, v47, v42
	s_waitcnt lgkmcnt(0)
	v_add_f32_e32 v42, v42, v44
	ds_bpermute_b32 v44, v48, v42
	s_waitcnt lgkmcnt(0)
	v_add_f32_e32 v42, v42, v44
	ds_bpermute_b32 v44, v49, v42
	s_waitcnt lgkmcnt(0)
	v_add_f32_e32 v42, v42, v44
	ds_bpermute_b32 v44, v50, v42
	s_waitcnt lgkmcnt(0)
	v_add_f32_e32 v42, v42, v44
	v_fmamk_f32 v42, v42, 0x3a000000, v51
	v_mul_f32_e32 v44, 0x4b800000, v42
	v_cmp_gt_f32_e32 vcc, s7, v42
	s_nop 1
	v_cndmask_b32_e32 v42, v42, v44, vcc
	v_rsq_f32_e32 v42, v42
	s_nop 0
	v_mul_f32_e32 v40, 0x45800000, v42
	v_cndmask_b32_e32 v40, v42, v40, vcc
	v_pk_mul_f32 v[0:1], v[0:1], v[40:41] op_sel_hi:[1,0]
	v_pk_mul_f32 v[2:3], v[2:3], v[40:41] op_sel_hi:[1,0]
	v_pk_fma_f32 v[0:1], v[54:55], v[0:1], v[58:59]
	v_pk_fma_f32 v[2:3], v[56:57], v[2:3], v[60:61]
	v_cvt_pk_bf16_f32 v44, v0, v1
	v_add_co_u32_e32 v38, vcc, s22, v38
	v_cvt_pk_bf16_f32 v45, v2, v3
	ds_read_b128 v[0:3], v52 offset:1024
	ds_read_b128 v[54:57], v52 offset:9216
	v_pk_mul_f32 v[4:5], v[4:5], v[40:41] op_sel_hi:[1,0]
	v_pk_mul_f32 v[6:7], v[6:7], v[40:41] op_sel_hi:[1,0]
	v_addc_co_u32_e32 v39, vcc, 0, v39, vcc
	s_waitcnt lgkmcnt(0)
	v_pk_fma_f32 v[2:3], v[2:3], v[6:7], v[56:57]
	v_pk_fma_f32 v[0:1], v[0:1], v[4:5], v[54:55]
	global_store_dwordx2 v[38:39], v[44:45], off
	v_cvt_pk_bf16_f32 v44, v0, v1
	v_cvt_pk_bf16_f32 v45, v2, v3
	ds_read_b128 v[0:3], v52 offset:2048
	ds_read_b128 v[4:7], v52 offset:10240
	v_pk_mul_f32 v[8:9], v[8:9], v[40:41] op_sel_hi:[1,0]
	v_pk_mul_f32 v[10:11], v[10:11], v[40:41] op_sel_hi:[1,0]
	global_store_dwordx2 v[38:39], v[44:45], off offset:512
	s_waitcnt lgkmcnt(0)
	v_pk_fma_f32 v[2:3], v[2:3], v[10:11], v[6:7]
	v_pk_fma_f32 v[0:1], v[0:1], v[8:9], v[4:5]
	v_pk_mul_f32 v[10:11], v[12:13], v[40:41] op_sel_hi:[1,0]
	v_cvt_pk_bf16_f32 v8, v0, v1
	v_cvt_pk_bf16_f32 v9, v2, v3
	ds_read_b128 v[0:3], v52 offset:3072
	ds_read_b128 v[4:7], v52 offset:11264
	v_pk_mul_f32 v[12:13], v[14:15], v[40:41] op_sel_hi:[1,0]
	global_store_dwordx2 v[38:39], v[8:9], off offset:1024
	s_waitcnt lgkmcnt(0)
	v_pk_fma_f32 v[2:3], v[2:3], v[12:13], v[6:7]
	v_pk_fma_f32 v[0:1], v[0:1], v[10:11], v[4:5]
	v_pk_mul_f32 v[10:11], v[16:17], v[40:41] op_sel_hi:[1,0]
	v_cvt_pk_bf16_f32 v8, v0, v1
	v_cvt_pk_bf16_f32 v9, v2, v3
	ds_read_b128 v[0:3], v52 offset:4096
	ds_read_b128 v[4:7], v52 offset:12288
	v_pk_mul_f32 v[12:13], v[18:19], v[40:41] op_sel_hi:[1,0]
	global_store_dwordx2 v[38:39], v[8:9], off offset:1536
	s_waitcnt lgkmcnt(0)
	v_pk_fma_f32 v[2:3], v[2:3], v[12:13], v[6:7]
	v_pk_fma_f32 v[0:1], v[0:1], v[10:11], v[4:5]
	v_pk_mul_f32 v[10:11], v[20:21], v[40:41] op_sel_hi:[1,0]
	v_cvt_pk_bf16_f32 v8, v0, v1
	v_cvt_pk_bf16_f32 v9, v2, v3
	ds_read_b128 v[0:3], v52 offset:5120
	ds_read_b128 v[4:7], v52 offset:13312
	v_pk_mul_f32 v[12:13], v[22:23], v[40:41] op_sel_hi:[1,0]
	global_store_dwordx2 v[38:39], v[8:9], off offset:2048
	s_waitcnt lgkmcnt(0)
	v_pk_fma_f32 v[2:3], v[12:13], v[2:3], v[6:7]
	v_pk_fma_f32 v[0:1], v[10:11], v[0:1], v[4:5]
	v_pk_mul_f32 v[10:11], v[28:29], v[40:41] op_sel_hi:[1,0]
	v_cvt_pk_bf16_f32 v8, v0, v1
	v_cvt_pk_bf16_f32 v9, v2, v3
	ds_read_b128 v[0:3], v52 offset:6144
	ds_read_b128 v[4:7], v52 offset:14336
	v_pk_mul_f32 v[12:13], v[30:31], v[40:41] op_sel_hi:[1,0]
	global_store_dwordx2 v[38:39], v[8:9], off offset:2560
	s_waitcnt lgkmcnt(0)
	v_pk_fma_f32 v[2:3], v[12:13], v[2:3], v[6:7]
	v_pk_fma_f32 v[0:1], v[10:11], v[0:1], v[4:5]
	v_pk_mul_f32 v[10:11], v[24:25], v[40:41] op_sel_hi:[1,0]
	v_cvt_pk_bf16_f32 v8, v0, v1
	v_cvt_pk_bf16_f32 v9, v2, v3
	ds_read_b128 v[0:3], v52 offset:7168
	ds_read_b128 v[4:7], v52 offset:15360
	v_pk_mul_f32 v[12:13], v[26:27], v[40:41] op_sel_hi:[1,0]
	global_store_dwordx2 v[38:39], v[8:9], off offset:3072
	s_waitcnt lgkmcnt(0)
	v_pk_fma_f32 v[0:1], v[10:11], v[0:1], v[4:5]
	v_pk_fma_f32 v[2:3], v[12:13], v[2:3], v[6:7]
	v_cvt_pk_bf16_f32 v0, v0, v1
	s_nop 0
	v_cvt_pk_bf16_f32 v1, v2, v3
	global_store_dwordx2 v[38:39], v[0:1], off offset:3584
	s_cbranch_scc0 .LBB0_1276

; #define LAS __attribute__((address_space(3)))
; template <bool POST, bool PRE>
; __device__ __forceinline__ void row_core(const Params& P, const RowCfg& c, LAS float* vA, LAS float* vB, LAS float* vP, const bf16_t* RAW, const float* SSQ, bf16_t* H, int row, int lane, f32x4 (&v)[8]) {
;     ...
;         const u32x2* rs = (const u32x2*)(RAW + (size_t)row * DM) + lane;
;         float s = (lane < 32) ? SSQ[(size_t)row * 32 + lane] : 0.f; s = wave_sum(s);
;         const float rstd = rsqrtf(s * (1.0f / DM) + EPS);
;         f32x4* os = (f32x4*)(P.out + (size_t)row * DM) + lane;
; #pragma unroll
;         for (int j = 0; j < 8; ++j) { const u32x2 rb = rs[64 * j]; const f32x4 r = (f32x4){__uint_as_float(rb.x << 16), __uint_as_float(rb.x & 0xffff0000u), __uint_as_float(rb.y << 16), __uint_as_float(rb.y & 0xffff0000u)};
;             const f32x4 pv = *(const LAS f32x4*)(vP + j * 256 + lane * 4); v[j] += r * rstd * pv; os[64 * j] = v[j]; }
;     }
;     if (PRE) {
;         float s2 = 0.f;
; #pragma unroll
;         for (int j = 0; j < 8; ++j) s2 += (v[j][0] * v[j][0] + v[j][1] * v[j][1]) + (v[j][2] * v[j][2] + v[j][3] * v[j][3]);
;         s2 = wave_sum(s2);
; template <bool POST, bool PRE, bool THIN>
; __device__ __forceinline__ void row_phase(const Ctx& F, const RowCfg c) {
;     ...
;             else {
; #pragma unroll
;                 for (int j = 0; j < 8; ++j) v1[j] = (f32x4){0.f, 0.f, 0.f, 0.f}; }
.LBB0_1505:
	s_or_b64 exec, exec, s[38:39]
	v_lshl_add_u64 v[62:63], s[92:93], 0, v[60:61]
	v_add_co_u32_e32 v40, vcc, s19, v62
	s_waitcnt vmcnt(0)
	ds_bpermute_b32 v33, v106, v32
	v_addc_co_u32_e32 v41, vcc, 0, v63, vcc
	global_load_dwordx2 v[42:43], v[40:41], off nt
	s_add_i32 s38, s3, s16
	s_waitcnt lgkmcnt(0)
	v_add_f32_e32 v32, v32, v33
	ds_bpermute_b32 v33, v107, v32
	s_cmpk_lt_i32 s38, 0x4000
	v_mov_b32_e32 v83, 0
	v_mov_b32_e32 v82, 0
	v_mov_b32_e32 v85, 0
	s_waitcnt lgkmcnt(0)
	v_add_f32_e32 v32, v32, v33
	ds_bpermute_b32 v33, v108, v32
	v_mov_b32_e32 v84, 0
	v_mov_b32_e32 v87, 0
	v_mov_b32_e32 v86, 0
	v_mov_b32_e32 v91, 0
	s_waitcnt lgkmcnt(0)
	v_add_f32_e32 v32, v32, v33
	ds_bpermute_b32 v33, v109, v32
	v_mov_b32_e32 v90, 0
	v_mov_b32_e32 v89, 0
	v_mov_b32_e32 v88, 0
	v_mov_b32_e32 v93, 0
	s_waitcnt lgkmcnt(0)
	v_add_f32_e32 v32, v32, v33
	ds_bpermute_b32 v33, v110, v32
	v_mov_b32_e32 v92, 0
	v_mov_b32_e32 v95, 0
	v_mov_b32_e32 v94, 0
	v_mov_b32_e32 v99, 0
	s_waitcnt lgkmcnt(0)
	v_add_f32_e32 v32, v32, v33
	ds_bpermute_b32 v33, v111, v32
	v_mov_b32_e32 v98, 0
	v_mov_b32_e32 v97, 0
	v_mov_b32_e32 v96, 0
	v_mov_b32_e32 v101, 0
	s_waitcnt lgkmcnt(0)
	v_add_f32_e32 v32, v32, v33
	v_fmamk_f32 v32, v32, 0x3a000000, v178
	v_mul_f32_e32 v33, 0x4b800000, v32
	v_cmp_gt_f32_e32 vcc, s17, v32
	v_mov_b32_e32 v100, 0
	v_mov_b32_e32 v103, 0
	v_cndmask_b32_e32 v32, v32, v33, vcc
	v_rsq_f32_e32 v64, v32
	ds_read_b128 v[32:35], v112 offset:16384
	ds_read_b128 v[36:39], v112 offset:17408
	v_mov_b32_e32 v102, 0
	v_mov_b32_e32 v105, 0
	v_mul_f32_e32 v65, 0x45800000, v64
	v_cndmask_b32_e32 v64, v64, v65, vcc
	v_mov_b32_e32 v104, 0
	s_cselect_b64 s[40:41], -1, 0
	s_cmpk_gt_i32 s38, 0x3fff
	s_waitcnt vmcnt(0)
	v_lshlrev_b32_e32 v66, 16, v42
	v_and_b32_e32 v67, 0xffff0000, v42
	v_lshlrev_b32_e32 v42, 16, v43
	v_and_b32_e32 v43, 0xffff0000, v43
	v_pk_mul_f32 v[66:67], v[64:65], v[66:67] op_sel_hi:[0,1]
	v_pk_mul_f32 v[42:43], v[64:65], v[42:43] op_sel_hi:[0,1]
	s_waitcnt lgkmcnt(1)
	v_pk_fma_f32 v[6:7], v[34:35], v[42:43], v[6:7]
	v_pk_fma_f32 v[4:5], v[32:33], v[66:67], v[4:5]
	global_store_dwordx4 v[58:59], v[4:7], off offset:-4096 nt
	global_load_dwordx2 v[32:33], v[40:41], off offset:512 nt
	v_mov_b32_e32 v70, v5
	v_mov_b32_e32 v74, v7
	v_mov_b32_e32 v68, v4
	v_mov_b32_e32 v72, v6
	s_waitcnt vmcnt(0)
	v_lshlrev_b32_e32 v34, 16, v32
	v_and_b32_e32 v35, 0xffff0000, v32
	v_lshlrev_b32_e32 v32, 16, v33
	v_and_b32_e32 v33, 0xffff0000, v33
	v_pk_mul_f32 v[34:35], v[64:65], v[34:35] op_sel_hi:[0,1]
	v_pk_mul_f32 v[32:33], v[64:65], v[32:33] op_sel_hi:[0,1]
	s_waitcnt lgkmcnt(0)
	v_pk_fma_f32 v[10:11], v[38:39], v[32:33], v[10:11]
	v_pk_fma_f32 v[8:9], v[36:37], v[34:35], v[8:9]
	global_store_dwordx4 v[58:59], v[8:11], off offset:-3072 nt
	global_load_dwordx2 v[42:43], v[40:41], off offset:1024 nt
	ds_read_b128 v[32:35], v112 offset:18432
	ds_read_b128 v[36:39], v112 offset:19456
	v_mov_b32_e32 v71, v9
	v_mov_b32_e32 v75, v11
	v_mov_b32_e32 v69, v8
	v_mov_b32_e32 v73, v10
	v_pk_mul_f32 v[70:71], v[70:71], v[70:71]
	v_pk_mul_f32 v[74:75], v[74:75], v[74:75]
	v_pk_fma_f32 v[68:69], v[68:69], v[68:69], v[70:71]
	v_pk_fma_f32 v[70:71], v[72:73], v[72:73], v[74:75]
	s_waitcnt vmcnt(0)
	v_lshlrev_b32_e32 v66, 16, v42
	v_and_b32_e32 v67, 0xffff0000, v42
	v_lshlrev_b32_e32 v42, 16, v43
	v_and_b32_e32 v43, 0xffff0000, v43
	v_pk_mul_f32 v[66:67], v[64:65], v[66:67] op_sel_hi:[0,1]
	v_pk_mul_f32 v[42:43], v[64:65], v[42:43] op_sel_hi:[0,1]
	s_waitcnt lgkmcnt(1)
	v_pk_fma_f32 v[14:15], v[34:35], v[42:43], v[14:15]
	v_pk_fma_f32 v[12:13], v[32:33], v[66:67], v[12:13]
	global_store_dwordx4 v[58:59], v[12:15], off offset:-2048 nt
	global_load_dwordx2 v[32:33], v[40:41], off offset:1536 nt
	v_pk_add_f32 v[68:69], v[68:69], v[70:71]
	v_pk_mul_f32 v[70:71], v[14:15], v[14:15]
	v_pk_mul_f32 v[72:73], v[12:13], v[12:13]
	v_pk_add_f32 v[68:69], v[68:69], v[68:69] op_sel:[0,1] op_sel_hi:[1,0]
	v_pk_mov_b32 v[74:75], v[72:73], v[70:71] op_sel:[1,0]
	v_mov_b32_e32 v73, v71
	v_pk_add_f32 v[70:71], v[74:75], v[72:73]
	s_waitcnt vmcnt(0)
	v_lshlrev_b32_e32 v34, 16, v32
	v_and_b32_e32 v35, 0xffff0000, v32
	v_lshlrev_b32_e32 v32, 16, v33
	v_and_b32_e32 v33, 0xffff0000, v33
	v_pk_mul_f32 v[34:35], v[64:65], v[34:35] op_sel_hi:[0,1]
	v_pk_mul_f32 v[32:33], v[64:65], v[32:33] op_sel_hi:[0,1]
	s_waitcnt lgkmcnt(0)
	v_pk_fma_f32 v[18:19], v[38:39], v[32:33], v[18:19]
	v_pk_fma_f32 v[16:17], v[36:37], v[34:35], v[16:17]
	global_store_dwordx4 v[58:59], v[16:19], off offset:-1024 nt
	global_load_dwordx2 v[42:43], v[40:41], off offset:2048 nt
	ds_read_b128 v[32:35], v112 offset:20480
	ds_read_b128 v[36:39], v112 offset:21504
	v_mul_f32_e32 v72, v17, v17
	v_mul_f32_e32 v74, v19, v19
	v_pk_add_f32 v[70:71], v[70:71], v[70:71] op_sel:[0,1] op_sel_hi:[1,0]
	v_pk_fma_f32 v[72:73], v[16:17], v[16:17], v[72:73] op_sel_hi:[1,1,0]
	v_pk_fma_f32 v[74:75], v[18:19], v[18:19], v[74:75] op_sel_hi:[1,1,0]
	s_waitcnt vmcnt(0)
	v_lshlrev_b32_e32 v66, 16, v42
	v_and_b32_e32 v67, 0xffff0000, v42
	v_lshlrev_b32_e32 v42, 16, v43
	v_and_b32_e32 v43, 0xffff0000, v43
	v_pk_mul_f32 v[66:67], v[64:65], v[66:67] op_sel_hi:[0,1]
	v_pk_mul_f32 v[42:43], v[64:65], v[42:43] op_sel_hi:[0,1]
	s_waitcnt lgkmcnt(1)
	v_pk_fma_f32 v[22:23], v[34:35], v[42:43], v[22:23]
	v_pk_fma_f32 v[20:21], v[32:33], v[66:67], v[20:21]
	global_store_dwordx4 v[58:59], v[20:23], off nt
	global_load_dwordx2 v[32:33], v[40:41], off offset:2560 nt
	v_mul_f32_e32 v69, v20, v20
	v_mul_f32_e32 v71, v21, v21
	v_mul_f32_e32 v73, v22, v22
	v_mul_f32_e32 v75, v23, v23
	v_pk_add_f32 v[68:69], v[68:69], v[70:71]
	v_pk_add_f32 v[70:71], v[72:73], v[74:75]
	s_waitcnt vmcnt(0)
; #define LAS __attribute__((address_space(3)))
; __device__ __forceinline__ unsigned cvt_pk_bf16(float lo, float hi) { unsigned r; asm volatile("v_cvt_pk_bf16_f32 %0, %1, %2" : "=v"(r) : "v"(lo), "v"(hi)); return r; }
; template <bool POST, bool PRE>
; __device__ __forceinline__ void row_core(const Params& P, const RowCfg& c, LAS float* vA, LAS float* vB, LAS float* vP, const bf16_t* RAW, const float* SSQ, bf16_t* H, int row, int lane, f32x4 (&v)[8]) {
;     ...
;             const f32x4 pv = *(const LAS f32x4*)(vP + j * 256 + lane * 4); v[j] += r * rstd * pv; os[64 * j] = v[j]; }
;     }
;     if (PRE) {
;         float s2 = 0.f;
; #pragma unroll
;         for (int j = 0; j < 8; ++j) s2 += (v[j][0] * v[j][0] + v[j][1] * v[j][1]) + (v[j][2] * v[j][2] + v[j][3] * v[j][3]);
;         s2 = wave_sum(s2);
;         const float rstd2 = rsqrtf(s2 * (1.0f / DM) + EPS);
;         u32x2* hs = (u32x2*)(H + (size_t)row * DM) + lane;
; #pragma unroll
;         for (int j = 0; j < 8; ++j) { const f32x4 a = *(const LAS f32x4*)(vA + j * 256 + lane * 4), b = *(const LAS f32x4*)(vB + j * 256 + lane * 4);
;             v[j] = v[j] * rstd2 * a + b; u32x2 w; w.x = cvt_pk_bf16(v[j][0], v[j][1]); w.y = cvt_pk_bf16(v[j][2], v[j][3]); hs[64 * j] = w; }
	v_lshlrev_b32_e32 v34, 16, v32
	v_and_b32_e32 v35, 0xffff0000, v32
	v_lshlrev_b32_e32 v32, 16, v33
	v_and_b32_e32 v33, 0xffff0000, v33
	v_pk_mul_f32 v[34:35], v[64:65], v[34:35] op_sel_hi:[0,1]
	v_pk_mul_f32 v[32:33], v[64:65], v[32:33] op_sel_hi:[0,1]
	s_waitcnt lgkmcnt(0)
	v_pk_fma_f32 v[26:27], v[38:39], v[32:33], v[26:27]
	v_pk_fma_f32 v[24:25], v[36:37], v[34:35], v[24:25]
	global_store_dwordx4 v[58:59], v[24:27], off offset:1024 nt
	global_load_dwordx2 v[42:43], v[40:41], off offset:3072 nt
	ds_read_b128 v[36:39], v112 offset:22528
	ds_read_b128 v[32:35], v112 offset:23552
	v_pk_add_f32 v[68:69], v[68:69], v[70:71]
	v_pk_mul_f32 v[70:71], v[26:27], v[26:27]
	v_pk_mul_f32 v[72:73], v[24:25], v[24:25]
	v_pk_add_f32 v[68:69], v[68:69], v[68:69] op_sel:[0,1] op_sel_hi:[1,0]
	v_pk_mov_b32 v[74:75], v[72:73], v[70:71] op_sel:[1,0]
	v_mov_b32_e32 v73, v71
	v_pk_add_f32 v[70:71], v[74:75], v[72:73]
	s_waitcnt vmcnt(0)
	v_lshlrev_b32_e32 v66, 16, v42
	v_and_b32_e32 v67, 0xffff0000, v42
	v_lshlrev_b32_e32 v42, 16, v43
	v_and_b32_e32 v43, 0xffff0000, v43
	v_pk_mul_f32 v[66:67], v[64:65], v[66:67] op_sel_hi:[0,1]
	v_pk_mul_f32 v[42:43], v[64:65], v[42:43] op_sel_hi:[0,1]
	s_waitcnt lgkmcnt(1)
	v_pk_fma_f32 v[30:31], v[38:39], v[42:43], v[30:31]
	v_pk_fma_f32 v[28:29], v[36:37], v[66:67], v[28:29]
	global_store_dwordx4 v[58:59], v[28:31], off offset:2048 nt
	global_load_dwordx2 v[66:67], v[40:41], off offset:3584 nt
	v_mul_f32_e32 v72, v29, v29
	v_mul_f32_e32 v74, v31, v31
	v_pk_add_f32 v[70:71], v[70:71], v[70:71] op_sel:[0,1] op_sel_hi:[1,0]
	v_pk_fma_f32 v[72:73], v[28:29], v[28:29], v[72:73] op_sel_hi:[1,1,0]
	v_pk_fma_f32 v[74:75], v[30:31], v[30:31], v[74:75] op_sel_hi:[1,1,0]
	ds_read_b128 v[36:39], v112
	ds_read_b128 v[40:43], v112 offset:8192
	s_waitcnt vmcnt(0)
	v_lshlrev_b32_e32 v76, 16, v66
	v_and_b32_e32 v77, 0xffff0000, v66
	v_lshlrev_b32_e32 v66, 16, v67
	v_and_b32_e32 v67, 0xffff0000, v67
	v_pk_mul_f32 v[76:77], v[64:65], v[76:77] op_sel_hi:[0,1]
	v_pk_mul_f32 v[64:65], v[64:65], v[66:67] op_sel_hi:[0,1]
	s_waitcnt lgkmcnt(2)
	v_pk_fma_f32 v[182:183], v[34:35], v[64:65], v[2:3]
	v_pk_fma_f32 v[180:181], v[32:33], v[76:77], v[0:1]
	v_mul_f32_e32 v73, v182, v182
	v_mul_f32_e32 v69, v180, v180
	v_mul_f32_e32 v71, v181, v181
	v_mul_f32_e32 v75, v183, v183
	v_pk_add_f32 v[0:1], v[68:69], v[70:71]
	v_pk_add_f32 v[2:3], v[72:73], v[74:75]
	global_store_dwordx4 v[58:59], v[180:183], off offset:3072 nt
	v_pk_add_f32 v[0:1], v[0:1], v[2:3]
	v_mov_b32_e32 v3, 0
	v_add_f32_e32 v32, v0, v1
	ds_bpermute_b32 v33, v106, v32
	v_mov_b32_e32 v2, 0
	v_mov_b32_e32 v1, 0
	v_mov_b32_e32 v0, 0
	s_waitcnt lgkmcnt(0)
	v_add_f32_e32 v32, v32, v33
	ds_bpermute_b32 v33, v107, v32
	s_waitcnt lgkmcnt(0)
	v_add_f32_e32 v32, v32, v33
	ds_bpermute_b32 v33, v108, v32
	s_waitcnt lgkmcnt(0)
	v_add_f32_e32 v32, v32, v33
	ds_bpermute_b32 v33, v109, v32
	s_waitcnt lgkmcnt(0)
	v_add_f32_e32 v32, v32, v33
	ds_bpermute_b32 v33, v110, v32
	s_waitcnt lgkmcnt(0)
	v_add_f32_e32 v32, v32, v33
	ds_bpermute_b32 v33, v111, v32
	s_waitcnt lgkmcnt(0)
	v_add_f32_e32 v32, v32, v33
	v_fmamk_f32 v32, v32, 0x3a000000, v178
	v_mul_f32_e32 v33, 0x4b800000, v32
	v_cmp_gt_f32_e32 vcc, s17, v32
	s_nop 1
	v_cndmask_b32_e32 v32, v32, v33, vcc
	v_rsq_f32_e32 v32, v32
	s_nop 0
	v_mul_f32_e32 v33, 0x45800000, v32
	v_cndmask_b32_e32 v184, v32, v33, vcc
	v_pk_mul_f32 v[4:5], v[4:5], v[184:185] op_sel_hi:[1,0]
	v_pk_mul_f32 v[6:7], v[6:7], v[184:185] op_sel_hi:[1,0]
	v_pk_fma_f32 v[80:81], v[36:37], v[4:5], v[40:41]
	v_pk_fma_f32 v[76:77], v[38:39], v[6:7], v[42:43]
	v_cvt_pk_bf16_f32 v36, v80, v81
	v_add_co_u32_e32 v186, vcc, s44, v62
	v_cvt_pk_bf16_f32 v37, v76, v77
	ds_read_b128 v[4:7], v112 offset:1024
	ds_read_b128 v[32:35], v112 offset:9216
	v_addc_co_u32_e32 v187, vcc, 0, v63, vcc
	v_pk_mul_f32 v[8:9], v[8:9], v[184:185] op_sel_hi:[1,0]
	v_pk_mul_f32 v[10:11], v[10:11], v[184:185] op_sel_hi:[1,0]
	global_store_dwordx2 v[186:187], v[36:37], off
	s_waitcnt lgkmcnt(0)
	v_pk_fma_f32 v[74:75], v[6:7], v[10:11], v[34:35]
	v_pk_fma_f32 v[78:79], v[4:5], v[8:9], v[32:33]
	v_pk_mul_f32 v[12:13], v[12:13], v[184:185] op_sel_hi:[1,0]
	v_cvt_pk_bf16_f32 v10, v78, v79
	v_cvt_pk_bf16_f32 v11, v74, v75
	ds_read_b128 v[4:7], v112 offset:2048
	ds_read_b128 v[32:35], v112 offset:10240
	v_pk_mul_f32 v[14:15], v[14:15], v[184:185] op_sel_hi:[1,0]
	global_store_dwordx2 v[186:187], v[10:11], off offset:512
	v_pk_mul_f32 v[16:17], v[16:17], v[184:185] op_sel_hi:[1,0]
	v_pk_mul_f32 v[18:19], v[18:19], v[184:185] op_sel_hi:[1,0]
	s_waitcnt lgkmcnt(0)
	v_pk_fma_f32 v[68:69], v[6:7], v[14:15], v[34:35]
	v_pk_fma_f32 v[72:73], v[4:5], v[12:13], v[32:33]
	v_mov_b32_e32 v9, 0
	v_cvt_pk_bf16_f32 v14, v72, v73
	v_cvt_pk_bf16_f32 v15, v68, v69
	ds_read_b128 v[4:7], v112 offset:3072
	ds_read_b128 v[10:13], v112 offset:11264
	global_store_dwordx2 v[186:187], v[14:15], off offset:1024
	v_mov_b32_e32 v8, 0
	s_waitcnt lgkmcnt(0)
	v_pk_fma_f32 v[66:67], v[6:7], v[18:19], v[12:13]
	v_pk_fma_f32 v[70:71], v[4:5], v[16:17], v[10:11]
	v_pk_mul_f32 v[18:19], v[20:21], v[184:185] op_sel_hi:[1,0]
	v_cvt_pk_bf16_f32 v16, v70, v71
	v_cvt_pk_bf16_f32 v17, v66, v67
	ds_read_b128 v[4:7], v112 offset:4096
	ds_read_b128 v[12:15], v112 offset:12288
	v_pk_mul_f32 v[20:21], v[22:23], v[184:185] op_sel_hi:[1,0]
	global_store_dwordx2 v[186:187], v[16:17], off offset:1536
	v_mov_b32_e32 v11, 0
	v_mov_b32_e32 v10, 0
	s_waitcnt lgkmcnt(0)
; #define LAS __attribute__((address_space(3)))
; __device__ __forceinline__ unsigned cvt_pk_bf16(float lo, float hi) { unsigned r; asm volatile("v_cvt_pk_bf16_f32 %0, %1, %2" : "=v"(r) : "v"(lo), "v"(hi)); return r; }
; template <bool POST, bool PRE>
; __device__ __forceinline__ void row_core(const Params& P, const RowCfg& c, LAS float* vA, LAS float* vB, LAS float* vP, const bf16_t* RAW, const float* SSQ, bf16_t* H, int row, int lane, f32x4 (&v)[8]) {
;     ...
;         const u32x2* rs = (const u32x2*)(RAW + (size_t)row * DM) + lane;
;         float s = (lane < 32) ? SSQ[(size_t)row * 32 + lane] : 0.f; s = wave_sum(s);
;         const float rstd = rsqrtf(s * (1.0f / DM) + EPS);
;         f32x4* os = (f32x4*)(P.out + (size_t)row * DM) + lane;
; #pragma unroll
;         for (int j = 0; j < 8; ++j) { const u32x2 rb = rs[64 * j]; const f32x4 r = (f32x4){__uint_as_float(rb.x << 16), __uint_as_float(rb.x & 0xffff0000u), __uint_as_float(rb.y << 16), __uint_as_float(rb.y & 0xffff0000u)};
;             const f32x4 pv = *(const LAS f32x4*)(vP + j * 256 + lane * 4); v[j] += r * rstd * pv; os[64 * j] = v[j]; }
;     ...
;         const float rstd2 = rsqrtf(s2 * (1.0f / DM) + EPS);
;         u32x2* hs = (u32x2*)(H + (size_t)row * DM) + lane;
; #pragma unroll
;         for (int j = 0; j < 8; ++j) { const f32x4 a = *(const LAS f32x4*)(vA + j * 256 + lane * 4), b = *(const LAS f32x4*)(vB + j * 256 + lane * 4);
;             v[j] = v[j] * rstd2 * a + b; u32x2 w; w.x = cvt_pk_bf16(v[j][0], v[j][1]); w.y = cvt_pk_bf16(v[j][2], v[j][3]); hs[64 * j] = w; }
; template <bool POST, bool PRE, bool THIN>
; __device__ __forceinline__ void row_phase(const Ctx& F, const RowCfg c) {
;     ...
;             const int rowB = row + NGW; const bool hasB = rowB < SEQ;
;             row_core<POST, PRE>(P, c, vA, vB, vP, RAW, SSQ, H, row, lane, v0);
;             if (hasB) row_core<POST, PRE>(P, c, vA, vB, vP, RAW, SSQ, H, rowB, lane, v1);
	v_pk_fma_f32 v[42:43], v[6:7], v[20:21], v[14:15]
	v_pk_fma_f32 v[64:65], v[4:5], v[18:19], v[12:13]
	v_pk_mul_f32 v[18:19], v[24:25], v[184:185] op_sel_hi:[1,0]
	v_cvt_pk_bf16_f32 v16, v64, v65
	v_cvt_pk_bf16_f32 v17, v42, v43
	ds_read_b128 v[4:7], v112 offset:5120
	ds_read_b128 v[12:15], v112 offset:13312
	v_pk_mul_f32 v[20:21], v[26:27], v[184:185] op_sel_hi:[1,0]
	global_store_dwordx2 v[186:187], v[16:17], off offset:2048
	s_waitcnt lgkmcnt(0)
	v_pk_fma_f32 v[40:41], v[20:21], v[6:7], v[14:15]
	v_pk_fma_f32 v[62:63], v[18:19], v[4:5], v[12:13]
	v_pk_mul_f32 v[18:19], v[28:29], v[184:185] op_sel_hi:[1,0]
	v_cvt_pk_bf16_f32 v16, v62, v63
	v_cvt_pk_bf16_f32 v17, v40, v41
	ds_read_b128 v[4:7], v112 offset:6144
	ds_read_b128 v[12:15], v112 offset:14336
	v_pk_mul_f32 v[20:21], v[30:31], v[184:185] op_sel_hi:[1,0]
	global_store_dwordx2 v[186:187], v[16:17], off offset:2560
	s_waitcnt lgkmcnt(0)
	v_pk_fma_f32 v[34:35], v[20:21], v[6:7], v[14:15]
	v_pk_fma_f32 v[38:39], v[18:19], v[4:5], v[12:13]
	v_pk_mul_f32 v[18:19], v[180:181], v[184:185] op_sel_hi:[1,0]
	v_cvt_pk_bf16_f32 v16, v38, v39
	v_cvt_pk_bf16_f32 v17, v34, v35
	ds_read_b128 v[4:7], v112 offset:7168
	ds_read_b128 v[12:15], v112 offset:15360
	v_pk_mul_f32 v[20:21], v[182:183], v[184:185] op_sel_hi:[1,0]
	global_store_dwordx2 v[186:187], v[16:17], off offset:3072
	s_waitcnt lgkmcnt(0)
	v_pk_fma_f32 v[32:33], v[20:21], v[6:7], v[14:15]
	v_pk_fma_f32 v[36:37], v[18:19], v[4:5], v[12:13]
	s_nop 0
	v_cvt_pk_bf16_f32 v4, v36, v37
	v_cvt_pk_bf16_f32 v5, v32, v33
	global_store_dwordx2 v[186:187], v[4:5], off offset:3584
	s_cbranch_scc1 .LBB0_1509
	s_ashr_i32 s39, s38, 31
	s_lshl_b64 s[42:43], s[38:39], 13
	v_lshl_add_u64 v[82:83], v[44:45], 0, s[42:43]
	v_add_co_u32_e32 v0, vcc, 0x1000, v82
	global_load_dwordx4 v[8:11], v[82:83], off nt
	global_load_dwordx4 v[4:7], v[82:83], off offset:1024 nt
	global_load_dwordx4 v[16:19], v[82:83], off offset:2048 nt
	global_load_dwordx4 v[12:15], v[82:83], off offset:3072 nt
	v_addc_co_u32_e32 v1, vcc, 0, v83, vcc
	global_load_dwordx4 v[24:27], v[0:1], off nt
	global_load_dwordx4 v[20:23], v[0:1], off offset:1024 nt
	global_load_dwordx4 v[28:31], v[0:1], off offset:2048 nt
	s_nop 0
	global_load_dwordx4 v[0:3], v[0:1], off offset:3072 nt
	v_mov_b32_e32 v84, 0
	s_and_saveexec_b64 s[42:43], s[0:1]
	s_cbranch_execz .LBB0_1508
	s_lshl_b64 s[46:47], s[38:39], 7
	v_lshl_add_u64 v[84:85], v[46:47], 0, s[46:47]
	global_load_dword v84, v[84:85], off
.LBB0_1508:
	s_or_b64 exec, exec, s[42:43]
	s_lshl_b64 s[42:43], s[38:39], 11
	s_lshl_b64 s[42:43], s[42:43], 1
	v_lshl_add_u64 v[86:87], v[48:49], 0, s[42:43]
	global_load_dwordx2 v[96:97], v[86:87], off nt
	s_waitcnt vmcnt(1)
	ds_bpermute_b32 v85, v106, v84
	ds_read_b128 v[88:91], v112 offset:16384
	ds_read_b128 v[92:95], v112 offset:17408
	v_lshl_add_u64 v[186:187], v[50:51], 0, s[42:43]
	s_waitcnt lgkmcnt(2)
	v_add_f32_e32 v84, v84, v85
	ds_bpermute_b32 v85, v107, v84
	s_waitcnt lgkmcnt(0)
	v_add_f32_e32 v84, v84, v85
	ds_bpermute_b32 v85, v108, v84
	s_waitcnt lgkmcnt(0)
	v_add_f32_e32 v84, v84, v85
	ds_bpermute_b32 v85, v109, v84
	s_waitcnt lgkmcnt(0)
	v_add_f32_e32 v84, v84, v85
	ds_bpermute_b32 v85, v110, v84
	s_waitcnt lgkmcnt(0)
	v_add_f32_e32 v84, v84, v85
	ds_bpermute_b32 v85, v111, v84
	s_waitcnt lgkmcnt(0)
	v_add_f32_e32 v84, v84, v85
	v_fmamk_f32 v84, v84, 0x3a000000, v178
	v_mul_f32_e32 v85, 0x4b800000, v84
	v_cmp_gt_f32_e32 vcc, s17, v84
	s_waitcnt vmcnt(0)
	v_lshlrev_b32_e32 v98, 16, v96
	v_cndmask_b32_e32 v84, v84, v85, vcc
	v_rsq_f32_e32 v84, v84
	v_and_b32_e32 v99, 0xffff0000, v96
	v_lshlrev_b32_e32 v96, 16, v97
	v_and_b32_e32 v97, 0xffff0000, v97
	v_mul_f32_e32 v85, 0x45800000, v84
	v_cndmask_b32_e32 v84, v84, v85, vcc
	v_pk_mul_f32 v[98:99], v[84:85], v[98:99] op_sel_hi:[0,1]
	v_pk_mul_f32 v[96:97], v[84:85], v[96:97] op_sel_hi:[0,1]
	v_pk_fma_f32 v[10:11], v[90:91], v[96:97], v[10:11]
	v_pk_fma_f32 v[8:9], v[88:89], v[98:99], v[8:9]
	global_store_dwordx4 v[82:83], v[8:11], off nt
	global_load_dwordx2 v[88:89], v[86:87], off offset:512 nt
	s_waitcnt vmcnt(0)
	v_lshlrev_b32_e32 v90, 16, v88
	v_and_b32_e32 v91, 0xffff0000, v88
	v_lshlrev_b32_e32 v88, 16, v89
	v_and_b32_e32 v89, 0xffff0000, v89
	v_pk_mul_f32 v[90:91], v[84:85], v[90:91] op_sel_hi:[0,1]
	v_pk_mul_f32 v[88:89], v[84:85], v[88:89] op_sel_hi:[0,1]
	v_pk_fma_f32 v[6:7], v[94:95], v[88:89], v[6:7]
	v_pk_fma_f32 v[4:5], v[92:93], v[90:91], v[4:5]
	global_store_dwordx4 v[82:83], v[4:7], off offset:1024 nt
	global_load_dwordx2 v[96:97], v[86:87], off offset:1024 nt
	ds_read_b128 v[88:91], v112 offset:18432
	ds_read_b128 v[92:95], v112 offset:19456
	s_waitcnt vmcnt(0)
	v_lshlrev_b32_e32 v98, 16, v96
	v_and_b32_e32 v99, 0xffff0000, v96
	v_lshlrev_b32_e32 v96, 16, v97
	v_and_b32_e32 v97, 0xffff0000, v97
	v_pk_mul_f32 v[98:99], v[84:85], v[98:99] op_sel_hi:[0,1]
	v_pk_mul_f32 v[96:97], v[84:85], v[96:97] op_sel_hi:[0,1]
	s_waitcnt lgkmcnt(1)
	v_pk_fma_f32 v[18:19], v[90:91], v[96:97], v[18:19]
	v_pk_fma_f32 v[16:17], v[88:89], v[98:99], v[16:17]
	global_store_dwordx4 v[82:83], v[16:19], off offset:2048 nt
	global_load_dwordx2 v[88:89], v[86:87], off offset:1536 nt
	v_lshl_add_u64 v[98:99], v[82:83], 0, s[24:25]
	s_waitcnt vmcnt(0)
	v_lshlrev_b32_e32 v90, 16, v88
	v_and_b32_e32 v91, 0xffff0000, v88
	v_lshlrev_b32_e32 v88, 16, v89
	v_and_b32_e32 v89, 0xffff0000, v89
	v_pk_mul_f32 v[90:91], v[84:85], v[90:91] op_sel_hi:[0,1]
	v_pk_mul_f32 v[88:89], v[84:85], v[88:89] op_sel_hi:[0,1]
	s_waitcnt lgkmcnt(0)
; #define LAS __attribute__((address_space(3)))
; template <bool POST, bool PRE>
; __device__ __forceinline__ void row_core(const Params& P, const RowCfg& c, LAS float* vA, LAS float* vB, LAS float* vP, const bf16_t* RAW, const float* SSQ, bf16_t* H, int row, int lane, f32x4 (&v)[8]) {
;     ...
;         const u32x2* rs = (const u32x2*)(RAW + (size_t)row * DM) + lane;
;         float s = (lane < 32) ? SSQ[(size_t)row * 32 + lane] : 0.f; s = wave_sum(s);
;         const float rstd = rsqrtf(s * (1.0f / DM) + EPS);
;         f32x4* os = (f32x4*)(P.out + (size_t)row * DM) + lane;
; #pragma unroll
;         for (int j = 0; j < 8; ++j) { const u32x2 rb = rs[64 * j]; const f32x4 r = (f32x4){__uint_as_float(rb.x << 16), __uint_as_float(rb.x & 0xffff0000u), __uint_as_float(rb.y << 16), __uint_as_float(rb.y & 0xffff0000u)};
;             const f32x4 pv = *(const LAS f32x4*)(vP + j * 256 + lane * 4); v[j] += r * rstd * pv; os[64 * j] = v[j]; }
;     }
;     if (PRE) {
;         float s2 = 0.f;
; #pragma unroll
;         for (int j = 0; j < 8; ++j) s2 += (v[j][0] * v[j][0] + v[j][1] * v[j][1]) + (v[j][2] * v[j][2] + v[j][3] * v[j][3]);
;         s2 = wave_sum(s2);
	v_pk_fma_f32 v[14:15], v[94:95], v[88:89], v[14:15]
	v_pk_fma_f32 v[12:13], v[92:93], v[90:91], v[12:13]
	global_store_dwordx4 v[82:83], v[12:15], off offset:3072 nt
	global_load_dwordx2 v[96:97], v[86:87], off offset:2048 nt
	ds_read_b128 v[88:91], v112 offset:20480
	ds_read_b128 v[92:95], v112 offset:21504
	s_waitcnt vmcnt(0)
	v_lshlrev_b32_e32 v100, 16, v96
	v_and_b32_e32 v101, 0xffff0000, v96
	v_lshlrev_b32_e32 v96, 16, v97
	v_and_b32_e32 v97, 0xffff0000, v97
	v_pk_mul_f32 v[100:101], v[84:85], v[100:101] op_sel_hi:[0,1]
	v_pk_mul_f32 v[96:97], v[84:85], v[96:97] op_sel_hi:[0,1]
	s_waitcnt lgkmcnt(1)
	v_pk_fma_f32 v[26:27], v[90:91], v[96:97], v[26:27]
	v_pk_fma_f32 v[24:25], v[88:89], v[100:101], v[24:25]
	global_store_dwordx4 v[98:99], v[24:27], off nt
	global_load_dwordx2 v[88:89], v[86:87], off offset:2560 nt
	v_lshl_add_u64 v[90:91], v[82:83], 0, s[30:31]
	v_lshl_add_u64 v[98:99], v[82:83], 0, s[34:35]
	s_waitcnt vmcnt(0)
	v_lshlrev_b32_e32 v96, 16, v88
	v_and_b32_e32 v97, 0xffff0000, v88
	v_lshlrev_b32_e32 v88, 16, v89
	v_and_b32_e32 v89, 0xffff0000, v89
	v_pk_mul_f32 v[96:97], v[84:85], v[96:97] op_sel_hi:[0,1]
	v_pk_mul_f32 v[88:89], v[84:85], v[88:89] op_sel_hi:[0,1]
	s_waitcnt lgkmcnt(0)
	v_pk_fma_f32 v[22:23], v[94:95], v[88:89], v[22:23]
	v_pk_fma_f32 v[20:21], v[92:93], v[96:97], v[20:21]
	global_store_dwordx4 v[90:91], v[20:23], off nt
	global_load_dwordx2 v[96:97], v[86:87], off offset:3072 nt
	ds_read_b128 v[88:91], v112 offset:22528
	ds_read_b128 v[92:95], v112 offset:23552
	s_waitcnt vmcnt(0)
	v_lshlrev_b32_e32 v100, 16, v96
	v_and_b32_e32 v101, 0xffff0000, v96
	v_lshlrev_b32_e32 v96, 16, v97
	v_and_b32_e32 v97, 0xffff0000, v97
	v_pk_mul_f32 v[100:101], v[84:85], v[100:101] op_sel_hi:[0,1]
	v_pk_mul_f32 v[96:97], v[84:85], v[96:97] op_sel_hi:[0,1]
	s_waitcnt lgkmcnt(1)
	v_pk_fma_f32 v[30:31], v[90:91], v[96:97], v[30:31]
	v_pk_fma_f32 v[28:29], v[88:89], v[100:101], v[28:29]
	global_store_dwordx4 v[98:99], v[28:31], off nt
	global_load_dwordx2 v[86:87], v[86:87], off offset:3584 nt
	v_mov_b32_e32 v90, v9
	v_mov_b32_e32 v98, v11
	v_mov_b32_e32 v91, v5
	v_mov_b32_e32 v99, v7
	v_mov_b32_e32 v88, v8
	v_mov_b32_e32 v96, v10
	v_mov_b32_e32 v89, v4
	v_mov_b32_e32 v97, v6
	v_pk_mul_f32 v[90:91], v[90:91], v[90:91]
	v_pk_mul_f32 v[98:99], v[98:99], v[98:99]
	v_pk_fma_f32 v[88:89], v[88:89], v[88:89], v[90:91]
	v_pk_fma_f32 v[90:91], v[96:97], v[96:97], v[98:99]
	v_pk_mul_f32 v[96:97], v[16:17], v[16:17]
	v_pk_add_f32 v[88:89], v[88:89], v[90:91]
	v_pk_mul_f32 v[90:91], v[18:19], v[18:19]
	v_pk_add_f32 v[88:89], v[88:89], v[88:89] op_sel:[0,1] op_sel_hi:[1,0]
	v_pk_mov_b32 v[98:99], v[96:97], v[90:91] op_sel:[1,0]
	v_mov_b32_e32 v97, v91
	v_pk_add_f32 v[90:91], v[98:99], v[96:97]
	v_mul_f32_e32 v96, v13, v13
	v_mul_f32_e32 v98, v15, v15
	v_pk_add_f32 v[90:91], v[90:91], v[90:91] op_sel:[0,1] op_sel_hi:[1,0]
	v_pk_fma_f32 v[96:97], v[12:13], v[12:13], v[96:97] op_sel_hi:[1,1,0]
	v_pk_fma_f32 v[98:99], v[14:15], v[14:15], v[98:99] op_sel_hi:[1,1,0]
	v_mul_f32_e32 v89, v24, v24
	v_mul_f32_e32 v91, v25, v25
	v_mul_f32_e32 v97, v26, v26
	v_mul_f32_e32 v99, v27, v27
	v_pk_add_f32 v[88:89], v[88:89], v[90:91]
	v_pk_add_f32 v[90:91], v[96:97], v[98:99]
	v_pk_mul_f32 v[96:97], v[20:21], v[20:21]
	v_pk_add_f32 v[88:89], v[88:89], v[90:91]
	v_pk_mul_f32 v[90:91], v[22:23], v[22:23]
	v_pk_add_f32 v[88:89], v[88:89], v[88:89] op_sel:[0,1] op_sel_hi:[1,0]
	v_pk_mov_b32 v[98:99], v[96:97], v[90:91] op_sel:[1,0]
	v_mov_b32_e32 v97, v91
	v_pk_add_f32 v[90:91], v[98:99], v[96:97]
	v_mul_f32_e32 v96, v29, v29
	v_mul_f32_e32 v98, v31, v31
	v_pk_add_f32 v[90:91], v[90:91], v[90:91] op_sel:[0,1] op_sel_hi:[1,0]
	v_pk_fma_f32 v[96:97], v[28:29], v[28:29], v[96:97] op_sel_hi:[1,1,0]
	v_pk_fma_f32 v[98:99], v[30:31], v[30:31], v[98:99] op_sel_hi:[1,1,0]
	s_waitcnt vmcnt(0)
	v_lshlrev_b32_e32 v100, 16, v86
	v_and_b32_e32 v101, 0xffff0000, v86
	v_lshlrev_b32_e32 v86, 16, v87
	v_and_b32_e32 v87, 0xffff0000, v87
	v_pk_mul_f32 v[100:101], v[84:85], v[100:101] op_sel_hi:[0,1]
	v_pk_mul_f32 v[84:85], v[84:85], v[86:87] op_sel_hi:[0,1]
	s_waitcnt lgkmcnt(0)
	v_pk_fma_f32 v[182:183], v[94:95], v[84:85], v[2:3]
	v_pk_fma_f32 v[180:181], v[92:93], v[100:101], v[0:1]
	v_mul_f32_e32 v97, v182, v182
	v_mul_f32_e32 v89, v180, v180
	v_mul_f32_e32 v91, v181, v181
	v_mul_f32_e32 v99, v183, v183
	v_pk_add_f32 v[0:1], v[88:89], v[90:91]
	v_pk_add_f32 v[2:3], v[96:97], v[98:99]
	v_lshl_add_u64 v[86:87], v[82:83], 0, s[36:37]
	v_pk_add_f32 v[0:1], v[0:1], v[2:3]
	s_nop 0
	v_add_f32_e32 v0, v0, v1
	ds_bpermute_b32 v1, v106, v0
	s_waitcnt lgkmcnt(0)
; #define LAS __attribute__((address_space(3)))
; __device__ __forceinline__ unsigned cvt_pk_bf16(float lo, float hi) { unsigned r; asm volatile("v_cvt_pk_bf16_f32 %0, %1, %2" : "=v"(r) : "v"(lo), "v"(hi)); return r; }
; template <bool POST, bool PRE>
; __device__ __forceinline__ void row_core(const Params& P, const RowCfg& c, LAS float* vA, LAS float* vB, LAS float* vP, const bf16_t* RAW, const float* SSQ, bf16_t* H, int row, int lane, f32x4 (&v)[8]) {
;     ...
;             const f32x4 pv = *(const LAS f32x4*)(vP + j * 256 + lane * 4); v[j] += r * rstd * pv; os[64 * j] = v[j]; }
;     }
;     if (PRE) {
;         float s2 = 0.f;
; #pragma unroll
;         for (int j = 0; j < 8; ++j) s2 += (v[j][0] * v[j][0] + v[j][1] * v[j][1]) + (v[j][2] * v[j][2] + v[j][3] * v[j][3]);
;         s2 = wave_sum(s2);
;         const float rstd2 = rsqrtf(s2 * (1.0f / DM) + EPS);
;         u32x2* hs = (u32x2*)(H + (size_t)row * DM) + lane;
; #pragma unroll
;         for (int j = 0; j < 8; ++j) { const f32x4 a = *(const LAS f32x4*)(vA + j * 256 + lane * 4), b = *(const LAS f32x4*)(vB + j * 256 + lane * 4);
;             v[j] = v[j] * rstd2 * a + b; u32x2 w; w.x = cvt_pk_bf16(v[j][0], v[j][1]); w.y = cvt_pk_bf16(v[j][2], v[j][3]); hs[64 * j] = w; }
	v_add_f32_e32 v0, v0, v1
	ds_bpermute_b32 v1, v107, v0
	s_waitcnt lgkmcnt(0)
	v_add_f32_e32 v0, v0, v1
	ds_bpermute_b32 v1, v108, v0
	s_waitcnt lgkmcnt(0)
	v_add_f32_e32 v0, v0, v1
	ds_bpermute_b32 v1, v109, v0
	s_waitcnt lgkmcnt(0)
	v_add_f32_e32 v0, v0, v1
	ds_bpermute_b32 v1, v110, v0
	s_waitcnt lgkmcnt(0)
	v_add_f32_e32 v0, v0, v1
	ds_bpermute_b32 v1, v111, v0
	s_waitcnt lgkmcnt(0)
	v_add_f32_e32 v0, v0, v1
	v_fmamk_f32 v0, v0, 0x3a000000, v178
	v_mul_f32_e32 v1, 0x4b800000, v0
	v_cmp_gt_f32_e32 vcc, s17, v0
	s_nop 1
	v_cndmask_b32_e32 v0, v0, v1, vcc
	v_rsq_f32_e32 v88, v0
	ds_read_b128 v[0:3], v112
	ds_read_b128 v[82:85], v112 offset:8192
	global_store_dwordx4 v[86:87], v[180:183], off nt
	v_mul_f32_e32 v86, 0x45800000, v88
	v_cndmask_b32_e32 v184, v88, v86, vcc
	v_pk_mul_f32 v[86:87], v[8:9], v[184:185] op_sel_hi:[1,0]
	v_pk_mul_f32 v[8:9], v[10:11], v[184:185] op_sel_hi:[1,0]
	s_waitcnt lgkmcnt(0)
	v_pk_fma_f32 v[10:11], v[0:1], v[86:87], v[82:83]
	v_pk_fma_f32 v[8:9], v[2:3], v[8:9], v[84:85]
	v_cvt_pk_bf16_f32 v86, v10, v11
	v_pk_mul_f32 v[4:5], v[4:5], v[184:185] op_sel_hi:[1,0]
	v_cvt_pk_bf16_f32 v87, v8, v9
	ds_read_b128 v[0:3], v112 offset:1024
	ds_read_b128 v[82:85], v112 offset:9216
	v_pk_mul_f32 v[6:7], v[6:7], v[184:185] op_sel_hi:[1,0]
	global_store_dwordx2 v[186:187], v[86:87], off
	v_pk_mul_f32 v[16:17], v[16:17], v[184:185] op_sel_hi:[1,0]
	v_pk_mul_f32 v[18:19], v[18:19], v[184:185] op_sel_hi:[1,0]
	s_waitcnt lgkmcnt(0)
	v_pk_fma_f32 v[102:103], v[2:3], v[6:7], v[84:85]
	v_pk_fma_f32 v[104:105], v[0:1], v[4:5], v[82:83]
	v_pk_mul_f32 v[12:13], v[12:13], v[184:185] op_sel_hi:[1,0]
	v_cvt_pk_bf16_f32 v82, v104, v105
	v_cvt_pk_bf16_f32 v83, v102, v103
	ds_read_b128 v[0:3], v112 offset:2048
	ds_read_b128 v[4:7], v112 offset:10240
	global_store_dwordx2 v[186:187], v[82:83], off offset:512
	v_pk_mul_f32 v[14:15], v[14:15], v[184:185] op_sel_hi:[1,0]
	s_waitcnt lgkmcnt(0)
	v_pk_fma_f32 v[96:97], v[2:3], v[18:19], v[6:7]
	v_pk_fma_f32 v[100:101], v[0:1], v[16:17], v[4:5]
	v_pk_mul_f32 v[18:19], v[182:183], v[184:185] op_sel_hi:[1,0]
	v_cvt_pk_bf16_f32 v16, v100, v101
	v_cvt_pk_bf16_f32 v17, v96, v97
	ds_read_b128 v[0:3], v112 offset:3072
	ds_read_b128 v[4:7], v112 offset:11264
	global_store_dwordx2 v[186:187], v[16:17], off offset:1024
	v_pk_mul_f32 v[16:17], v[26:27], v[184:185] op_sel_hi:[1,0]
	s_waitcnt lgkmcnt(0)
	v_pk_fma_f32 v[94:95], v[2:3], v[14:15], v[6:7]
	v_pk_fma_f32 v[98:99], v[0:1], v[12:13], v[4:5]
	v_pk_mul_f32 v[14:15], v[24:25], v[184:185] op_sel_hi:[1,0]
	v_cvt_pk_bf16_f32 v12, v98, v99
	v_cvt_pk_bf16_f32 v13, v94, v95
	ds_read_b128 v[0:3], v112 offset:4096
	ds_read_b128 v[4:7], v112 offset:12288
	global_store_dwordx2 v[186:187], v[12:13], off offset:1536
	s_waitcnt lgkmcnt(0)
	v_pk_fma_f32 v[88:89], v[2:3], v[16:17], v[6:7]
	v_pk_fma_f32 v[92:93], v[0:1], v[14:15], v[4:5]
	v_pk_mul_f32 v[14:15], v[20:21], v[184:185] op_sel_hi:[1,0]
	v_cvt_pk_bf16_f32 v12, v92, v93
	v_cvt_pk_bf16_f32 v13, v88, v89
	ds_read_b128 v[0:3], v112 offset:5120
	ds_read_b128 v[4:7], v112 offset:13312
	v_pk_mul_f32 v[16:17], v[22:23], v[184:185] op_sel_hi:[1,0]
	global_store_dwordx2 v[186:187], v[12:13], off offset:2048
	s_waitcnt lgkmcnt(0)
	v_pk_fma_f32 v[86:87], v[16:17], v[2:3], v[6:7]
	v_pk_fma_f32 v[90:91], v[14:15], v[0:1], v[4:5]
	v_pk_mul_f32 v[6:7], v[28:29], v[184:185] op_sel_hi:[1,0]
	v_cvt_pk_bf16_f32 v0, v90, v91
	v_cvt_pk_bf16_f32 v1, v86, v87
	ds_read_b128 v[2:5], v112 offset:6144
	ds_read_b128 v[12:15], v112 offset:14336
	v_pk_mul_f32 v[16:17], v[30:31], v[184:185] op_sel_hi:[1,0]
	global_store_dwordx2 v[186:187], v[0:1], off offset:2560
	s_waitcnt lgkmcnt(0)
	v_pk_fma_f32 v[0:1], v[16:17], v[4:5], v[14:15]
	v_pk_fma_f32 v[84:85], v[6:7], v[2:3], v[12:13]
	v_pk_mul_f32 v[16:17], v[180:181], v[184:185] op_sel_hi:[1,0]
	v_cvt_pk_bf16_f32 v6, v84, v85
	v_cvt_pk_bf16_f32 v7, v0, v1
	ds_read_b128 v[2:5], v112 offset:7168
	ds_read_b128 v[12:15], v112 offset:15360
	global_store_dwordx2 v[186:187], v[6:7], off offset:3072
	s_waitcnt lgkmcnt(0)
	v_pk_fma_f32 v[82:83], v[18:19], v[4:5], v[14:15]
	v_pk_fma_f32 v[2:3], v[16:17], v[2:3], v[12:13]
	s_nop 0
	v_cvt_pk_bf16_f32 v4, v2, v3
	v_cvt_pk_bf16_f32 v5, v82, v83
	global_store_dwordx2 v[186:187], v[4:5], off offset:3584

; __device__ __forceinline__ void gla_finalize(const Ctx& F) {
;     ...
;     for (int row = gw; row < SEQ; row += NGW) {
;         f32x4 o[8]; const u32x4* op0 = (const u32x4*)(O + ((size_t)(lane * 2) * SEQ + row) * 16); const u32x4* op1 = (const u32x4*)(O + ((size_t)(lane * 2 + 1) * SEQ + row) * 16); float ss = 0.f;
;         const u32x4 ob[4] = {op0[0], op0[1], op1[0], op1[1]};
; #pragma unroll
;         for (int i = 0; i < 8; ++i) { const u32x4 q4 = ob[i >> 1]; const unsigned w0 = (i & 1) ? q4.z : q4.x, w1 = (i & 1) ? q4.w : q4.y;
;             o[i] = (f32x4){__uint_as_float(w0 << 16), __uint_as_float(w0 & 0xffff0000u), __uint_as_float(w1 << 16), __uint_as_float(w1 & 0xffff0000u)}; ss += (o[i][0] * o[i][0] + o[i][1] * o[i][1]) + (o[i][2] * o[i][2] + o[i][3] * o[i][3]); }
;         ss += __shfl_xor(ss, 1); ss += __shfl_xor(ss, 2); ss += __shfl_xor(ss, 4); ss += __shfl_xor(ss, 8);
;         const float rstd = rsqrtf(ss * (1.0f / 512.0f) + EPS);
;         const u32x4* rp = (const u32x4*)(Y1 + (size_t)row * 6144 + 4096 + lane * 32); u32x4* cp = (u32x4*)(CAT + (size_t)row * 2048 + lane * 32);
.LBB0_1904:
	v_lshl_add_u64 v[20:21], s[92:93], 0, v[18:19]
	v_lshl_add_u64 v[8:9], s[92:93], 0, v[16:17]
	v_add_co_u32_e32 v54, vcc, 0xac00000, v20
	v_add_co_u32_e64 v58, s[0:1], s7, v8
	v_lshl_add_u64 v[10:11], s[92:93], 0, v[14:15]
	s_nop 0
	v_addc_co_u32_e64 v59, s[0:1], 0, v9, s[0:1]
	v_addc_co_u32_e32 v55, vcc, 0, v21, vcc
	v_lshl_add_u64 v[28:29], v[20:21], 0, s[16:17]
	v_lshl_add_u64 v[52:53], v[20:21], 0, s[18:19]
	v_add_co_u32_e64 v22, s[0:1], s23, v10
	v_add_co_u32_e32 v20, vcc, 0xac80000, v20
	v_mov_b32_e32 v0, v164
	v_mov_b32_e32 v1, v165
	v_mov_b32_e32 v2, v166
	v_mov_b32_e32 v3, v167
	v_mov_b32_e32 v4, v160
	v_mov_b32_e32 v5, v161
	v_mov_b32_e32 v6, v162
	v_mov_b32_e32 v7, v163
	v_lshl_add_u64 v[56:57], v[8:9], 0, s[20:21]
	v_addc_co_u32_e64 v23, s[0:1], 0, v11, s[0:1]
	global_load_dwordx4 v[24:27], v[28:29], off offset:16 nt
	global_load_dwordx4 v[44:47], v[52:53], off offset:16 nt
	global_load_dwordx4 v[30:33], v[58:59], off nt
	global_load_dwordx4 v[34:37], v[56:57], off offset:16 nt
	global_load_dwordx4 v[48:51], v[56:57], off offset:32 nt
	global_load_dwordx4 v[8:11], v[56:57], off offset:48 nt
	v_addc_co_u32_e32 v21, vcc, 0, v21, vcc
	global_load_dwordx4 v[52:55], v[54:55], off nt
	s_add_i32 s6, s6, s8
	global_load_dwordx4 v[56:59], v[20:21], off nt
	v_lshl_add_u64 v[14:15], v[14:15], 0, s[10:11]
	v_lshl_add_u64 v[16:17], v[16:17], 0, s[12:13]
	v_lshl_add_u64 v[18:19], v[18:19], 0, s[14:15]
	s_cmpk_lt_i32 s6, 0x4000
	s_waitcnt vmcnt(9)
	v_mov_b32_e32 v62, v0
	s_waitcnt vmcnt(8)
	v_mov_b32_e32 v60, v4
	s_waitcnt vmcnt(7)
	v_and_b32_e32 v70, 0xffff0000, v26
	s_waitcnt vmcnt(6)
	v_lshlrev_b32_e32 v4, 16, v44
	v_and_b32_e32 v0, 0xffff0000, v44
	v_lshlrev_b32_e32 v28, 16, v45
	s_waitcnt vmcnt(5)
	v_and_b32_e32 v75, 0xffff0000, v31
	v_lshlrev_b32_e32 v76, 16, v32
	v_lshlrev_b32_e32 v20, 16, v46
	s_waitcnt vmcnt(1)
	v_lshlrev_b32_e32 v93, 16, v53
	v_lshlrev_b32_e32 v92, 16, v52
	v_and_b32_e32 v53, 0xffff0000, v53
	v_and_b32_e32 v52, 0xffff0000, v52
	v_lshlrev_b32_e32 v95, 16, v55
	v_lshlrev_b32_e32 v94, 16, v54
	v_and_b32_e32 v55, 0xffff0000, v55
	v_and_b32_e32 v54, 0xffff0000, v54
	v_lshlrev_b32_e32 v65, 16, v25
	v_lshlrev_b32_e32 v64, 16, v24
	v_and_b32_e32 v67, 0xffff0000, v25
	v_and_b32_e32 v66, 0xffff0000, v24
	v_lshlrev_b32_e32 v68, 16, v26
	v_lshlrev_b32_e32 v72, 16, v27
	v_and_b32_e32 v29, 0xffff0000, v45
	v_lshlrev_b32_e32 v81, 16, v35
	v_lshlrev_b32_e32 v80, 16, v34
	v_and_b32_e32 v83, 0xffff0000, v35
	v_and_b32_e32 v82, 0xffff0000, v34
	v_lshlrev_b32_e32 v85, 16, v37
	v_lshlrev_b32_e32 v84, 16, v36
	v_and_b32_e32 v87, 0xffff0000, v37
	v_and_b32_e32 v86, 0xffff0000, v36
	v_lshlrev_b32_e32 v35, 16, v51
	v_lshlrev_b32_e32 v34, 16, v50
	v_and_b32_e32 v37, 0xffff0000, v51
	v_and_b32_e32 v36, 0xffff0000, v50
	v_lshlrev_b32_e32 v21, 16, v47
	v_and_b32_e32 v25, 0xffff0000, v47
	v_and_b32_e32 v24, 0xffff0000, v46
	v_mul_f32_e32 v51, v70, v70
	v_mul_f32_e32 v89, v4, v4
	v_mul_f32_e32 v91, v0, v0
	v_mul_f32_e32 v50, v28, v28
	v_mul_f32_e32 v104, 0xbfb8aa3b, v75
	v_mul_f32_e32 v112, 0xbfb8aa3b, v76
	v_mov_b32_e32 v88, v20
	v_mov_b32_e32 v90, v20
	s_waitcnt vmcnt(0)
	v_lshlrev_b32_e32 v101, 16, v59
	v_lshlrev_b32_e32 v100, 16, v58
	v_and_b32_e32 v59, 0xffff0000, v59
	v_and_b32_e32 v58, 0xffff0000, v58
	v_mov_b32_e32 v106, v52
	v_mov_b32_e32 v107, v54
	v_mov_b32_e32 v110, v53
	v_mov_b32_e32 v111, v55
	v_and_b32_e32 v73, 0xffff0000, v27
	v_lshlrev_b32_e32 v45, 16, v31
	v_lshlrev_b32_e32 v44, 16, v30
	v_and_b32_e32 v74, 0xffff0000, v30
	v_lshlrev_b32_e32 v77, 16, v33
	v_and_b32_e32 v79, 0xffff0000, v33
	v_and_b32_e32 v78, 0xffff0000, v32
	v_lshlrev_b32_e32 v31, 16, v49
	v_lshlrev_b32_e32 v30, 16, v48
	v_and_b32_e32 v33, 0xffff0000, v49
	v_and_b32_e32 v32, 0xffff0000, v48
	v_mul_f32_e32 v49, v68, v68
	v_mul_f32_e32 v48, v72, v72
	v_pk_mul_f32 v[96:97], v[24:25], v[24:25]
	v_pk_mul_f32 v[98:99], v[20:21], v[20:21]
	v_pk_fma_f32 v[102:103], v[28:29], v[28:29], v[50:51] op_sel_hi:[1,1,0]
	v_exp_f32_e32 v132, v104
	v_mov_b32_e32 v104, v92
	v_mov_b32_e32 v105, v94
	v_mov_b32_e32 v108, v93
	v_mov_b32_e32 v109, v95
	v_exp_f32_e32 v133, v112
	v_lshlrev_b32_e32 v112, 16, v56
	v_pk_add_f32 v[88:89], v[88:89], v[90:91]
	v_pk_mul_f32 v[90:91], v[58:59], v[58:59]
	v_pk_mul_f32 v[106:107], v[106:107], v[106:107]
	v_pk_mul_f32 v[110:111], v[110:111], v[110:111]
	v_mov_b32_e32 v69, v72
	v_mov_b32_e32 v71, v73
	v_pk_fma_f32 v[72:73], v[72:73], v[72:73], v[48:49] op_sel_hi:[1,1,0]
	v_mov_b32_e32 v48, v112
	v_mov_b32_e32 v50, v112
	v_mov_b32_e32 v88, v98
	v_mov_b32_e32 v102, v96
	v_pk_fma_f32 v[90:91], v[100:101], v[100:101], v[90:91]
	v_pk_fma_f32 v[104:105], v[104:105], v[104:105], v[106:107]
	v_pk_fma_f32 v[106:107], v[108:109], v[108:109], v[110:111]
	v_pk_mul_f32 v[46:47], v[66:67], v[66:67]
	v_mul_f32_e32 v113, 0xbfb8aa3b, v78
	v_pk_add_f32 v[48:49], v[48:49], v[50:51]
	v_pk_add_f32 v[50:51], v[88:89], v[102:103]
	v_pk_add_f32 v[88:89], v[90:91], v[90:91] op_sel_hi:[0,1]
	v_pk_add_f32 v[90:91], v[104:105], v[106:107]
	v_mul_f32_e32 v114, 0xbfb8aa3b, v77
	v_mul_f32_e32 v115, 0xbfb8aa3b, v79
	v_mul_f32_e32 v116, 0xbfb8aa3b, v80
	v_mul_f32_e32 v117, 0xbfb8aa3b, v82
	v_pk_fma_f32 v[46:47], v[64:65], v[64:65], v[46:47]
	v_exp_f32_e32 v134, v113
	v_lshlrev_b32_e32 v113, 16, v57
	v_and_b32_e32 v57, 0xffff0000, v57
	v_and_b32_e32 v56, 0xffff0000, v56
	v_pk_add_f32 v[90:91], v[90:91], v[90:91] op_sel_hi:[0,1]
	v_exp_f32_e32 v135, v114
	v_exp_f32_e32 v136, v115
	v_exp_f32_e32 v137, v116
	v_exp_f32_e32 v138, v117
	v_pk_add_f32 v[46:47], v[46:47], v[46:47] op_sel_hi:[0,1]
	v_pk_mul_f32 v[114:115], v[56:57], v[56:57]
	v_pk_mul_f32 v[116:117], v[112:113], v[112:113]
	v_add_f32_e32 v90, 1.0, v133
	v_mov_b32_e32 v72, v114
	v_mov_b32_e32 v46, v115
	v_mov_b32_e32 v48, v116
	v_rcp_f32_e32 v102, v90
	v_mov_b32_e32 v90, v117
	v_mov_b32_e32 v63, v2
	v_mov_b32_e32 v2, v1
	v_mul_f32_e32 v1, 0xbfb8aa3b, v44
	v_pk_add_f32 v[48:49], v[48:49], v[72:73]
	v_pk_add_f32 v[46:47], v[90:91], v[46:47]
	v_mov_b32_e32 v61, v6
	v_mov_b32_e32 v6, v5
	v_mul_f32_e32 v5, 0xbfb8aa3b, v74
	v_exp_f32_e32 v1, v1
	v_pk_add_f32 v[46:47], v[48:49], v[46:47]
	v_exp_f32_e32 v5, v5
	v_pk_add_f32 v[46:47], v[46:47], v[46:47] op_sel_hi:[0,1]
	v_mov_b32_e32 v88, v99
	v_mov_b32_e32 v46, v97
	v_pk_add_f32 v[46:47], v[88:89], v[46:47]
	v_add_f32_e32 v1, 1.0, v1
	v_pk_add_f32 v[46:47], v[50:51], v[46:47]
	v_add_f32_e32 v5, 1.0, v5
	v_rcp_f32_e32 v72, v1
	v_add_f32_e32 v1, v46, v47
	v_rcp_f32_e32 v98, v5
	ds_bpermute_b32 v5, v38, v1
	v_mul_f32_e32 v43, 0xbfb8aa3b, v45
	v_mul_f32_e32 v118, 0xbfb8aa3b, v81
	v_mul_f32_e32 v119, 0xbfb8aa3b, v83
	v_mul_f32_e32 v120, 0xbfb8aa3b, v84
	s_waitcnt lgkmcnt(0)
; __device__ __forceinline__ unsigned pk2(float lo, float hi) { return f2bf(lo) | (f2bf(hi) << 16); }
; __device__ __forceinline__ float siluf_(float x) { return x * __builtin_amdgcn_rcpf(1.0f + __expf(-x)); }
; __device__ __forceinline__ void gla_finalize(const Ctx& F) {
;     ...
;         ss += __shfl_xor(ss, 1); ss += __shfl_xor(ss, 2); ss += __shfl_xor(ss, 4); ss += __shfl_xor(ss, 8);
;         const float rstd = rsqrtf(ss * (1.0f / 512.0f) + EPS);
;         const u32x4* rp = (const u32x4*)(Y1 + (size_t)row * 6144 + 4096 + lane * 32); u32x4* cp = (u32x4*)(CAT + (size_t)row * 2048 + lane * 32);
; #pragma unroll
;         for (int i = 0; i < 4; ++i) { const u32x4 rv = rp[i]; const unsigned rr[4] = {rv.x, rv.y, rv.z, rv.w}; unsigned ov[4];
; #pragma unroll
;             for (int j = 0; j < 4; ++j) { const int e = i * 8 + j * 2; const float r0 = __uint_as_float(rr[j] << 16), r1 = __uint_as_float(rr[j] & 0xffff0000u);
;                 const float x0 = o[e >> 2][e & 3], x1 = o[(e + 1) >> 2][(e + 1) & 3];
;                 ov[j] = pk2(x0 * rstd * P.in[36][d0 + e] * siluf_(r0), x1 * rstd * P.in[36][d0 + e + 1] * siluf_(r1)); }
;             cp[i] = (u32x4){ov[0], ov[1], ov[2], ov[3]}; }
	v_add_f32_e32 v1, v1, v5
	ds_bpermute_b32 v5, v39, v1
	v_mul_f32_e32 v122, 0xbfb8aa3b, v85
	v_exp_f32_e32 v43, v43
	v_exp_f32_e32 v118, v118
	v_exp_f32_e32 v119, v119
	s_waitcnt lgkmcnt(0)
	v_add_f32_e32 v1, v1, v5
	ds_bpermute_b32 v5, v40, v1
	v_exp_f32_e32 v120, v120
	v_exp_f32_e32 v122, v122
	v_add_f32_e32 v43, 1.0, v43
	v_add_f32_e32 v103, 1.0, v134
	s_waitcnt lgkmcnt(0)
	v_add_f32_e32 v1, v1, v5
	ds_bpermute_b32 v5, v41, v1
	v_add_f32_e32 v105, 1.0, v135
	v_add_f32_e32 v106, 1.0, v136
	v_add_f32_e32 v107, 1.0, v137
	v_add_f32_e32 v109, 1.0, v118
	s_waitcnt lgkmcnt(0)
	v_add_f32_e32 v1, v1, v5
	v_fmamk_f32 v1, v1, 0x3b000000, v42
	v_mul_f32_e32 v5, 0x4b800000, v1
	v_cmp_gt_f32_e32 vcc, s9, v1
	v_add_f32_e32 v110, 1.0, v119
	v_add_f32_e32 v111, 1.0, v120
	v_cndmask_b32_e32 v1, v1, v5, vcc
	v_add_f32_e32 v115, 1.0, v122
	v_rsq_f32_e32 v1, v1
	v_rcp_f32_e32 v73, v43
	v_rcp_f32_e32 v104, v103
	v_rcp_f32_e32 v103, v105
	v_rcp_f32_e32 v105, v106
	v_rcp_f32_e32 v106, v107
	v_rcp_f32_e32 v107, v109
	v_rcp_f32_e32 v109, v110
	v_rcp_f32_e32 v110, v111
	v_rcp_f32_e32 v111, v115
	v_add_f32_e32 v96, 1.0, v132
	v_rcp_f32_e32 v99, v96
	v_mul_f32_e32 v5, 0x45800000, v1
	v_pk_mul_f32 v[44:45], v[72:73], v[44:45]
	v_pk_mul_f32 v[72:73], v[102:103], v[76:77]
	v_pk_mul_f32 v[76:77], v[106:107], v[80:81]
	v_pk_mul_f32 v[80:81], v[110:111], v[84:85]
	v_cndmask_b32_e32 v84, v1, v5, vcc
	v_pk_mul_f32 v[46:47], v[84:85], v[92:93] op_sel_hi:[0,1]
	v_pk_mul_f32 v[50:51], v[84:85], v[52:53] op_sel_hi:[0,1]
	v_pk_mul_f32 v[52:53], v[84:85], v[94:95] op_sel_hi:[0,1]
	v_pk_mul_f32 v[54:55], v[84:85], v[54:55] op_sel_hi:[0,1]
	v_pk_mul_f32 v[48:49], v[98:99], v[74:75]
	v_pk_mul_f32 v[74:75], v[104:105], v[78:79]
	v_pk_mul_f32 v[46:47], v[60:61], v[46:47]
	v_pk_mul_f32 v[6:7], v[6:7], v[50:51]
	v_pk_mul_f32 v[50:51], v[62:63], v[52:53]
	v_pk_mul_f32 v[2:3], v[2:3], v[54:55]
	v_pk_mul_f32 v[44:45], v[44:45], v[46:47]
	v_pk_mul_f32 v[6:7], v[48:49], v[6:7]
	v_pk_mul_f32 v[46:47], v[72:73], v[50:51]
	v_pk_mul_f32 v[2:3], v[74:75], v[2:3]
	v_bfe_u32 v43, v7, 16, 1
	v_bfe_u32 v1, v3, 16, 1
	v_bfe_u32 v5, v2, 16, 1
	v_bfe_u32 v49, v44, 16, 1
	v_bfe_u32 v50, v45, 16, 1
	v_bfe_u32 v51, v46, 16, 1
	v_bfe_u32 v52, v47, 16, 1
	v_bfe_u32 v48, v6, 16, 1
	v_add3_u32 v7, v7, v43, s22
	v_add3_u32 v2, v2, v5, s22
	v_add3_u32 v1, v3, v1, s22
	v_add3_u32 v3, v47, v52, s22
	v_add3_u32 v5, v46, v51, s22
	v_add3_u32 v43, v45, v50, s22
	v_add3_u32 v44, v44, v49, s22
	v_add3_u32 v6, v6, v48, s22
	v_lshrrev_b32_e32 v44, 16, v44
	v_lshrrev_b32_e32 v43, 16, v43
	v_lshrrev_b32_e32 v5, 16, v5
	v_lshrrev_b32_e32 v3, 16, v3
	v_and_or_b32 v47, v1, s3, v3
	v_and_or_b32 v46, v2, s3, v5
	v_and_or_b32 v45, v7, s3, v43
	v_and_or_b32 v44, v6, s3, v44
	global_store_dwordx4 v[22:23], v[44:47], off
	s_nop 1
	v_mov_b32_e32 v44, v168
	v_mov_b32_e32 v45, v169
	v_mov_b32_e32 v46, v170
	v_mov_b32_e32 v47, v171
	s_nop 0
	v_mov_b32_e32 v48, v172
	v_mov_b32_e32 v49, v173
	v_mov_b32_e32 v50, v174
	v_mov_b32_e32 v51, v175
	v_mul_f32_e32 v121, 0xbfb8aa3b, v86
	v_mul_f32_e32 v123, 0xbfb8aa3b, v87
	v_exp_f32_e32 v121, v121
	v_exp_f32_e32 v123, v123
	v_add_f32_e32 v108, 1.0, v138
	v_rcp_f32_e32 v108, v108
	v_add_f32_e32 v114, 1.0, v121
	v_add_f32_e32 v116, 1.0, v123
	v_rcp_f32_e32 v114, v114
	v_rcp_f32_e32 v115, v116
	v_pk_mul_f32 v[64:65], v[84:85], v[64:65] op_sel_hi:[0,1]
	v_pk_mul_f32 v[68:69], v[84:85], v[68:69] op_sel_hi:[0,1]
	v_pk_mul_f32 v[66:67], v[84:85], v[66:67] op_sel_hi:[0,1]
	v_pk_mul_f32 v[70:71], v[84:85], v[70:71] op_sel_hi:[0,1]
	v_pk_mul_f32 v[78:79], v[108:109], v[82:83]
	v_pk_mul_f32 v[82:83], v[114:115], v[86:87]
	v_mul_f32_e32 v124, 0xbfb8aa3b, v30
	v_mul_f32_e32 v125, 0xbfb8aa3b, v32
	v_mul_f32_e32 v126, 0xbfb8aa3b, v31
	v_mul_f32_e32 v127, 0xbfb8aa3b, v33
	v_mul_f32_e32 v128, 0xbfb8aa3b, v34
	v_mul_f32_e32 v129, 0xbfb8aa3b, v36
	v_mul_f32_e32 v130, 0xbfb8aa3b, v35
	v_mul_f32_e32 v131, 0xbfb8aa3b, v37
	v_exp_f32_e32 v124, v124
	v_exp_f32_e32 v125, v125
	v_exp_f32_e32 v126, v126
	v_exp_f32_e32 v127, v127
	v_exp_f32_e32 v128, v128
	v_exp_f32_e32 v129, v129
	v_exp_f32_e32 v130, v130
	v_exp_f32_e32 v131, v131
	v_add_f32_e32 v118, 1.0, v124
	v_add_f32_e32 v119, 1.0, v125
	v_add_f32_e32 v120, 1.0, v126
	v_add_f32_e32 v121, 1.0, v127
	v_add_f32_e32 v122, 1.0, v128
	v_add_f32_e32 v123, 1.0, v129
	v_add_f32_e32 v124, 1.0, v130
	v_rcp_f32_e32 v54, v123
	v_rcp_f32_e32 v53, v124
	v_lshlrev_b32_e32 v27, 16, v9
	v_lshlrev_b32_e32 v26, 16, v8
	v_pk_mul_f32 v[20:21], v[84:85], v[20:21] op_sel_hi:[0,1]
	v_pk_mul_f32 v[24:25], v[84:85], v[24:25] op_sel_hi:[0,1]
	v_mov_b32_e32 v2, v44
	v_mov_b32_e32 v3, v46
	v_mov_b32_e32 v6, v48
	v_mov_b32_e32 v7, v50
	v_mov_b32_e32 v46, v45
	v_mov_b32_e32 v50, v49
	v_pk_mul_f32 v[2:3], v[2:3], v[64:65]
	v_pk_mul_f32 v[6:7], v[6:7], v[68:69]
	v_pk_mul_f32 v[44:45], v[46:47], v[66:67]
	v_pk_mul_f32 v[46:47], v[50:51], v[70:71]
	v_pk_mul_f32 v[2:3], v[76:77], v[2:3]
	v_pk_mul_f32 v[6:7], v[80:81], v[6:7]
	v_pk_mul_f32 v[44:45], v[78:79], v[44:45]
	v_pk_mul_f32 v[46:47], v[82:83], v[46:47]
	v_bfe_u32 v49, v2, 16, 1
	v_bfe_u32 v50, v3, 16, 1
	v_bfe_u32 v51, v6, 16, 1
	v_bfe_u32 v52, v7, 16, 1
	v_bfe_u32 v1, v47, 16, 1
	v_bfe_u32 v5, v46, 16, 1
	v_bfe_u32 v43, v45, 16, 1
	v_bfe_u32 v48, v44, 16, 1
	v_add3_u32 v7, v7, v52, s22
	v_add3_u32 v6, v6, v51, s22
	v_add3_u32 v3, v3, v50, s22
; __device__ __forceinline__ unsigned pk2(float lo, float hi) { return f2bf(lo) | (f2bf(hi) << 16); }
; __device__ __forceinline__ float siluf_(float x) { return x * __builtin_amdgcn_rcpf(1.0f + __expf(-x)); }
; __device__ __forceinline__ void gla_finalize(const Ctx& F) {
;     ...
;         for (int i = 0; i < 4; ++i) { const u32x4 rv = rp[i]; const unsigned rr[4] = {rv.x, rv.y, rv.z, rv.w}; unsigned ov[4];
; #pragma unroll
;             for (int j = 0; j < 4; ++j) { const int e = i * 8 + j * 2; const float r0 = __uint_as_float(rr[j] << 16), r1 = __uint_as_float(rr[j] & 0xffff0000u);
;                 const float x0 = o[e >> 2][e & 3], x1 = o[(e + 1) >> 2][(e + 1) & 3];
;                 ov[j] = pk2(x0 * rstd * P.in[36][d0 + e] * siluf_(r0), x1 * rstd * P.in[36][d0 + e + 1] * siluf_(r1)); }
;             cp[i] = (u32x4){ov[0], ov[1], ov[2], ov[3]}; }
	v_add3_u32 v2, v2, v49, s22
	v_add3_u32 v44, v44, v48, s22
	v_add3_u32 v43, v45, v43, s22
	v_add3_u32 v5, v46, v5, s22
	v_add3_u32 v1, v47, v1, s22
	v_lshrrev_b32_e32 v2, 16, v2
	v_lshrrev_b32_e32 v3, 16, v3
	v_lshrrev_b32_e32 v6, 16, v6
	v_lshrrev_b32_e32 v7, 16, v7
	v_and_or_b32 v47, v1, s3, v7
	v_and_or_b32 v46, v5, s3, v6
	v_and_or_b32 v45, v43, s3, v3
	v_and_or_b32 v44, v44, s3, v2
	global_store_dwordx4 v[22:23], v[44:47], off offset:16
	s_nop 1
	v_mov_b32_e32 v44, v176
	v_mov_b32_e32 v45, v177
	v_mov_b32_e32 v46, v178
	v_mov_b32_e32 v47, v179
	s_nop 0
	v_mov_b32_e32 v48, v180
	v_mov_b32_e32 v49, v181
	v_mov_b32_e32 v50, v182
	v_mov_b32_e32 v51, v183
	v_add_f32_e32 v1, 1.0, v131
	v_rcp_f32_e32 v2, v118
	v_rcp_f32_e32 v6, v119
	v_rcp_f32_e32 v3, v120
	v_rcp_f32_e32 v7, v121
	v_rcp_f32_e32 v52, v122
	v_rcp_f32_e32 v55, v1
	v_pk_mul_f32 v[2:3], v[2:3], v[30:31]
	v_pk_mul_f32 v[6:7], v[6:7], v[32:33]
	v_pk_mul_f32 v[30:31], v[52:53], v[34:35]
	v_pk_mul_f32 v[32:33], v[54:55], v[36:37]
	v_pk_mul_f32 v[34:35], v[84:85], v[112:113] op_sel_hi:[0,1]
	v_pk_mul_f32 v[36:37], v[84:85], v[56:57] op_sel_hi:[0,1]
	v_pk_mul_f32 v[52:53], v[84:85], v[100:101] op_sel_hi:[0,1]
	v_pk_mul_f32 v[54:55], v[84:85], v[58:59] op_sel_hi:[0,1]
	v_mov_b32_e32 v56, v44
	v_mov_b32_e32 v57, v46
	v_mov_b32_e32 v46, v45
	v_mov_b32_e32 v44, v48
	v_mov_b32_e32 v45, v50
	v_mov_b32_e32 v50, v49
	v_pk_mul_f32 v[34:35], v[34:35], v[56:57]
	v_pk_mul_f32 v[44:45], v[52:53], v[44:45]
	v_pk_mul_f32 v[36:37], v[36:37], v[46:47]
	v_pk_mul_f32 v[46:47], v[54:55], v[50:51]
	v_pk_mul_f32 v[2:3], v[34:35], v[2:3]
	v_pk_mul_f32 v[30:31], v[30:31], v[44:45]
	v_pk_mul_f32 v[6:7], v[36:37], v[6:7]
	v_pk_mul_f32 v[32:33], v[32:33], v[46:47]
	v_bfe_u32 v36, v2, 16, 1
	v_bfe_u32 v37, v3, 16, 1
	v_bfe_u32 v43, v30, 16, 1
	v_bfe_u32 v44, v31, 16, 1
	v_bfe_u32 v1, v33, 16, 1
	v_bfe_u32 v5, v32, 16, 1
	v_bfe_u32 v34, v7, 16, 1
	v_bfe_u32 v35, v6, 16, 1
	v_add3_u32 v31, v31, v44, s22
	v_add3_u32 v30, v30, v43, s22
	v_add3_u32 v3, v3, v37, s22
	v_add3_u32 v2, v2, v36, s22
	v_add3_u32 v6, v6, v35, s22
	v_add3_u32 v7, v7, v34, s22
	v_add3_u32 v5, v32, v5, s22
	v_add3_u32 v1, v33, v1, s22
	v_lshrrev_b32_e32 v2, 16, v2
	v_lshrrev_b32_e32 v3, 16, v3
	v_lshrrev_b32_e32 v30, 16, v30
	v_lshrrev_b32_e32 v31, 16, v31
	v_and_or_b32 v33, v1, s3, v31
	v_and_or_b32 v32, v5, s3, v30
	v_and_or_b32 v31, v7, s3, v3
	v_and_or_b32 v30, v6, s3, v2
	global_store_dwordx4 v[22:23], v[30:33], off offset:32
	s_nop 1
	v_mov_b32_e32 v30, v184
	v_mov_b32_e32 v31, v185
	v_mov_b32_e32 v32, v186
	v_mov_b32_e32 v33, v187
	s_nop 0
	v_mov_b32_e32 v34, v188
	v_mov_b32_e32 v35, v189
	v_mov_b32_e32 v36, v190
	v_mov_b32_e32 v37, v191
	v_and_b32_e32 v3, 0xffff0000, v9
	v_and_b32_e32 v2, 0xffff0000, v8
	v_lshlrev_b32_e32 v7, 16, v11
	v_lshlrev_b32_e32 v6, 16, v10
	v_and_b32_e32 v9, 0xffff0000, v11
	v_and_b32_e32 v8, 0xffff0000, v10
	v_mul_f32_e32 v10, 0xbfb8aa3b, v26
	v_mul_f32_e32 v11, 0xbfb8aa3b, v2
	v_mov_b32_e32 v5, v28
	v_mul_f32_e32 v28, 0xbfb8aa3b, v27
	v_mov_b32_e32 v1, v29
	v_mul_f32_e32 v29, 0xbfb8aa3b, v3
	v_mul_f32_e32 v43, 0xbfb8aa3b, v6
	v_mul_f32_e32 v45, 0xbfb8aa3b, v7
	v_exp_f32_e32 v10, v10
	v_exp_f32_e32 v11, v11
	v_exp_f32_e32 v28, v28
	v_exp_f32_e32 v29, v29
	v_mul_f32_e32 v44, 0xbfb8aa3b, v8
	v_mul_f32_e32 v46, 0xbfb8aa3b, v9
	v_exp_f32_e32 v43, v43
	v_exp_f32_e32 v45, v45
	v_exp_f32_e32 v44, v44
	v_exp_f32_e32 v46, v46
	v_add_f32_e32 v10, 1.0, v10
	v_add_f32_e32 v11, 1.0, v11
	v_add_f32_e32 v47, 1.0, v28
	v_add_f32_e32 v29, 1.0, v29
	v_add_f32_e32 v43, 1.0, v43
	v_add_f32_e32 v45, 1.0, v45
	v_rcp_f32_e32 v10, v10
	v_rcp_f32_e32 v28, v11
	v_rcp_f32_e32 v11, v47
	v_rcp_f32_e32 v29, v29
	v_add_f32_e32 v48, 1.0, v44
	v_add_f32_e32 v49, 1.0, v46
	v_rcp_f32_e32 v44, v43
	v_rcp_f32_e32 v45, v45
	v_rcp_f32_e32 v46, v48
	v_rcp_f32_e32 v47, v49
	v_pk_mul_f32 v[10:11], v[10:11], v[26:27]
	v_pk_mul_f32 v[2:3], v[28:29], v[2:3]
	v_pk_mul_f32 v[4:5], v[84:85], v[4:5] op_sel_hi:[0,1]
	v_pk_mul_f32 v[0:1], v[84:85], v[0:1] op_sel_hi:[0,1]
	v_pk_mul_f32 v[6:7], v[44:45], v[6:7]
	v_pk_mul_f32 v[8:9], v[46:47], v[8:9]
	v_mov_b32_e32 v26, v30
	v_mov_b32_e32 v27, v32
	v_mov_b32_e32 v32, v31
	v_mov_b32_e32 v28, v34
	v_mov_b32_e32 v29, v36
	v_mov_b32_e32 v36, v35
	v_pk_mul_f32 v[4:5], v[4:5], v[26:27]
	v_pk_mul_f32 v[0:1], v[0:1], v[32:33]
	v_pk_mul_f32 v[20:21], v[20:21], v[28:29]
	v_pk_mul_f32 v[24:25], v[24:25], v[36:37]
	v_pk_mul_f32 v[4:5], v[4:5], v[10:11]
	v_pk_mul_f32 v[0:1], v[0:1], v[2:3]
	v_pk_mul_f32 v[2:3], v[6:7], v[20:21]
	v_pk_mul_f32 v[6:7], v[8:9], v[24:25]
	v_bfe_u32 v20, v4, 16, 1
	v_bfe_u32 v21, v5, 16, 1
	v_bfe_u32 v24, v2, 16, 1
	v_bfe_u32 v25, v3, 16, 1
	v_bfe_u32 v8, v7, 16, 1
	v_bfe_u32 v9, v6, 16, 1
	v_bfe_u32 v10, v1, 16, 1
	v_bfe_u32 v11, v0, 16, 1
	v_add3_u32 v3, v3, v25, s22
	v_add3_u32 v2, v2, v24, s22
	v_add3_u32 v5, v5, v21, s22
	v_add3_u32 v4, v4, v20, s22
	v_add3_u32 v0, v0, v11, s22
	v_add3_u32 v1, v1, v10, s22
	v_add3_u32 v6, v6, v9, s22
	v_add3_u32 v7, v7, v8, s22
	v_lshrrev_b32_e32 v4, 16, v4
	v_lshrrev_b32_e32 v5, 16, v5
	v_lshrrev_b32_e32 v2, 16, v2
	v_lshrrev_b32_e32 v3, 16, v3
	v_and_or_b32 v3, v7, s3, v3
	v_and_or_b32 v2, v6, s3, v2
	v_and_or_b32 v1, v1, s3, v5
	v_and_or_b32 v0, v0, s3, v4
	global_store_dwordx4 v[22:23], v[0:3], off offset:48
	s_cbranch_scc1 .LBB0_1904

; #define LAS __attribute__((address_space(3)))
; template <bool POST, bool PRE>
; __device__ __forceinline__ void row_core(const Params& P, const RowCfg& c, LAS float* vA, LAS float* vB, LAS float* vP, const bf16_t* RAW, const float* SSQ, bf16_t* H, int row, int lane, f32x4 (&v)[8]) {
;     ...
;         const u32x2* rs = (const u32x2*)(RAW + (size_t)row * DM) + lane;
;         float s = (lane < 32) ? SSQ[(size_t)row * 32 + lane] : 0.f; s = wave_sum(s);
;         const float rstd = rsqrtf(s * (1.0f / DM) + EPS);
;         f32x4* os = (f32x4*)(P.out + (size_t)row * DM) + lane;
; #pragma unroll
;         for (int j = 0; j < 8; ++j) { const u32x2 rb = rs[64 * j]; const f32x4 r = (f32x4){__uint_as_float(rb.x << 16), __uint_as_float(rb.x & 0xffff0000u), __uint_as_float(rb.y << 16), __uint_as_float(rb.y & 0xffff0000u)};
;             const f32x4 pv = *(const LAS f32x4*)(vP + j * 256 + lane * 4); v[j] += r * rstd * pv; os[64 * j] = v[j]; }
.LBB0_2053:
	s_or_b64 exec, exec, s[0:1]
	v_lshl_add_u64 v[40:41], s[92:93], 0, v[38:39]
	v_add_co_u32_e64 v58, s[0:1], s7, v40
	s_waitcnt vmcnt(0)
	ds_bpermute_b32 v49, v43, v42
	v_addc_co_u32_e64 v59, s[0:1], 0, v41, s[0:1]
	global_load_dwordx2 v[60:61], v[58:59], off nt
	s_add_i32 s6, s6, s8
	s_waitcnt lgkmcnt(0)
	v_add_f32_e32 v42, v42, v49
	ds_bpermute_b32 v49, v44, v42
	v_lshl_add_u64 v[34:35], v[34:35], 0, s[10:11]
	s_cmpk_lt_i32 s6, 0x4000
	v_lshl_add_u64 v[38:39], v[38:39], 0, s[14:15]
	s_waitcnt lgkmcnt(0)
	v_add_f32_e32 v42, v42, v49
	ds_bpermute_b32 v49, v45, v42
	s_waitcnt lgkmcnt(0)
	v_add_f32_e32 v42, v42, v49
	ds_bpermute_b32 v49, v46, v42
	s_waitcnt lgkmcnt(0)
	v_add_f32_e32 v42, v42, v49
	ds_bpermute_b32 v49, v47, v42
	s_waitcnt lgkmcnt(0)
	v_add_f32_e32 v42, v42, v49
	ds_bpermute_b32 v49, v48, v42
	s_waitcnt lgkmcnt(0)
	v_add_f32_e32 v42, v42, v49
	v_fmamk_f32 v42, v42, 0x3a000000, v33
	v_mul_f32_e32 v49, 0x4b800000, v42
	v_cmp_gt_f32_e64 s[0:1], s3, v42
	s_waitcnt vmcnt(0)
	v_and_b32_e32 v63, 0xffff0000, v60
	v_cndmask_b32_e64 v42, v42, v49, s[0:1]
	v_rsq_f32_e32 v42, v42
	v_add_u32_e32 v49, 0, v32
	ds_read_b128 v[50:53], v49 offset:16384
	ds_read_b128 v[54:57], v49 offset:17408
	v_mul_f32_e32 v62, 0x45800000, v42
	v_cndmask_b32_e64 v42, v42, v62, s[0:1]
	v_lshlrev_b32_e32 v62, 16, v60
	v_lshlrev_b32_e32 v60, 16, v61
	v_and_b32_e32 v61, 0xffff0000, v61
	v_pk_mul_f32 v[62:63], v[42:43], v[62:63] op_sel_hi:[0,1]
	v_pk_mul_f32 v[60:61], v[42:43], v[60:61] op_sel_hi:[0,1]
	s_waitcnt lgkmcnt(1)
	v_pk_fma_f32 v[22:23], v[52:53], v[60:61], v[22:23]
	v_pk_fma_f32 v[20:21], v[50:51], v[62:63], v[20:21]
	global_store_dwordx4 v[36:37], v[20:23], off offset:-4096 nt
	global_load_dwordx2 v[50:51], v[58:59], off offset:512 nt
	s_waitcnt vmcnt(0)
	v_lshlrev_b32_e32 v52, 16, v50
	v_and_b32_e32 v53, 0xffff0000, v50
	v_lshlrev_b32_e32 v50, 16, v51
	v_and_b32_e32 v51, 0xffff0000, v51
	v_pk_mul_f32 v[52:53], v[42:43], v[52:53] op_sel_hi:[0,1]
	v_pk_mul_f32 v[50:51], v[42:43], v[50:51] op_sel_hi:[0,1]
	s_waitcnt lgkmcnt(0)
	v_pk_fma_f32 v[14:15], v[56:57], v[50:51], v[14:15]
	v_pk_fma_f32 v[12:13], v[54:55], v[52:53], v[12:13]
	global_store_dwordx4 v[36:37], v[12:15], off offset:-3072 nt
	global_load_dwordx2 v[60:61], v[58:59], off offset:1024 nt
	ds_read_b128 v[50:53], v49 offset:18432
	ds_read_b128 v[54:57], v49 offset:19456
	s_waitcnt vmcnt(0)
	v_lshlrev_b32_e32 v62, 16, v60
	v_and_b32_e32 v63, 0xffff0000, v60
	v_lshlrev_b32_e32 v60, 16, v61
	v_and_b32_e32 v61, 0xffff0000, v61
	v_pk_mul_f32 v[62:63], v[42:43], v[62:63] op_sel_hi:[0,1]
	v_pk_mul_f32 v[60:61], v[42:43], v[60:61] op_sel_hi:[0,1]
	s_waitcnt lgkmcnt(1)
	v_pk_fma_f32 v[30:31], v[52:53], v[60:61], v[30:31]
	v_pk_fma_f32 v[28:29], v[50:51], v[62:63], v[28:29]
	global_store_dwordx4 v[36:37], v[28:31], off offset:-2048 nt
	global_load_dwordx2 v[50:51], v[58:59], off offset:1536 nt
	s_waitcnt vmcnt(0)
	v_lshlrev_b32_e32 v52, 16, v50
	v_and_b32_e32 v53, 0xffff0000, v50
	v_lshlrev_b32_e32 v50, 16, v51
	v_and_b32_e32 v51, 0xffff0000, v51
	v_pk_mul_f32 v[52:53], v[42:43], v[52:53] op_sel_hi:[0,1]
	v_pk_mul_f32 v[50:51], v[42:43], v[50:51] op_sel_hi:[0,1]
	s_waitcnt lgkmcnt(0)
	v_pk_fma_f32 v[26:27], v[56:57], v[50:51], v[26:27]
	v_pk_fma_f32 v[24:25], v[54:55], v[52:53], v[24:25]
	global_store_dwordx4 v[36:37], v[24:27], off offset:-1024 nt
	global_load_dwordx2 v[60:61], v[58:59], off offset:2048 nt
	ds_read_b128 v[50:53], v49 offset:20480
	ds_read_b128 v[54:57], v49 offset:21504
	s_waitcnt vmcnt(0)
	v_lshlrev_b32_e32 v62, 16, v60
	v_and_b32_e32 v63, 0xffff0000, v60
	v_lshlrev_b32_e32 v60, 16, v61
	v_and_b32_e32 v61, 0xffff0000, v61
	v_pk_mul_f32 v[62:63], v[42:43], v[62:63] op_sel_hi:[0,1]
	v_pk_mul_f32 v[60:61], v[42:43], v[60:61] op_sel_hi:[0,1]
	s_waitcnt lgkmcnt(1)
	v_pk_fma_f32 v[6:7], v[52:53], v[60:61], v[6:7]
	v_pk_fma_f32 v[4:5], v[50:51], v[62:63], v[4:5]
	global_store_dwordx4 v[36:37], v[4:7], off nt
	global_load_dwordx2 v[50:51], v[58:59], off offset:2560 nt
	s_waitcnt vmcnt(0)
	v_lshlrev_b32_e32 v52, 16, v50
	v_and_b32_e32 v53, 0xffff0000, v50
	v_lshlrev_b32_e32 v50, 16, v51
	v_and_b32_e32 v51, 0xffff0000, v51
	v_pk_mul_f32 v[52:53], v[42:43], v[52:53] op_sel_hi:[0,1]
	v_pk_mul_f32 v[50:51], v[42:43], v[50:51] op_sel_hi:[0,1]
	s_waitcnt lgkmcnt(0)
	v_pk_fma_f32 v[10:11], v[56:57], v[50:51], v[10:11]
	v_pk_fma_f32 v[8:9], v[54:55], v[52:53], v[8:9]
	global_store_dwordx4 v[36:37], v[8:11], off offset:1024 nt
	global_load_dwordx2 v[60:61], v[58:59], off offset:3072 nt
	ds_read_b128 v[50:53], v49 offset:22528
	ds_read_b128 v[54:57], v49 offset:23552
	s_waitcnt vmcnt(0)
	v_lshlrev_b32_e32 v62, 16, v60
	v_and_b32_e32 v63, 0xffff0000, v60
	v_lshlrev_b32_e32 v60, 16, v61
	v_and_b32_e32 v61, 0xffff0000, v61
	v_pk_mul_f32 v[62:63], v[42:43], v[62:63] op_sel_hi:[0,1]
	v_pk_mul_f32 v[60:61], v[42:43], v[60:61] op_sel_hi:[0,1]
	s_waitcnt lgkmcnt(1)
; #define LAS __attribute__((address_space(3)))
; __device__ __forceinline__ unsigned cvt_pk_bf16(float lo, float hi) { unsigned r; asm volatile("v_cvt_pk_bf16_f32 %0, %1, %2" : "=v"(r) : "v"(lo), "v"(hi)); return r; }
; template <bool POST, bool PRE>
; __device__ __forceinline__ void row_core(const Params& P, const RowCfg& c, LAS float* vA, LAS float* vB, LAS float* vP, const bf16_t* RAW, const float* SSQ, bf16_t* H, int row, int lane, f32x4 (&v)[8]) {
;     ...
;         for (int j = 0; j < 8; ++j) { const u32x2 rb = rs[64 * j]; const f32x4 r = (f32x4){__uint_as_float(rb.x << 16), __uint_as_float(rb.x & 0xffff0000u), __uint_as_float(rb.y << 16), __uint_as_float(rb.y & 0xffff0000u)};
;             const f32x4 pv = *(const LAS f32x4*)(vP + j * 256 + lane * 4); v[j] += r * rstd * pv; os[64 * j] = v[j]; }
;     }
;     if (PRE) {
;         float s2 = 0.f;
; #pragma unroll
;         for (int j = 0; j < 8; ++j) s2 += (v[j][0] * v[j][0] + v[j][1] * v[j][1]) + (v[j][2] * v[j][2] + v[j][3] * v[j][3]);
;         s2 = wave_sum(s2);
;         const float rstd2 = rsqrtf(s2 * (1.0f / DM) + EPS);
;         u32x2* hs = (u32x2*)(H + (size_t)row * DM) + lane;
; #pragma unroll
;         for (int j = 0; j < 8; ++j) { const f32x4 a = *(const LAS f32x4*)(vA + j * 256 + lane * 4), b = *(const LAS f32x4*)(vB + j * 256 + lane * 4);
;             v[j] = v[j] * rstd2 * a + b; u32x2 w; w.x = cvt_pk_bf16(v[j][0], v[j][1]); w.y = cvt_pk_bf16(v[j][2], v[j][3]); hs[64 * j] = w; }
	v_pk_fma_f32 v[18:19], v[52:53], v[60:61], v[18:19]
	v_pk_fma_f32 v[16:17], v[50:51], v[62:63], v[16:17]
	global_store_dwordx4 v[36:37], v[16:19], off offset:2048 nt
	global_load_dwordx2 v[50:51], v[58:59], off offset:3584 nt
	v_mov_b32_e32 v58, v21
	v_mov_b32_e32 v62, v23
	v_mov_b32_e32 v59, v13
	v_mov_b32_e32 v63, v15
	v_mov_b32_e32 v52, v20
	v_mov_b32_e32 v60, v22
	v_mov_b32_e32 v53, v12
	v_mov_b32_e32 v61, v14
	v_pk_mul_f32 v[58:59], v[58:59], v[58:59]
	v_pk_mul_f32 v[62:63], v[62:63], v[62:63]
	v_pk_fma_f32 v[52:53], v[52:53], v[52:53], v[58:59]
	v_pk_fma_f32 v[58:59], v[60:61], v[60:61], v[62:63]
	v_pk_mul_f32 v[60:61], v[28:29], v[28:29]
	v_pk_add_f32 v[52:53], v[52:53], v[58:59]
	v_pk_mul_f32 v[58:59], v[30:31], v[30:31]
	v_pk_add_f32 v[52:53], v[52:53], v[52:53] op_sel:[0,1] op_sel_hi:[1,0]
	v_pk_mov_b32 v[62:63], v[60:61], v[58:59] op_sel:[1,0]
	v_mov_b32_e32 v61, v59
	v_pk_add_f32 v[58:59], v[62:63], v[60:61]
	v_mul_f32_e32 v60, v25, v25
	v_mul_f32_e32 v62, v27, v27
	v_pk_add_f32 v[58:59], v[58:59], v[58:59] op_sel:[0,1] op_sel_hi:[1,0]
	v_pk_fma_f32 v[60:61], v[24:25], v[24:25], v[60:61] op_sel_hi:[1,1,0]
	v_pk_fma_f32 v[62:63], v[26:27], v[26:27], v[62:63] op_sel_hi:[1,1,0]
	v_mul_f32_e32 v53, v4, v4
	v_mul_f32_e32 v59, v5, v5
	v_mul_f32_e32 v61, v6, v6
	v_mul_f32_e32 v63, v7, v7
	v_pk_add_f32 v[52:53], v[52:53], v[58:59]
	v_pk_add_f32 v[58:59], v[60:61], v[62:63]
	v_pk_mul_f32 v[60:61], v[8:9], v[8:9]
	v_pk_add_f32 v[52:53], v[52:53], v[58:59]
	v_pk_mul_f32 v[58:59], v[10:11], v[10:11]
	v_pk_add_f32 v[52:53], v[52:53], v[52:53] op_sel:[0,1] op_sel_hi:[1,0]
	v_pk_mov_b32 v[62:63], v[60:61], v[58:59] op_sel:[1,0]
	v_mov_b32_e32 v61, v59
	v_pk_add_f32 v[58:59], v[62:63], v[60:61]
	v_mul_f32_e32 v60, v17, v17
	v_mul_f32_e32 v62, v19, v19
	v_pk_add_f32 v[58:59], v[58:59], v[58:59] op_sel:[0,1] op_sel_hi:[1,0]
	v_pk_fma_f32 v[60:61], v[16:17], v[16:17], v[60:61] op_sel_hi:[1,1,0]
	v_pk_fma_f32 v[62:63], v[18:19], v[18:19], v[62:63] op_sel_hi:[1,1,0]
	s_waitcnt vmcnt(0)
	v_lshlrev_b32_e32 v64, 16, v50
	v_and_b32_e32 v65, 0xffff0000, v50
	v_lshlrev_b32_e32 v50, 16, v51
	v_and_b32_e32 v51, 0xffff0000, v51
	v_pk_mul_f32 v[64:65], v[42:43], v[64:65] op_sel_hi:[0,1]
	v_pk_mul_f32 v[50:51], v[42:43], v[50:51] op_sel_hi:[0,1]
	s_waitcnt lgkmcnt(0)
	v_pk_fma_f32 v[2:3], v[56:57], v[50:51], v[2:3]
	v_pk_fma_f32 v[0:1], v[54:55], v[64:65], v[0:1]
	v_mul_f32_e32 v61, v2, v2
	v_mul_f32_e32 v53, v0, v0
	v_mul_f32_e32 v59, v1, v1
	v_mul_f32_e32 v63, v3, v3
	v_pk_add_f32 v[50:51], v[52:53], v[58:59]
	v_pk_add_f32 v[52:53], v[60:61], v[62:63]
	s_nop 0
	v_pk_add_f32 v[50:51], v[50:51], v[52:53]
	s_nop 0
	v_add_f32_e32 v42, v50, v51
	ds_bpermute_b32 v50, v43, v42
	s_waitcnt lgkmcnt(0)
	v_add_f32_e32 v42, v42, v50
	ds_bpermute_b32 v50, v44, v42
	s_waitcnt lgkmcnt(0)
	v_add_f32_e32 v42, v42, v50
	ds_bpermute_b32 v50, v45, v42
	s_waitcnt lgkmcnt(0)
	v_add_f32_e32 v42, v42, v50
	ds_bpermute_b32 v50, v46, v42
	s_waitcnt lgkmcnt(0)
	v_add_f32_e32 v42, v42, v50
	ds_bpermute_b32 v50, v47, v42
	s_waitcnt lgkmcnt(0)
	v_add_f32_e32 v42, v42, v50
	ds_bpermute_b32 v50, v48, v42
	s_waitcnt lgkmcnt(0)
	v_add_f32_e32 v42, v42, v50
	v_fmamk_f32 v42, v42, 0x3a000000, v33
	v_mul_f32_e32 v50, 0x4b800000, v42
	v_cmp_gt_f32_e64 s[0:1], s3, v42
	s_nop 1
	v_cndmask_b32_e64 v42, v42, v50, s[0:1]
	v_rsq_f32_e32 v42, v42
	ds_read_b128 v[50:53], v49
	ds_read_b128 v[54:57], v49 offset:8192
	global_store_dwordx4 v[36:37], v[0:3], off offset:3072 nt
	v_lshl_add_u64 v[36:37], v[36:37], 0, s[12:13]
	v_mul_f32_e32 v58, 0x45800000, v42
	v_cndmask_b32_e64 v42, v42, v58, s[0:1]
	v_pk_mul_f32 v[20:21], v[20:21], v[42:43] op_sel_hi:[1,0]
	v_pk_mul_f32 v[22:23], v[22:23], v[42:43] op_sel_hi:[1,0]
	s_waitcnt lgkmcnt(0)
; #define LAS __attribute__((address_space(3)))
; __device__ __forceinline__ unsigned cvt_pk_bf16(float lo, float hi) { unsigned r; asm volatile("v_cvt_pk_bf16_f32 %0, %1, %2" : "=v"(r) : "v"(lo), "v"(hi)); return r; }
; template <bool POST, bool PRE>
; __device__ __forceinline__ void row_core(const Params& P, const RowCfg& c, LAS float* vA, LAS float* vB, LAS float* vP, const bf16_t* RAW, const float* SSQ, bf16_t* H, int row, int lane, f32x4 (&v)[8]) {
;     ...
;         for (int j = 0; j < 8; ++j) { const f32x4 a = *(const LAS f32x4*)(vA + j * 256 + lane * 4), b = *(const LAS f32x4*)(vB + j * 256 + lane * 4);
;             v[j] = v[j] * rstd2 * a + b; u32x2 w; w.x = cvt_pk_bf16(v[j][0], v[j][1]); w.y = cvt_pk_bf16(v[j][2], v[j][3]); hs[64 * j] = w; }
	v_pk_fma_f32 v[20:21], v[50:51], v[20:21], v[54:55]
	v_pk_fma_f32 v[22:23], v[52:53], v[22:23], v[56:57]
	v_cvt_pk_bf16_f32 v54, v20, v21
	v_add_co_u32_e64 v40, s[0:1], s9, v40
	v_cvt_pk_bf16_f32 v55, v22, v23
	ds_read_b128 v[20:23], v49 offset:1024
	ds_read_b128 v[50:53], v49 offset:9216
	v_pk_mul_f32 v[12:13], v[12:13], v[42:43] op_sel_hi:[1,0]
	v_pk_mul_f32 v[14:15], v[14:15], v[42:43] op_sel_hi:[1,0]
	v_addc_co_u32_e64 v41, s[0:1], 0, v41, s[0:1]
	s_waitcnt lgkmcnt(0)
	v_pk_fma_f32 v[14:15], v[22:23], v[14:15], v[52:53]
	v_pk_fma_f32 v[12:13], v[20:21], v[12:13], v[50:51]
	global_store_dwordx2 v[40:41], v[54:55], off
	v_cvt_pk_bf16_f32 v50, v12, v13
	v_cvt_pk_bf16_f32 v51, v14, v15
	ds_read_b128 v[12:15], v49 offset:2048
	ds_read_b128 v[20:23], v49 offset:10240
	v_pk_mul_f32 v[28:29], v[28:29], v[42:43] op_sel_hi:[1,0]
	v_pk_mul_f32 v[30:31], v[30:31], v[42:43] op_sel_hi:[1,0]
	global_store_dwordx2 v[40:41], v[50:51], off offset:512
	v_pk_mul_f32 v[24:25], v[24:25], v[42:43] op_sel_hi:[1,0]
	s_waitcnt lgkmcnt(0)
	v_pk_fma_f32 v[14:15], v[14:15], v[30:31], v[22:23]
	v_pk_fma_f32 v[12:13], v[12:13], v[28:29], v[20:21]
	v_pk_mul_f32 v[26:27], v[26:27], v[42:43] op_sel_hi:[1,0]
	v_cvt_pk_bf16_f32 v28, v12, v13
	v_cvt_pk_bf16_f32 v29, v14, v15
	ds_read_b128 v[12:15], v49 offset:3072
	ds_read_b128 v[20:23], v49 offset:11264
	global_store_dwordx2 v[40:41], v[28:29], off offset:1024
	v_pk_mul_f32 v[4:5], v[4:5], v[42:43] op_sel_hi:[1,0]
	v_pk_mul_f32 v[6:7], v[6:7], v[42:43] op_sel_hi:[1,0]
	v_pk_mul_f32 v[8:9], v[8:9], v[42:43] op_sel_hi:[1,0]
	s_waitcnt lgkmcnt(0)
	v_pk_fma_f32 v[14:15], v[14:15], v[26:27], v[22:23]
	v_pk_fma_f32 v[12:13], v[12:13], v[24:25], v[20:21]
	v_pk_mul_f32 v[10:11], v[10:11], v[42:43] op_sel_hi:[1,0]
	v_cvt_pk_bf16_f32 v24, v12, v13
	v_cvt_pk_bf16_f32 v25, v14, v15
	ds_read_b128 v[12:15], v49 offset:4096
	ds_read_b128 v[20:23], v49 offset:12288
	global_store_dwordx2 v[40:41], v[24:25], off offset:1536
	v_pk_mul_f32 v[0:1], v[0:1], v[42:43] op_sel_hi:[1,0]
	v_pk_mul_f32 v[2:3], v[2:3], v[42:43] op_sel_hi:[1,0]
	s_waitcnt lgkmcnt(0)
	v_pk_fma_f32 v[6:7], v[14:15], v[6:7], v[22:23]
	v_pk_fma_f32 v[4:5], v[12:13], v[4:5], v[20:21]
	s_nop 0
	v_cvt_pk_bf16_f32 v20, v4, v5
	v_cvt_pk_bf16_f32 v21, v6, v7
	ds_read_b128 v[4:7], v49 offset:5120
	ds_read_b128 v[12:15], v49 offset:13312
	global_store_dwordx2 v[40:41], v[20:21], off offset:2048
	s_waitcnt lgkmcnt(0)
	v_pk_fma_f32 v[6:7], v[10:11], v[6:7], v[14:15]
	v_pk_fma_f32 v[4:5], v[8:9], v[4:5], v[12:13]
	v_pk_mul_f32 v[14:15], v[16:17], v[42:43] op_sel_hi:[1,0]
	v_cvt_pk_bf16_f32 v12, v4, v5
	v_cvt_pk_bf16_f32 v13, v6, v7
	ds_read_b128 v[4:7], v49 offset:6144
	ds_read_b128 v[8:11], v49 offset:14336
	v_pk_mul_f32 v[16:17], v[18:19], v[42:43] op_sel_hi:[1,0]
	global_store_dwordx2 v[40:41], v[12:13], off offset:2560
	s_waitcnt lgkmcnt(0)
	v_pk_fma_f32 v[6:7], v[16:17], v[6:7], v[10:11]
	v_pk_fma_f32 v[4:5], v[14:15], v[4:5], v[8:9]
	s_nop 0
	v_cvt_pk_bf16_f32 v12, v4, v5
	v_cvt_pk_bf16_f32 v13, v6, v7
	ds_read_b128 v[4:7], v49 offset:7168
	ds_read_b128 v[8:11], v49 offset:15360
	global_store_dwordx2 v[40:41], v[12:13], off offset:3072
	s_waitcnt lgkmcnt(0)
	v_pk_fma_f32 v[0:1], v[0:1], v[4:5], v[8:9]
	v_pk_fma_f32 v[2:3], v[2:3], v[6:7], v[10:11]
	v_cvt_pk_bf16_f32 v0, v0, v1
	s_nop 0
	v_cvt_pk_bf16_f32 v1, v2, v3
	global_store_dwordx2 v[40:41], v[0:1], off offset:3584
	s_cbranch_scc0 .LBB0_2056

; #define LAS __attribute__((address_space(3)))
; template <bool POST, bool PRE>
; __device__ __forceinline__ void row_core(const Params& P, const RowCfg& c, LAS float* vA, LAS float* vB, LAS float* vP, const bf16_t* RAW, const float* SSQ, bf16_t* H, int row, int lane, f32x4 (&v)[8]) {
;     ...
;         const u32x2* rs = (const u32x2*)(RAW + (size_t)row * DM) + lane;
;         float s = (lane < 32) ? SSQ[(size_t)row * 32 + lane] : 0.f; s = wave_sum(s);
;         const float rstd = rsqrtf(s * (1.0f / DM) + EPS);
;         f32x4* os = (f32x4*)(P.out + (size_t)row * DM) + lane;
; #pragma unroll
;         for (int j = 0; j < 8; ++j) { const u32x2 rb = rs[64 * j]; const f32x4 r = (f32x4){__uint_as_float(rb.x << 16), __uint_as_float(rb.x & 0xffff0000u), __uint_as_float(rb.y << 16), __uint_as_float(rb.y & 0xffff0000u)};
;             const f32x4 pv = *(const LAS f32x4*)(vP + j * 256 + lane * 4); v[j] += r * rstd * pv; os[64 * j] = v[j]; }
.LBB0_2275:
	s_or_b64 exec, exec, s[0:1]
	v_lshl_add_u64 v[78:79], s[92:93], 0, v[68:69]
	v_add_co_u32_e64 v78, s[0:1], s5, v78
	s_waitcnt vmcnt(0)
	ds_bpermute_b32 v82, v70, v77
	v_addc_co_u32_e64 v79, s[0:1], 0, v79, s[0:1]
	global_load_dwordx2 v[80:81], v[78:79], off nt
	s_add_i32 s2, s2, s4
	s_waitcnt lgkmcnt(0)
	v_add_f32_e32 v77, v77, v82
	ds_bpermute_b32 v82, v71, v77
	v_lshl_add_u64 v[64:65], v[64:65], 0, s[6:7]
	s_cmpk_lt_i32 s2, 0x4000
	v_lshl_add_u64 v[68:69], v[68:69], 0, s[10:11]
	s_waitcnt lgkmcnt(0)
	v_add_f32_e32 v77, v77, v82
	ds_bpermute_b32 v82, v72, v77
	s_waitcnt lgkmcnt(0)
	v_add_f32_e32 v77, v77, v82
	ds_bpermute_b32 v82, v73, v77
	s_waitcnt lgkmcnt(0)
	v_add_f32_e32 v77, v77, v82
	ds_bpermute_b32 v82, v74, v77
	s_waitcnt lgkmcnt(0)
	v_add_f32_e32 v77, v77, v82
	ds_bpermute_b32 v82, v75, v77
	s_waitcnt lgkmcnt(0)
	v_add_f32_e32 v77, v77, v82
	v_fmamk_f32 v77, v77, 0x3a000000, v76
	v_mul_f32_e32 v82, 0x4b800000, v77
	v_cmp_gt_f32_e64 s[0:1], s3, v77
	s_waitcnt vmcnt(0)
	v_lshlrev_b32_e32 v84, 16, v80
	v_cndmask_b32_e64 v77, v77, v82, s[0:1]
	v_rsq_f32_e32 v77, v77
	v_and_b32_e32 v85, 0xffff0000, v80
	v_lshlrev_b32_e32 v80, 16, v81
	v_and_b32_e32 v81, 0xffff0000, v81
	v_mul_f32_e32 v82, 0x45800000, v77
	v_cndmask_b32_e64 v82, v77, v82, s[0:1]
	v_pk_mul_f32 v[84:85], v[82:83], v[84:85] op_sel_hi:[0,1]
	v_pk_mul_f32 v[80:81], v[82:83], v[80:81] op_sel_hi:[0,1]
	v_pk_fma_f32 v[62:63], v[2:3], v[80:81], v[62:63]
	v_pk_fma_f32 v[60:61], v[0:1], v[84:85], v[60:61]
	global_store_dwordx4 v[66:67], v[60:63], off offset:-4096 nt
	global_load_dwordx2 v[60:61], v[78:79], off offset:512 nt
	s_waitcnt vmcnt(0)
	v_lshlrev_b32_e32 v62, 16, v60
	v_and_b32_e32 v63, 0xffff0000, v60
	v_lshlrev_b32_e32 v60, 16, v61
	v_and_b32_e32 v61, 0xffff0000, v61
	v_pk_mul_f32 v[62:63], v[82:83], v[62:63] op_sel_hi:[0,1]
	v_pk_mul_f32 v[60:61], v[82:83], v[60:61] op_sel_hi:[0,1]
	v_pk_fma_f32 v[58:59], v[6:7], v[60:61], v[58:59]
	v_pk_fma_f32 v[56:57], v[4:5], v[62:63], v[56:57]
	global_store_dwordx4 v[66:67], v[56:59], off offset:-3072 nt
	global_load_dwordx2 v[56:57], v[78:79], off offset:1024 nt
	s_waitcnt vmcnt(0)
	v_lshlrev_b32_e32 v58, 16, v56
	v_and_b32_e32 v59, 0xffff0000, v56
	v_lshlrev_b32_e32 v56, 16, v57
	v_and_b32_e32 v57, 0xffff0000, v57
	v_pk_mul_f32 v[58:59], v[82:83], v[58:59] op_sel_hi:[0,1]
	v_pk_mul_f32 v[56:57], v[82:83], v[56:57] op_sel_hi:[0,1]
	v_pk_fma_f32 v[54:55], v[10:11], v[56:57], v[54:55]
	v_pk_fma_f32 v[52:53], v[8:9], v[58:59], v[52:53]
	global_store_dwordx4 v[66:67], v[52:55], off offset:-2048 nt
	global_load_dwordx2 v[52:53], v[78:79], off offset:1536 nt
	s_waitcnt vmcnt(0)
	v_lshlrev_b32_e32 v54, 16, v52
	v_and_b32_e32 v55, 0xffff0000, v52
	v_lshlrev_b32_e32 v52, 16, v53
	v_and_b32_e32 v53, 0xffff0000, v53
	v_pk_mul_f32 v[54:55], v[82:83], v[54:55] op_sel_hi:[0,1]
	v_pk_mul_f32 v[52:53], v[82:83], v[52:53] op_sel_hi:[0,1]
	v_pk_fma_f32 v[50:51], v[14:15], v[52:53], v[50:51]
	v_pk_fma_f32 v[48:49], v[12:13], v[54:55], v[48:49]
	global_store_dwordx4 v[66:67], v[48:51], off offset:-1024 nt
	global_load_dwordx2 v[48:49], v[78:79], off offset:2048 nt
	s_waitcnt vmcnt(0)
	v_lshlrev_b32_e32 v50, 16, v48
	v_and_b32_e32 v51, 0xffff0000, v48
	v_lshlrev_b32_e32 v48, 16, v49
	v_and_b32_e32 v49, 0xffff0000, v49
	v_pk_mul_f32 v[50:51], v[82:83], v[50:51] op_sel_hi:[0,1]
	v_pk_mul_f32 v[48:49], v[82:83], v[48:49] op_sel_hi:[0,1]
	v_pk_fma_f32 v[46:47], v[18:19], v[48:49], v[46:47]
	v_pk_fma_f32 v[44:45], v[16:17], v[50:51], v[44:45]
	global_store_dwordx4 v[66:67], v[44:47], off nt
	global_load_dwordx2 v[44:45], v[78:79], off offset:2560 nt
	s_waitcnt vmcnt(0)
	v_lshlrev_b32_e32 v46, 16, v44
	v_and_b32_e32 v47, 0xffff0000, v44
	v_lshlrev_b32_e32 v44, 16, v45
	v_and_b32_e32 v45, 0xffff0000, v45
	v_pk_mul_f32 v[46:47], v[82:83], v[46:47] op_sel_hi:[0,1]
	v_pk_mul_f32 v[44:45], v[82:83], v[44:45] op_sel_hi:[0,1]
	v_pk_fma_f32 v[42:43], v[22:23], v[44:45], v[42:43]
	v_pk_fma_f32 v[40:41], v[20:21], v[46:47], v[40:41]
	global_store_dwordx4 v[66:67], v[40:43], off offset:1024 nt
	global_load_dwordx2 v[40:41], v[78:79], off offset:3072 nt
	s_waitcnt vmcnt(0)
	v_lshlrev_b32_e32 v42, 16, v40
	v_and_b32_e32 v43, 0xffff0000, v40
	v_lshlrev_b32_e32 v40, 16, v41
	v_and_b32_e32 v41, 0xffff0000, v41
	v_pk_mul_f32 v[42:43], v[82:83], v[42:43] op_sel_hi:[0,1]
	v_pk_mul_f32 v[40:41], v[82:83], v[40:41] op_sel_hi:[0,1]
	v_pk_fma_f32 v[38:39], v[26:27], v[40:41], v[38:39]
	v_pk_fma_f32 v[36:37], v[24:25], v[42:43], v[36:37]
	global_store_dwordx4 v[66:67], v[36:39], off offset:2048 nt
	global_load_dwordx2 v[36:37], v[78:79], off offset:3584 nt
	s_waitcnt vmcnt(0)
	v_lshlrev_b32_e32 v38, 16, v36
	v_and_b32_e32 v39, 0xffff0000, v36
	v_lshlrev_b32_e32 v36, 16, v37
	v_and_b32_e32 v37, 0xffff0000, v37
	v_pk_mul_f32 v[38:39], v[82:83], v[38:39] op_sel_hi:[0,1]
	v_pk_mul_f32 v[36:37], v[82:83], v[36:37] op_sel_hi:[0,1]
	v_pk_fma_f32 v[34:35], v[30:31], v[36:37], v[34:35]
	v_pk_fma_f32 v[32:33], v[28:29], v[38:39], v[32:33]
	global_store_dwordx4 v[66:67], v[32:35], off offset:3072 nt
	v_lshl_add_u64 v[66:67], v[66:67], 0, s[8:9]
	s_cbranch_scc0 .LBB0_2278
